# all flat_load/flat_store in mega converted to global_ forms (no LGKM counter or LDS queue coupling)
# speedup vs baseline: 1.0051x; 1.0016x over previous
.LBB2_205:
	v_lshl_add_u32 v144, s15, 8, v140
	v_max_f32_e32 v124, v124, v124
	v_ashrrev_i32_e32 v145, 31, v144
	v_max_f32_e32 v124, 0, v124
	v_lshlrev_b64 v[158:159], 14, v[144:145]
	v_max_f32_e32 v126, v126, v126
	v_max_f32_e32 v122, v122, v122
	v_max_f32_e32 v123, v123, v123
	v_max_f32_e32 v128, v128, v128
	v_mul_f32_e32 v145, v124, v124
	v_max_f32_e32 v124, v129, v129
	v_lshl_or_b32 v156, s14, 8, v142
	v_max_f32_e32 v126, 0, v126
	v_max_f32_e32 v122, 0, v122
	v_max_f32_e32 v127, v127, v127
	v_max_f32_e32 v123, 0, v123
	v_max_f32_e32 v128, 0, v128
	v_max_f32_e32 v124, 0, v124
	v_max_f32_e32 v125, v125, v125
	v_ashrrev_i32_e32 v157, 31, v156
	v_mul_f32_e32 v126, v126, v126
	v_mul_f32_e32 v122, v122, v122
	v_max_f32_e32 v127, 0, v127
	v_mul_f32_e32 v123, v123, v123
	v_mul_f32_e32 v128, v128, v128
	v_max_f32_e32 v125, 0, v125
	v_mul_f32_e32 v129, v124, v124
	v_mul_f32_e32 v127, v127, v127
	v_mul_f32_e32 v160, v125, v125
	v_cvt_pk_bf16_f32 v124, v126, v127
	v_cvt_pk_bf16_f32 v125, v128, v129
	v_cvt_pk_bf16_f32 v126, v122, v123
	v_lshl_add_u64 v[122:123], s[6:7], 0, v[158:159]
	v_lshlrev_b64 v[128:129], 1, v[156:157]
	v_max_f32_e32 v114, v114, v114
	v_max_f32_e32 v115, v115, v115
	v_max_f32_e32 v116, v116, v116
	v_lshl_add_u64 v[122:123], v[122:123], 0, v[128:129]
	v_max_f32_e32 v114, 0, v114
	v_max_f32_e32 v115, 0, v115
	v_max_f32_e32 v116, 0, v116
	v_cvt_pk_bf16_f32 v127, v145, v160
	global_store_dwordx4 v[122:123], v[124:127], off
	v_max_f32_e32 v118, v118, v118
	v_max_f32_e32 v117, v117, v117
	v_mul_f32_e32 v124, v114, v114
	v_max_f32_e32 v114, v119, v119
	v_mul_f32_e32 v119, v115, v115
	v_max_f32_e32 v115, v120, v120
	v_mul_f32_e32 v120, v116, v116
	v_max_f32_e32 v116, v121, v121
	v_max_f32_e32 v114, 0, v114
	v_max_f32_e32 v115, 0, v115
	v_max_f32_e32 v116, 0, v116
	v_max_f32_e32 v118, 0, v118
	v_mul_f32_e32 v114, v114, v114
	v_mul_f32_e32 v115, v115, v115
	v_max_f32_e32 v117, 0, v117
	v_mul_f32_e32 v116, v116, v116
	v_max_f32_e32 v106, v106, v106
	v_max_f32_e32 v107, v107, v107
	v_max_f32_e32 v108, v108, v108
	v_mul_f32_e32 v118, v118, v118
	v_mul_f32_e32 v117, v117, v117
	v_cvt_pk_bf16_f32 v114, v118, v114
	v_cvt_pk_bf16_f32 v115, v115, v116
	v_cvt_pk_bf16_f32 v116, v124, v119
	v_max_f32_e32 v106, 0, v106
	v_max_f32_e32 v107, 0, v107
	v_max_f32_e32 v108, 0, v108
	v_cvt_pk_bf16_f32 v117, v120, v117
	global_store_dwordx4 v[122:123], v[114:117], off offset:256
	v_max_f32_e32 v110, v110, v110
	v_max_f32_e32 v110, 0, v110
	v_or_b32_e32 v114, 16, v144
	v_mul_f32_e32 v116, v106, v106
	v_max_f32_e32 v106, v111, v111
	v_mul_f32_e32 v111, v107, v107
	v_max_f32_e32 v107, v112, v112
	v_mul_f32_e32 v112, v108, v108
	v_max_f32_e32 v108, v113, v113
	v_ashrrev_i32_e32 v115, 31, v114
	v_max_f32_e32 v106, 0, v106
	v_max_f32_e32 v107, 0, v107
	v_max_f32_e32 v108, 0, v108
	v_lshlrev_b64 v[114:115], 14, v[114:115]
	v_mul_f32_e32 v110, v110, v110
	v_mul_f32_e32 v106, v106, v106
	v_mul_f32_e32 v107, v107, v107
	v_max_f32_e32 v109, v109, v109
	v_mul_f32_e32 v108, v108, v108
	v_max_f32_e32 v109, 0, v109
	v_cvt_pk_bf16_f32 v106, v110, v106
	v_cvt_pk_bf16_f32 v107, v107, v108
	v_cvt_pk_bf16_f32 v108, v116, v111
	v_lshl_add_u64 v[110:111], s[6:7], 0, v[114:115]
	v_max_f32_e32 v98, v98, v98
	v_max_f32_e32 v99, v99, v99
	v_max_f32_e32 v100, v100, v100
	v_mul_f32_e32 v109, v109, v109
	v_lshl_add_u64 v[110:111], v[110:111], 0, v[128:129]
	v_max_f32_e32 v98, 0, v98
	v_max_f32_e32 v99, 0, v99
	v_max_f32_e32 v100, 0, v100
	v_cvt_pk_bf16_f32 v109, v112, v109
	global_store_dwordx4 v[110:111], v[106:109], off
	v_max_f32_e32 v102, v102, v102
	v_max_f32_e32 v101, v101, v101
	v_mul_f32_e32 v106, v98, v98
	v_max_f32_e32 v98, v103, v103
	v_mul_f32_e32 v103, v99, v99
	v_max_f32_e32 v99, v104, v104
	v_mul_f32_e32 v104, v100, v100
	v_max_f32_e32 v100, v105, v105
	v_max_f32_e32 v98, 0, v98
	v_max_f32_e32 v99, 0, v99
	v_max_f32_e32 v100, 0, v100
	v_max_f32_e32 v102, 0, v102
	v_mul_f32_e32 v98, v98, v98
	v_mul_f32_e32 v99, v99, v99
	v_max_f32_e32 v101, 0, v101
	v_mul_f32_e32 v100, v100, v100
	v_max_f32_e32 v90, v90, v90
	v_max_f32_e32 v91, v91, v91
	v_max_f32_e32 v92, v92, v92
	v_mul_f32_e32 v102, v102, v102
	v_mul_f32_e32 v101, v101, v101
	v_cvt_pk_bf16_f32 v98, v102, v98
	v_cvt_pk_bf16_f32 v99, v99, v100
	v_cvt_pk_bf16_f32 v100, v106, v103
	v_max_f32_e32 v90, 0, v90
	v_max_f32_e32 v91, 0, v91
	v_max_f32_e32 v92, 0, v92
	v_cvt_pk_bf16_f32 v101, v104, v101
	global_store_dwordx4 v[110:111], v[98:101], off offset:256
	v_max_f32_e32 v94, v94, v94
	v_max_f32_e32 v94, 0, v94
	v_or_b32_e32 v98, 32, v144
	v_mul_f32_e32 v100, v90, v90
	v_max_f32_e32 v90, v95, v95
	v_mul_f32_e32 v95, v91, v91
	v_max_f32_e32 v91, v96, v96
	v_mul_f32_e32 v96, v92, v92
	v_max_f32_e32 v92, v97, v97
	v_ashrrev_i32_e32 v99, 31, v98
	v_max_f32_e32 v90, 0, v90
	v_max_f32_e32 v91, 0, v91
	v_max_f32_e32 v92, 0, v92
	v_lshlrev_b64 v[98:99], 14, v[98:99]
	v_mul_f32_e32 v94, v94, v94
	v_mul_f32_e32 v90, v90, v90
	v_mul_f32_e32 v91, v91, v91
	v_max_f32_e32 v93, v93, v93
	v_mul_f32_e32 v92, v92, v92
	v_max_f32_e32 v93, 0, v93
	v_cvt_pk_bf16_f32 v90, v94, v90
	v_cvt_pk_bf16_f32 v91, v91, v92
	v_cvt_pk_bf16_f32 v92, v100, v95
	v_lshl_add_u64 v[94:95], s[6:7], 0, v[98:99]
	v_max_f32_e32 v82, v82, v82
	v_max_f32_e32 v83, v83, v83
	v_max_f32_e32 v84, v84, v84
	v_mul_f32_e32 v93, v93, v93
	v_lshl_add_u64 v[94:95], v[94:95], 0, v[128:129]
	v_max_f32_e32 v82, 0, v82
	v_max_f32_e32 v83, 0, v83
	v_max_f32_e32 v84, 0, v84
	v_cvt_pk_bf16_f32 v93, v96, v93
	global_store_dwordx4 v[94:95], v[90:93], off
	v_max_f32_e32 v86, v86, v86
	v_max_f32_e32 v85, v85, v85
	v_mul_f32_e32 v90, v82, v82
	v_max_f32_e32 v82, v87, v87
	v_mul_f32_e32 v87, v83, v83
	v_max_f32_e32 v83, v88, v88
	v_mul_f32_e32 v88, v84, v84
	v_max_f32_e32 v84, v89, v89
	v_max_f32_e32 v82, 0, v82
	v_max_f32_e32 v83, 0, v83
	v_max_f32_e32 v84, 0, v84
	v_max_f32_e32 v86, 0, v86
	v_mul_f32_e32 v82, v82, v82
	v_mul_f32_e32 v83, v83, v83
	v_max_f32_e32 v85, 0, v85
	v_mul_f32_e32 v84, v84, v84
	v_max_f32_e32 v74, v74, v74
	v_max_f32_e32 v75, v75, v75
	v_max_f32_e32 v76, v76, v76
	v_mul_f32_e32 v86, v86, v86
	v_mul_f32_e32 v85, v85, v85
	v_cvt_pk_bf16_f32 v82, v86, v82
	v_cvt_pk_bf16_f32 v83, v83, v84
	v_cvt_pk_bf16_f32 v84, v90, v87
	v_max_f32_e32 v74, 0, v74
	v_max_f32_e32 v75, 0, v75
	v_max_f32_e32 v76, 0, v76
	v_cvt_pk_bf16_f32 v85, v88, v85
	global_store_dwordx4 v[94:95], v[82:85], off offset:256
	v_max_f32_e32 v78, v78, v78
	v_max_f32_e32 v78, 0, v78
	v_or_b32_e32 v82, 48, v144
	v_mul_f32_e32 v84, v74, v74
	v_max_f32_e32 v74, v79, v79
	v_mul_f32_e32 v79, v75, v75
	v_max_f32_e32 v75, v80, v80
	v_mul_f32_e32 v80, v76, v76
	v_max_f32_e32 v76, v81, v81
	v_ashrrev_i32_e32 v83, 31, v82
	v_max_f32_e32 v74, 0, v74
	v_max_f32_e32 v75, 0, v75
	v_max_f32_e32 v76, 0, v76
	v_lshlrev_b64 v[82:83], 14, v[82:83]
	v_mul_f32_e32 v78, v78, v78
	v_mul_f32_e32 v74, v74, v74
	v_mul_f32_e32 v75, v75, v75
	v_max_f32_e32 v77, v77, v77
	v_mul_f32_e32 v76, v76, v76
	v_max_f32_e32 v77, 0, v77
	v_cvt_pk_bf16_f32 v74, v78, v74
	v_cvt_pk_bf16_f32 v75, v75, v76
	v_cvt_pk_bf16_f32 v76, v84, v79
	v_lshl_add_u64 v[78:79], s[6:7], 0, v[82:83]
	v_max_f32_e32 v66, v66, v66
	v_mul_f32_e32 v77, v77, v77
	v_lshl_add_u64 v[78:79], v[78:79], 0, v[128:129]
	v_max_f32_e32 v66, 0, v66
	v_max_f32_e32 v67, v67, v67
	v_max_f32_e32 v68, v68, v68
	v_cvt_pk_bf16_f32 v77, v80, v77
	global_store_dwordx4 v[78:79], v[74:77], off
	v_max_f32_e32 v67, 0, v67
	v_max_f32_e32 v68, 0, v68
	v_mul_f32_e32 v74, v66, v66
	v_max_f32_e32 v66, v71, v71
	v_max_f32_e32 v70, v70, v70
	v_max_f32_e32 v66, 0, v66
	v_mul_f32_e32 v71, v67, v67
	v_max_f32_e32 v67, v72, v72
	v_mul_f32_e32 v72, v68, v68
	v_max_f32_e32 v68, v73, v73
	v_max_f32_e32 v69, v69, v69
	v_max_f32_e32 v70, 0, v70
	v_mul_f32_e32 v66, v66, v66
	v_max_f32_e32 v67, 0, v67
	v_max_f32_e32 v68, 0, v68
	v_max_f32_e32 v69, 0, v69
	v_max_f32_e32 v58, v58, v58
	v_max_f32_e32 v59, v59, v59
	v_max_f32_e32 v60, v60, v60
	v_mul_f32_e32 v70, v70, v70
	v_mul_f32_e32 v67, v67, v67
	v_mul_f32_e32 v68, v68, v68
	v_mul_f32_e32 v69, v69, v69
	v_cvt_pk_bf16_f32 v66, v70, v66
	v_max_f32_e32 v58, 0, v58
	v_max_f32_e32 v59, 0, v59
	v_max_f32_e32 v60, 0, v60
	v_cvt_pk_bf16_f32 v67, v67, v68
	v_cvt_pk_bf16_f32 v68, v74, v71
	v_cvt_pk_bf16_f32 v69, v72, v69
	global_store_dwordx4 v[78:79], v[66:69], off offset:256
	v_max_f32_e32 v62, v62, v62
	v_max_f32_e32 v62, 0, v62
	v_mul_f32_e32 v66, v58, v58
	v_max_f32_e32 v58, v63, v63
	v_mul_f32_e32 v63, v59, v59
	v_max_f32_e32 v59, v64, v64
	v_mul_f32_e32 v64, v60, v60
	v_max_f32_e32 v60, v65, v65
	v_max_f32_e32 v58, 0, v58
	v_max_f32_e32 v59, 0, v59
	v_max_f32_e32 v60, 0, v60
	v_max_f32_e32 v61, v61, v61
	v_mul_f32_e32 v62, v62, v62
	v_mul_f32_e32 v58, v58, v58
	v_mul_f32_e32 v59, v59, v59
	v_max_f32_e32 v61, 0, v61
	v_mul_f32_e32 v60, v60, v60
	s_mov_b64 s[2:3], 0x200000
	v_mul_f32_e32 v61, v61, v61
	v_cvt_pk_bf16_f32 v58, v62, v58
	v_cvt_pk_bf16_f32 v59, v59, v60
	v_cvt_pk_bf16_f32 v60, v66, v63
	v_lshl_add_u64 v[62:63], v[122:123], 0, s[2:3]
	s_mov_b32 s2, 0x200000
	v_cvt_pk_bf16_f32 v61, v64, v61
	v_add_co_u32_e32 v64, vcc, s2, v122
	v_max_f32_e32 v50, v50, v50
	s_nop 0
	v_addc_co_u32_e32 v65, vcc, 0, v123, vcc
	v_max_f32_e32 v50, 0, v50
	v_max_f32_e32 v51, v51, v51
	v_max_f32_e32 v52, v52, v52
	global_store_dwordx4 v[64:65], v[58:61], off
	v_max_f32_e32 v51, 0, v51
	v_max_f32_e32 v52, 0, v52
	v_mul_f32_e32 v58, v50, v50
	v_max_f32_e32 v50, v55, v55
	v_max_f32_e32 v54, v54, v54
	v_max_f32_e32 v50, 0, v50
	v_mul_f32_e32 v55, v51, v51
	v_max_f32_e32 v51, v56, v56
	v_mul_f32_e32 v56, v52, v52
	v_max_f32_e32 v52, v57, v57
	v_max_f32_e32 v53, v53, v53
	v_max_f32_e32 v54, 0, v54
	v_mul_f32_e32 v50, v50, v50
	v_max_f32_e32 v51, 0, v51
	v_max_f32_e32 v52, 0, v52
	v_max_f32_e32 v53, 0, v53
	v_max_f32_e32 v42, v42, v42
	v_max_f32_e32 v43, v43, v43
	v_max_f32_e32 v44, v44, v44
	v_mul_f32_e32 v54, v54, v54
	v_mul_f32_e32 v51, v51, v51
	v_mul_f32_e32 v52, v52, v52
	v_mul_f32_e32 v53, v53, v53
	v_cvt_pk_bf16_f32 v50, v54, v50
	v_max_f32_e32 v42, 0, v42
	v_max_f32_e32 v43, 0, v43
	v_max_f32_e32 v44, 0, v44
	v_cvt_pk_bf16_f32 v51, v51, v52
	v_cvt_pk_bf16_f32 v52, v58, v55
	v_cvt_pk_bf16_f32 v53, v56, v53
	global_store_dwordx4 v[62:63], v[50:53], off offset:256
	v_max_f32_e32 v46, v46, v46
	v_max_f32_e32 v46, 0, v46
	v_mul_f32_e32 v50, v42, v42
	v_max_f32_e32 v42, v47, v47
	v_mul_f32_e32 v47, v43, v43
	v_max_f32_e32 v43, v48, v48
	v_mul_f32_e32 v48, v44, v44
	v_max_f32_e32 v44, v49, v49
	v_max_f32_e32 v42, 0, v42
	v_max_f32_e32 v43, 0, v43
	v_max_f32_e32 v44, 0, v44
	v_max_f32_e32 v45, v45, v45
	v_mul_f32_e32 v46, v46, v46
	v_mul_f32_e32 v42, v42, v42
	v_mul_f32_e32 v43, v43, v43
	v_max_f32_e32 v45, 0, v45
	v_mul_f32_e32 v44, v44, v44
	s_mov_b64 s[2:3], 0x240000
	v_mul_f32_e32 v45, v45, v45
	v_cvt_pk_bf16_f32 v42, v46, v42
	v_cvt_pk_bf16_f32 v43, v43, v44
	v_cvt_pk_bf16_f32 v44, v50, v47
	v_lshl_add_u64 v[46:47], v[122:123], 0, s[2:3]
	s_mov_b32 s2, 0x240000
	v_cvt_pk_bf16_f32 v45, v48, v45
	v_add_co_u32_e32 v48, vcc, s2, v122
	v_max_f32_e32 v34, v34, v34
	s_nop 0
	v_addc_co_u32_e32 v49, vcc, 0, v123, vcc
	v_max_f32_e32 v34, 0, v34
	v_max_f32_e32 v35, v35, v35
	v_max_f32_e32 v36, v36, v36
	global_store_dwordx4 v[48:49], v[42:45], off
	v_max_f32_e32 v35, 0, v35
	v_max_f32_e32 v36, 0, v36
	v_mul_f32_e32 v42, v34, v34
	v_max_f32_e32 v34, v39, v39
	v_max_f32_e32 v38, v38, v38
	v_max_f32_e32 v34, 0, v34
	v_mul_f32_e32 v39, v35, v35
	v_max_f32_e32 v35, v40, v40
	v_mul_f32_e32 v40, v36, v36
	v_max_f32_e32 v36, v41, v41
	v_max_f32_e32 v37, v37, v37
	v_max_f32_e32 v38, 0, v38
	v_mul_f32_e32 v34, v34, v34
	v_max_f32_e32 v35, 0, v35
	v_max_f32_e32 v36, 0, v36
	v_max_f32_e32 v37, 0, v37
	v_max_f32_e32 v26, v26, v26
	v_max_f32_e32 v27, v27, v27
	v_max_f32_e32 v28, v28, v28
	v_mul_f32_e32 v38, v38, v38
	v_mul_f32_e32 v35, v35, v35
	v_mul_f32_e32 v36, v36, v36
	v_mul_f32_e32 v37, v37, v37
	v_cvt_pk_bf16_f32 v34, v38, v34
	v_max_f32_e32 v26, 0, v26
	v_max_f32_e32 v27, 0, v27
	v_max_f32_e32 v28, 0, v28
	v_cvt_pk_bf16_f32 v35, v35, v36
	v_cvt_pk_bf16_f32 v36, v42, v39
	v_cvt_pk_bf16_f32 v37, v40, v37
	global_store_dwordx4 v[46:47], v[34:37], off offset:256
	v_max_f32_e32 v30, v30, v30
	v_max_f32_e32 v30, 0, v30
	v_mul_f32_e32 v34, v26, v26
	v_max_f32_e32 v26, v31, v31
	v_mul_f32_e32 v31, v27, v27
	v_max_f32_e32 v27, v32, v32
	v_mul_f32_e32 v32, v28, v28
	v_max_f32_e32 v28, v33, v33
	v_max_f32_e32 v26, 0, v26
	v_max_f32_e32 v27, 0, v27
	v_max_f32_e32 v28, 0, v28
	v_max_f32_e32 v29, v29, v29
	v_mul_f32_e32 v30, v30, v30
	v_mul_f32_e32 v26, v26, v26
	v_mul_f32_e32 v27, v27, v27
	v_max_f32_e32 v29, 0, v29
	v_mul_f32_e32 v28, v28, v28
	s_mov_b64 s[2:3], 0x280000
	v_mul_f32_e32 v29, v29, v29
	v_cvt_pk_bf16_f32 v26, v30, v26
	v_cvt_pk_bf16_f32 v27, v27, v28
	v_cvt_pk_bf16_f32 v28, v34, v31
	v_lshl_add_u64 v[30:31], v[122:123], 0, s[2:3]
	s_mov_b32 s2, 0x280000
	v_cvt_pk_bf16_f32 v29, v32, v29
	v_add_co_u32_e32 v32, vcc, s2, v122
	v_max_f32_e32 v18, v18, v18
	s_nop 0
	v_addc_co_u32_e32 v33, vcc, 0, v123, vcc
	v_max_f32_e32 v18, 0, v18
	v_max_f32_e32 v19, v19, v19
	v_max_f32_e32 v20, v20, v20
	global_store_dwordx4 v[32:33], v[26:29], off
	v_max_f32_e32 v19, 0, v19
	v_max_f32_e32 v20, 0, v20
	v_mul_f32_e32 v26, v18, v18
	v_max_f32_e32 v18, v23, v23
	v_max_f32_e32 v22, v22, v22
	v_max_f32_e32 v18, 0, v18
	v_mul_f32_e32 v23, v19, v19
	v_max_f32_e32 v19, v24, v24
	v_mul_f32_e32 v24, v20, v20
	v_max_f32_e32 v20, v25, v25
	v_max_f32_e32 v21, v21, v21
	v_max_f32_e32 v22, 0, v22
	v_mul_f32_e32 v18, v18, v18
	v_max_f32_e32 v19, 0, v19
	v_max_f32_e32 v20, 0, v20
	v_max_f32_e32 v21, 0, v21
	v_max_f32_e32 v10, v10, v10
	v_max_f32_e32 v11, v11, v11
	v_max_f32_e32 v12, v12, v12
	v_mul_f32_e32 v22, v22, v22
	v_mul_f32_e32 v19, v19, v19
	v_mul_f32_e32 v20, v20, v20
	v_mul_f32_e32 v21, v21, v21
	v_cvt_pk_bf16_f32 v18, v22, v18
	v_max_f32_e32 v10, 0, v10
	v_max_f32_e32 v11, 0, v11
	v_max_f32_e32 v12, 0, v12
	v_cvt_pk_bf16_f32 v19, v19, v20
	v_cvt_pk_bf16_f32 v20, v26, v23
	v_cvt_pk_bf16_f32 v21, v24, v21
	global_store_dwordx4 v[30:31], v[18:21], off offset:256
	v_max_f32_e32 v14, v14, v14
	v_max_f32_e32 v14, 0, v14
	v_mul_f32_e32 v18, v10, v10
	v_max_f32_e32 v10, v15, v15
	v_mul_f32_e32 v15, v11, v11
	v_max_f32_e32 v11, v16, v16
	v_mul_f32_e32 v16, v12, v12
	v_max_f32_e32 v12, v17, v17
	v_max_f32_e32 v10, 0, v10
	v_max_f32_e32 v11, 0, v11
	v_max_f32_e32 v12, 0, v12
	v_max_f32_e32 v13, v13, v13
	v_mul_f32_e32 v14, v14, v14
	v_mul_f32_e32 v10, v10, v10
	v_mul_f32_e32 v11, v11, v11
	v_max_f32_e32 v13, 0, v13
	v_mul_f32_e32 v12, v12, v12
	s_mov_b64 s[2:3], 0x2c0000
	v_mul_f32_e32 v13, v13, v13
	v_cvt_pk_bf16_f32 v10, v14, v10
	v_cvt_pk_bf16_f32 v11, v11, v12
	v_cvt_pk_bf16_f32 v12, v18, v15
	v_lshl_add_u64 v[14:15], v[122:123], 0, s[2:3]
	s_mov_b32 s2, 0x2c0000
	v_cvt_pk_bf16_f32 v13, v16, v13
	v_add_co_u32_e32 v16, vcc, s2, v122
	v_max_f32_e32 v2, v2, v2
	v_max_f32_e32 v3, v3, v3
	v_max_f32_e32 v4, v4, v4
	v_addc_co_u32_e32 v17, vcc, 0, v123, vcc
	v_max_f32_e32 v2, 0, v2
	v_max_f32_e32 v3, 0, v3
	v_max_f32_e32 v4, 0, v4
	global_store_dwordx4 v[16:17], v[10:13], off
	v_max_f32_e32 v5, v5, v5
	v_max_f32_e32 v6, v6, v6
	v_mul_f32_e32 v10, v2, v2
	v_max_f32_e32 v2, v7, v7
	v_mul_f32_e32 v7, v3, v3
	v_max_f32_e32 v3, v8, v8
	v_mul_f32_e32 v8, v4, v4
	v_max_f32_e32 v4, v9, v9
	v_max_f32_e32 v2, 0, v2
	v_max_f32_e32 v3, 0, v3
	v_max_f32_e32 v4, 0, v4
	v_max_f32_e32 v5, 0, v5
	v_readlane_b32 s20, v254, 38
	v_max_f32_e32 v6, 0, v6
	v_mul_f32_e32 v2, v2, v2
	v_mul_f32_e32 v3, v3, v3
	v_mul_f32_e32 v4, v4, v4
	v_mul_f32_e32 v5, v5, v5
	s_andn2_b64 vcc, exec, s[36:37]
	s_mov_b64 s[2:3], -1
	v_readlane_b32 s22, v254, 36
	v_readlane_b32 s21, v254, 39
	v_mul_f32_e32 v6, v6, v6
	v_cvt_pk_bf16_f32 v2, v6, v2
	v_cvt_pk_bf16_f32 v3, v3, v4
	v_cvt_pk_bf16_f32 v4, v10, v7
	v_cvt_pk_bf16_f32 v5, v8, v5
	global_store_dwordx4 v[14:15], v[2:5], off offset:256
	v_readlane_b32 s23, v254, 37
	s_cbranch_vccnz .LBB2_194
	s_andn2_b64 vcc, exec, s[4:5]
	s_cbranch_vccnz .LBB2_193
	s_barrier
	s_branch .LBB2_193

.LBB2_331:
	s_or_b64 exec, exec, s[0:1]
	s_waitcnt lgkmcnt(0)
	v_add_u32_e32 v0, s60, v162
	ds_read_b128 v[66:69], v0
	ds_read_b128 v[70:73], v0 offset:32
	s_lshl_b64 s[0:1], s[6:7], 19
	s_add_u32 s0, s39, s0
	s_addc_u32 s1, s56, s1
	s_waitcnt lgkmcnt(0)
	v_rcp_f32_e32 v74, v66
	v_rcp_f32_e32 v75, v67
	v_rcp_f32_e32 v76, v68
	v_rcp_f32_e32 v77, v69
	v_rcp_f32_e32 v78, v70
	ds_read_b128 v[66:69], v0 offset:64
	v_rcp_f32_e32 v79, v71
	v_rcp_f32_e32 v80, v72
	v_rcp_f32_e32 v81, v73
	ds_read_b128 v[70:73], v0 offset:96
	s_lshl_b32 s2, s5, 1
	s_add_u32 s2, s0, s2
	s_addc_u32 s3, s1, 0
	s_ashr_i32 s5, s4, 31
	s_lshl_b64 s[0:1], s[4:5], 11
	s_lshl_b32 s4, s59, 13
	s_waitcnt lgkmcnt(0)
	v_rcp_f32_e32 v0, v66
	v_rcp_f32_e32 v66, v67
	v_rcp_f32_e32 v67, v68
	v_rcp_f32_e32 v68, v69
	v_rcp_f32_e32 v69, v70
	v_rcp_f32_e32 v70, v71
	v_rcp_f32_e32 v71, v72
	v_rcp_f32_e32 v72, v73
	s_add_i32 s4, s4, 0
	v_lshlrev_b32_e32 v73, 10, v192
	v_lshlrev_b32_e32 v82, 1, v191
	v_mul_f32_e32 v2, v2, v74
	v_add3_u32 v73, s4, v73, v82
	v_bfe_u32 v82, v2, 16, 1
	v_add3_u32 v2, v2, v82, s33
	ds_write_b16_d16_hi v73, v2
	v_mul_f32_e32 v2, v50, v74
	v_bfe_u32 v50, v2, 16, 1
	v_add3_u32 v2, v2, v50, s33
	ds_write_b16_d16_hi v73, v2 offset:64
	v_mul_f32_e32 v2, v34, v74
	v_bfe_u32 v34, v2, 16, 1
	v_add3_u32 v2, v2, v34, s33
	ds_write_b16_d16_hi v73, v2 offset:128
	v_mul_f32_e32 v2, v18, v74
	v_bfe_u32 v18, v2, 16, 1
	v_add3_u32 v2, v2, v18, s33
	ds_write_b16_d16_hi v73, v2 offset:192
	v_mul_f32_e32 v2, v3, v75
	v_bfe_u32 v3, v2, 16, 1
	v_add3_u32 v2, v2, v3, s33
	ds_write_b16_d16_hi v73, v2 offset:256
	v_mul_f32_e32 v2, v51, v75
	v_bfe_u32 v3, v2, 16, 1
	v_add3_u32 v2, v2, v3, s33
	ds_write_b16_d16_hi v73, v2 offset:320
	v_mul_f32_e32 v2, v35, v75
	v_bfe_u32 v3, v2, 16, 1
	v_add3_u32 v2, v2, v3, s33
	ds_write_b16_d16_hi v73, v2 offset:384
	v_mul_f32_e32 v2, v19, v75
	v_bfe_u32 v3, v2, 16, 1
	v_add3_u32 v2, v2, v3, s33
	ds_write_b16_d16_hi v73, v2 offset:448
	v_mul_f32_e32 v2, v4, v76
	v_bfe_u32 v3, v2, 16, 1
	v_add3_u32 v2, v2, v3, s33
	ds_write_b16_d16_hi v73, v2 offset:512
	v_mul_f32_e32 v2, v52, v76
	v_bfe_u32 v3, v2, 16, 1
	v_add3_u32 v2, v2, v3, s33
	ds_write_b16_d16_hi v73, v2 offset:576
	v_mul_f32_e32 v2, v36, v76
	v_bfe_u32 v3, v2, 16, 1
	v_add3_u32 v2, v2, v3, s33
	ds_write_b16_d16_hi v73, v2 offset:640
	v_mul_f32_e32 v2, v20, v76
	v_bfe_u32 v3, v2, 16, 1
	v_add3_u32 v2, v2, v3, s33
	ds_write_b16_d16_hi v73, v2 offset:704
	v_mul_f32_e32 v2, v5, v77
	v_bfe_u32 v3, v2, 16, 1
	v_add3_u32 v2, v2, v3, s33
	ds_write_b16_d16_hi v73, v2 offset:768
	v_mul_f32_e32 v2, v53, v77
	v_bfe_u32 v3, v2, 16, 1
	v_add3_u32 v2, v2, v3, s33
	ds_write_b16_d16_hi v73, v2 offset:832
	v_mul_f32_e32 v2, v37, v77
	v_bfe_u32 v3, v2, 16, 1
	v_add3_u32 v2, v2, v3, s33
	ds_write_b16_d16_hi v73, v2 offset:896
	v_mul_f32_e32 v2, v21, v77
	v_bfe_u32 v3, v2, 16, 1
	v_add3_u32 v2, v2, v3, s33
	ds_write_b16_d16_hi v73, v2 offset:960
	v_mul_f32_e32 v2, v6, v78
	v_bfe_u32 v3, v2, 16, 1
	v_add3_u32 v2, v2, v3, s33
	ds_write_b16_d16_hi v73, v2 offset:2048
	v_mul_f32_e32 v2, v54, v78
	v_bfe_u32 v3, v2, 16, 1
	v_add3_u32 v2, v2, v3, s33
	ds_write_b16_d16_hi v73, v2 offset:2112
	v_mul_f32_e32 v2, v38, v78
	v_bfe_u32 v3, v2, 16, 1
	v_add3_u32 v2, v2, v3, s33
	ds_write_b16_d16_hi v73, v2 offset:2176
	v_mul_f32_e32 v2, v22, v78
	v_bfe_u32 v3, v2, 16, 1
	v_add3_u32 v2, v2, v3, s33
	ds_write_b16_d16_hi v73, v2 offset:2240
	v_mul_f32_e32 v2, v7, v79
	v_bfe_u32 v3, v2, 16, 1
	v_add3_u32 v2, v2, v3, s33
	ds_write_b16_d16_hi v73, v2 offset:2304
	v_mul_f32_e32 v2, v55, v79
	v_bfe_u32 v3, v2, 16, 1
	v_add3_u32 v2, v2, v3, s33
	ds_write_b16_d16_hi v73, v2 offset:2368
	v_mul_f32_e32 v2, v39, v79
	v_bfe_u32 v3, v2, 16, 1
	v_add3_u32 v2, v2, v3, s33
	ds_write_b16_d16_hi v73, v2 offset:2432
	v_mul_f32_e32 v2, v23, v79
	v_bfe_u32 v3, v2, 16, 1
	v_add3_u32 v2, v2, v3, s33
	ds_write_b16_d16_hi v73, v2 offset:2496
	v_mul_f32_e32 v2, v8, v80
	v_bfe_u32 v3, v2, 16, 1
	v_add3_u32 v2, v2, v3, s33
	ds_write_b16_d16_hi v73, v2 offset:2560
	v_mul_f32_e32 v2, v56, v80
	v_bfe_u32 v3, v2, 16, 1
	v_add3_u32 v2, v2, v3, s33
	ds_write_b16_d16_hi v73, v2 offset:2624
	v_mul_f32_e32 v2, v40, v80
	v_bfe_u32 v3, v2, 16, 1
	v_add3_u32 v2, v2, v3, s33
	ds_write_b16_d16_hi v73, v2 offset:2688
	v_mul_f32_e32 v2, v24, v80
	v_bfe_u32 v3, v2, 16, 1
	v_add3_u32 v2, v2, v3, s33
	ds_write_b16_d16_hi v73, v2 offset:2752
	v_mul_f32_e32 v2, v9, v81
	v_bfe_u32 v3, v2, 16, 1
	v_add3_u32 v2, v2, v3, s33
	ds_write_b16_d16_hi v73, v2 offset:2816
	v_mul_f32_e32 v2, v57, v81
	v_bfe_u32 v3, v2, 16, 1
	v_add3_u32 v2, v2, v3, s33
	ds_write_b16_d16_hi v73, v2 offset:2880
	v_mul_f32_e32 v2, v41, v81
	v_bfe_u32 v3, v2, 16, 1
	v_add3_u32 v2, v2, v3, s33
	ds_write_b16_d16_hi v73, v2 offset:2944
	v_mul_f32_e32 v2, v25, v81
	v_bfe_u32 v3, v2, 16, 1
	v_add3_u32 v2, v2, v3, s33
	ds_write_b16_d16_hi v73, v2 offset:3008
	v_mul_f32_e32 v2, v10, v0
	v_bfe_u32 v3, v2, 16, 1
	v_add3_u32 v2, v2, v3, s33
	ds_write_b16_d16_hi v73, v2 offset:4096
	v_mul_f32_e32 v2, v58, v0
	v_bfe_u32 v3, v2, 16, 1
	v_add3_u32 v2, v2, v3, s33
	ds_write_b16_d16_hi v73, v2 offset:4160
	v_mul_f32_e32 v2, v42, v0
	v_bfe_u32 v3, v2, 16, 1
	v_add3_u32 v2, v2, v3, s33
	v_mul_f32_e32 v0, v26, v0
	ds_write_b16_d16_hi v73, v2 offset:4224
	v_bfe_u32 v2, v0, 16, 1
	v_add3_u32 v0, v0, v2, s33
	ds_write_b16_d16_hi v73, v0 offset:4288
	v_mul_f32_e32 v0, v11, v66
	v_bfe_u32 v2, v0, 16, 1
	v_add3_u32 v0, v0, v2, s33
	ds_write_b16_d16_hi v73, v0 offset:4352
	v_mul_f32_e32 v0, v59, v66
	v_bfe_u32 v2, v0, 16, 1
	v_add3_u32 v0, v0, v2, s33
	ds_write_b16_d16_hi v73, v0 offset:4416
	v_mul_f32_e32 v0, v43, v66
	v_bfe_u32 v2, v0, 16, 1
	v_add3_u32 v0, v0, v2, s33
	ds_write_b16_d16_hi v73, v0 offset:4480
	v_mul_f32_e32 v0, v27, v66
	v_bfe_u32 v2, v0, 16, 1
	v_add3_u32 v0, v0, v2, s33
	ds_write_b16_d16_hi v73, v0 offset:4544
	v_mul_f32_e32 v0, v12, v67
	v_bfe_u32 v2, v0, 16, 1
	v_add3_u32 v0, v0, v2, s33
	ds_write_b16_d16_hi v73, v0 offset:4608
	v_mul_f32_e32 v0, v60, v67
	v_bfe_u32 v2, v0, 16, 1
	v_add3_u32 v0, v0, v2, s33
	ds_write_b16_d16_hi v73, v0 offset:4672
	v_mul_f32_e32 v0, v44, v67
	v_bfe_u32 v2, v0, 16, 1
	v_add3_u32 v0, v0, v2, s33
	ds_write_b16_d16_hi v73, v0 offset:4736
	v_mul_f32_e32 v0, v28, v67
	v_bfe_u32 v2, v0, 16, 1
	v_add3_u32 v0, v0, v2, s33
	ds_write_b16_d16_hi v73, v0 offset:4800
	v_mul_f32_e32 v0, v13, v68
	v_bfe_u32 v2, v0, 16, 1
	v_add3_u32 v0, v0, v2, s33
	ds_write_b16_d16_hi v73, v0 offset:4864
	v_mul_f32_e32 v0, v61, v68
	v_bfe_u32 v2, v0, 16, 1
	v_add3_u32 v0, v0, v2, s33
	ds_write_b16_d16_hi v73, v0 offset:4928
	v_mul_f32_e32 v0, v45, v68
	v_bfe_u32 v2, v0, 16, 1
	v_add3_u32 v0, v0, v2, s33
	ds_write_b16_d16_hi v73, v0 offset:4992
	v_mul_f32_e32 v0, v29, v68
	v_bfe_u32 v2, v0, 16, 1
	v_add3_u32 v0, v0, v2, s33
	ds_write_b16_d16_hi v73, v0 offset:5056
	v_mul_f32_e32 v0, v14, v69
	v_bfe_u32 v2, v0, 16, 1
	v_add3_u32 v0, v0, v2, s33
	ds_write_b16_d16_hi v73, v0 offset:6144
	v_mul_f32_e32 v0, v62, v69
	v_bfe_u32 v2, v0, 16, 1
	v_add3_u32 v0, v0, v2, s33
	ds_write_b16_d16_hi v73, v0 offset:6208
	v_mul_f32_e32 v0, v46, v69
	v_bfe_u32 v2, v0, 16, 1
	v_add3_u32 v0, v0, v2, s33
	ds_write_b16_d16_hi v73, v0 offset:6272
	v_mul_f32_e32 v0, v30, v69
	v_bfe_u32 v2, v0, 16, 1
	v_add3_u32 v0, v0, v2, s33
	ds_write_b16_d16_hi v73, v0 offset:6336
	v_mul_f32_e32 v0, v15, v70
	v_bfe_u32 v2, v0, 16, 1
	v_add3_u32 v0, v0, v2, s33
	ds_write_b16_d16_hi v73, v0 offset:6400
	v_mul_f32_e32 v0, v63, v70
	v_bfe_u32 v2, v0, 16, 1
	v_add3_u32 v0, v0, v2, s33
	ds_write_b16_d16_hi v73, v0 offset:6464
	v_mul_f32_e32 v0, v47, v70
	v_bfe_u32 v2, v0, 16, 1
	v_add3_u32 v0, v0, v2, s33
	ds_write_b16_d16_hi v73, v0 offset:6528
	v_mul_f32_e32 v0, v31, v70
	v_bfe_u32 v2, v0, 16, 1
	v_add3_u32 v0, v0, v2, s33
	ds_write_b16_d16_hi v73, v0 offset:6592
	v_mul_f32_e32 v0, v16, v71
	v_bfe_u32 v2, v0, 16, 1
	v_add3_u32 v0, v0, v2, s33
	ds_write_b16_d16_hi v73, v0 offset:6656
	v_mul_f32_e32 v0, v64, v71
	v_bfe_u32 v2, v0, 16, 1
	v_add3_u32 v0, v0, v2, s33
	ds_write_b16_d16_hi v73, v0 offset:6720
	v_mul_f32_e32 v0, v48, v71
	v_bfe_u32 v2, v0, 16, 1
	v_add3_u32 v0, v0, v2, s33
	ds_write_b16_d16_hi v73, v0 offset:6784
	v_mul_f32_e32 v0, v32, v71
	v_bfe_u32 v2, v0, 16, 1
	v_add3_u32 v0, v0, v2, s33
	ds_write_b16_d16_hi v73, v0 offset:6848
	v_mul_f32_e32 v0, v17, v72
	v_bfe_u32 v2, v0, 16, 1
	v_add3_u32 v0, v0, v2, s33
	ds_write_b16_d16_hi v73, v0 offset:6912
	v_mul_f32_e32 v0, v65, v72
	v_bfe_u32 v2, v0, 16, 1
	v_add3_u32 v0, v0, v2, s33
	ds_write_b16_d16_hi v73, v0 offset:6976
	v_mul_f32_e32 v0, v49, v72
	v_bfe_u32 v2, v0, 16, 1
	v_add3_u32 v0, v0, v2, s33
	ds_write_b16_d16_hi v73, v0 offset:7040
	v_mul_f32_e32 v0, v33, v72
	v_bfe_u32 v2, v0, 16, 1
	v_add3_u32 v0, v0, v2, s33
	ds_write_b16_d16_hi v73, v0 offset:7104
	v_lshlrev_b32_e32 v0, 1, v161
	s_add_u32 s0, s2, s0
	v_and_b32_e32 v0, 0xf0, v0
	s_addc_u32 s1, s3, s1
	v_lshrrev_b32_e32 v14, 4, v163
	v_add_u32_e32 v15, s4, v0
	s_waitcnt lgkmcnt(0)
	v_lshl_add_u64 v[10:11], s[0:1], 0, v[0:1]
	v_lshl_add_u32 v0, v14, 8, v15
	v_or_b32_e32 v16, 4, v14
	ds_read_b128 v[2:5], v0
	v_lshl_add_u32 v6, v16, 8, v15
	ds_read_b128 v[6:9], v6
	v_lshlrev_b32_e32 v0, 11, v14
	v_lshl_add_u64 v[12:13], v[10:11], 0, v[0:1]
	v_lshlrev_b32_e32 v0, 11, v16
	s_waitcnt lgkmcnt(0)
	global_store_dwordx4 v[12:13], v[2:5], off
	v_or_b32_e32 v16, 12, v14
	v_readlane_b32 s0, v252, 1
	v_lshl_add_u64 v[2:3], v[10:11], 0, v[0:1]
	v_or_b32_e32 v0, 8, v14
	global_store_dwordx4 v[2:3], v[6:9], off
	v_lshl_add_u32 v2, v0, 8, v15
	ds_read_b128 v[2:5], v2
	v_lshl_add_u32 v6, v16, 8, v15
	ds_read_b128 v[6:9], v6
	v_lshlrev_b32_e32 v0, 11, v0
	v_lshl_add_u64 v[12:13], v[10:11], 0, v[0:1]
	v_lshlrev_b32_e32 v0, 11, v16
	s_waitcnt lgkmcnt(0)
	global_store_dwordx4 v[12:13], v[2:5], off
	v_or_b32_e32 v16, 20, v14
	s_add_i32 s58, s58, s0
	v_lshl_add_u64 v[2:3], v[10:11], 0, v[0:1]
	v_or_b32_e32 v0, 16, v14
	global_store_dwordx4 v[2:3], v[6:9], off
	v_lshl_add_u32 v2, v0, 8, v15
	ds_read_b128 v[2:5], v2
	v_lshl_add_u32 v6, v16, 8, v15
	ds_read_b128 v[6:9], v6
	v_lshlrev_b32_e32 v0, 11, v0
	v_lshl_add_u64 v[12:13], v[10:11], 0, v[0:1]
	v_lshlrev_b32_e32 v0, 11, v16
	s_waitcnt lgkmcnt(0)
	global_store_dwordx4 v[12:13], v[2:5], off
	s_add_i32 s57, s57, s0
	s_cmpk_gt_i32 s58, 0xff
	v_lshl_add_u64 v[2:3], v[10:11], 0, v[0:1]
	v_or_b32_e32 v0, 24, v14
	global_store_dwordx4 v[2:3], v[6:9], off
	v_lshl_add_u32 v2, v0, 8, v15
	v_or_b32_e32 v14, 28, v14
	ds_read_b128 v[2:5], v2
	v_lshl_add_u32 v6, v14, 8, v15
	ds_read_b128 v[6:9], v6
	v_lshlrev_b32_e32 v0, 11, v0
	v_lshl_add_u64 v[12:13], v[10:11], 0, v[0:1]
	v_lshlrev_b32_e32 v0, 11, v14
	s_waitcnt lgkmcnt(0)
	global_store_dwordx4 v[12:13], v[2:5], off
	v_readlane_b32 s1, v252, 2
	s_nop 0
	v_lshl_add_u64 v[2:3], v[10:11], 0, v[0:1]
	global_store_dwordx4 v[2:3], v[6:9], off
	s_waitcnt vmcnt(0) lgkmcnt(0)
	s_barrier
	s_cbranch_scc1 .LBB2_355
.LBB2_332:
	s_and_b32 s11, s57, 7
	s_ashr_i32 s6, s58, 3
	s_lshl_b32 s0, s11, 8
	s_and_b32 s1, s58, 7
	s_ashr_i32 s7, s6, 31
	s_mul_i32 s3, s6, 0xc0000
	s_mul_hi_i32 s2, s6, 0xc0000
	s_add_u32 s3, s8, s3
	s_addc_u32 s4, s9, s2
	s_mul_i32 s5, s1, 0x180
	s_add_u32 s2, s3, s5
	s_addc_u32 s3, s4, 0
	s_add_u32 s14, s16, s5
	s_addc_u32 s15, s30, 0
	s_lshl_b32 s5, s1, 7
	s_lshl_b32 s1, s1, 8
	v_mov_b32_e32 v58, v146
	s_add_u32 s18, s31, s1
	s_addc_u32 s19, s38, 0
	v_readfirstlane_b32 s1, v58
	s_ashr_i32 s59, s1, 6
	v_and_b32_e32 v191, 31, v58
	s_lshl_b32 s4, s59, 5
	v_bfe_u32 v192, v58, 5, 1
	v_or_b32_e32 v0, s4, v191
	s_waitcnt lgkmcnt(0)
	v_mov_b64_e32 v[2:3], s[2:3]
	s_movk_i32 s20, 0xc00
	v_mad_i64_i32 v[2:3], s[2:3], v0, s20, v[2:3]
	v_lshlrev_b32_e32 v162, 4, v192
	v_mov_b32_e32 v163, v1
	v_lshl_add_u64 v[2:3], v[2:3], 0, v[162:163]
	s_ashr_i32 s3, s1, 4
	s_waitcnt vmcnt(0)
	v_lshrrev_b32_e32 v8, 1, v58
	global_load_dwordx4 v[142:145], v[2:3], off
	global_load_dwordx4 v[138:141], v[2:3], off offset:32
	global_load_dwordx4 v[134:137], v[2:3], off offset:64
	global_load_dwordx4 v[130:133], v[2:3], off offset:96
	global_load_dwordx4 v[126:129], v[2:3], off offset:128
	global_load_dwordx4 v[122:125], v[2:3], off offset:160
	global_load_dwordx4 v[118:121], v[2:3], off offset:192
	global_load_dwordx4 v[114:117], v[2:3], off offset:224
	global_load_dwordx4 v[110:113], v[2:3], off offset:256
	global_load_dwordx4 v[106:109], v[2:3], off offset:288
	global_load_dwordx4 v[102:105], v[2:3], off offset:320
	global_load_dwordx4 v[98:101], v[2:3], off offset:352
	v_and_b32_e32 v2, 8, v8
	s_lshr_b32 s2, s3, 1
	v_bfe_u32 v61, v58, 2, 2
	s_and_b32 s2, s2, 4
	v_and_or_b32 v62, s3, -16, v2
	v_bfe_u32 v0, v58, 3, 3
	v_or3_b32 v2, v62, v61, s2
	v_lshlrev_b32_e32 v161, 3, v58
	v_lshl_or_b32 v59, s59, 3, v0
	s_lshl_b32 s3, s59, 1
	v_and_b32_e32 v63, 24, v161
	v_ashrrev_i32_e32 v3, 31, v2
	v_lshrrev_b32_e32 v60, 1, v59
	v_and_or_b32 v4, s3, 2, v192
	v_lshlrev_b64 v[2:3], 11, v[2:3]
	v_lshlrev_b32_e32 v5, 1, v63
	v_xor_b32_e32 v0, v60, v58
	v_lshl_add_u64 v[2:3], s[18:19], 0, v[2:3]
	v_lshl_or_b32 v4, v4, 6, v5
	v_mov_b32_e32 v5, v1
	v_lshl_add_u64 v[2:3], v[2:3], 0, v[4:5]
	v_mov_b64_e32 v[4:5], s[14:15]
	v_lshlrev_b32_e32 v0, 4, v0
	s_lshl_b32 s3, s59, 10
	v_mad_i64_i32 v[4:5], s[14:15], v59, s20, v[4:5]
	v_and_b32_e32 v6, 0x70, v0
	v_mov_b32_e32 v7, v1
	s_add_i32 s61, s3, 0
	v_lshl_add_u64 v[4:5], v[4:5], 0, v[6:7]
	s_mov_b32 m0, s61
	v_lshl_add_u64 v[6:7], v[4:5], 0, s[34:35]
	global_load_lds_dwordx4 v[4:5], off
	s_add_i32 m0, s61, 0x2000
	s_mov_b64 s[14:15], 0x100
	global_load_lds_dwordx4 v[6:7], off
	v_lshl_add_u64 v[6:7], v[4:5], 0, s[14:15]
	s_add_i32 m0, s61, 0x4000
	s_mov_b64 s[24:25], 0x30000
	global_load_lds_dwordx4 v[6:7], off
	v_lshl_add_u64 v[6:7], v[4:5], 0, s[24:25]
	s_add_i32 m0, s61, 0x6000
	s_mov_b64 s[14:15], 0x30080
	global_load_lds_dwordx4 v[6:7], off
	v_lshl_add_u64 v[6:7], v[4:5], 0, s[14:15]
	s_add_i32 m0, s61, 0x8000
	s_mov_b64 s[14:15], 0x30100
	s_add_i32 s18, 0, 0x18000
	global_load_lds_dwordx4 v[6:7], off
	v_lshl_add_u64 v[6:7], v[4:5], 0, s[14:15]
	s_add_i32 m0, s61, 0xa000
	s_add_i32 s62, s18, s3
	global_load_lds_dwordx4 v[6:7], off
	s_mov_b32 m0, s62
	s_mov_b64 s[14:15], 0x10000
	global_load_lds_dwordx4 v[2:3], off
	v_lshl_add_u64 v[6:7], v[2:3], 0, s[14:15]
	s_add_i32 m0, s61, 0x1a000
	s_mov_b64 s[14:15], 0x60000
	global_load_lds_dwordx4 v[6:7], off
	s_waitcnt vmcnt(0) lgkmcnt(0)
	s_barrier
	v_lshl_add_u64 v[6:7], v[4:5], 0, s[14:15]
	s_add_i32 m0, s61, 0xc000
	s_mov_b64 s[14:15], 0x60080
	global_load_lds_dwordx4 v[6:7], off
	v_lshl_add_u64 v[6:7], v[4:5], 0, s[14:15]
	s_add_i32 m0, s61, 0xe000
	s_mov_b64 s[14:15], 0x60100
	global_load_lds_dwordx4 v[6:7], off
	v_lshl_add_u64 v[4:5], v[4:5], 0, s[14:15]
	s_add_i32 m0, s61, 0x10000
	s_mov_b64 s[14:15], 0x20000
	global_load_lds_dwordx4 v[4:5], off
	v_lshl_add_u64 v[4:5], v[2:3], 0, s[14:15]
	s_add_i32 m0, s61, 0x1c000
	v_lshl_add_u64 v[2:3], v[2:3], 0, s[24:25]
	global_load_lds_dwordx4 v[4:5], off
	s_add_i32 m0, s61, 0x1e000
	v_and_b32_e32 v163, 63, v58
	global_load_lds_dwordx4 v[2:3], off
	v_bitop3_b32 v2, v192, v8, 1 bitop3:0x78
	v_lshlrev_b32_e32 v3, 7, v191
	v_lshl_or_b32 v2, v2, 4, v3
	v_and_b32_e32 v3, 0x60, v161
	v_or_b32_e32 v197, v2, v3
	v_bitop3_b32 v198, v2, 32, v3 bitop3:0x36
	v_bitop3_b32 v199, v2, 64, v3 bitop3:0x36
	v_lshlrev_b32_e32 v3, 4, v58
	v_bitop3_b32 v200, v2, s75, v161 bitop3:0x34
	v_lshlrev_b32_e32 v2, 3, v163
	v_and_b32_e32 v3, 0xc0, v3
	v_lshlrev_b32_e32 v4, 1, v58
	s_and_b32 s3, s1, 0x3fffffc0
	v_and_or_b32 v3, v2, 24, v3
	v_and_b32_e32 v4, 32, v4
	v_and_b32_e32 v2, 0x100, v2
	s_lshl_b32 s3, s3, 2
	v_or3_b32 v193, v3, v4, v2
	v_add_u32_e32 v64, 0, v197
	v_add_u32_e32 v65, 0, v198
	v_add_u32_e32 v66, 0, v199
	ds_read_b128 v[2:5], v64 offset:0
	ds_read_b128 v[6:9], v64 offset:0x1000
	ds_read_b128 v[10:13], v65 offset:0
	ds_read_b128 v[14:17], v65 offset:0x1000
	ds_read_b128 v[50:53], v66 offset:0
	ds_read_b128 v[54:57], v66 offset:0x1000
	s_add_i32 s60, s3, 0
	s_mulk_i32 s11, 0x180
	s_mov_b32 s63, 3
	s_mov_b32 s24, 2
	s_add_i32 s60, s60, 0x24000
	s_mov_b32 s64, 1
	v_add_u32_e32 v196, s18, v193
	v_mov_b32_e32 v0, s11
	v_add_u32_e32 v67, 0, v200
	s_setprio 1
	s_waitcnt lgkmcnt(4)
	s_mov_b32 s40, 0
	s_waitcnt vmcnt(0) lgkmcnt(0)
	v_mfma_f32_32x32x16_bf16 v[34:49], v[2:5], v[142:145], 0
	ds_read_b128 v[2:5], v67 offset:0
	s_mov_b32 s41, s40
	s_mov_b32 s42, s40
	s_mov_b32 s43, s40
	s_mov_b32 s44, s40
	s_mov_b32 s45, s40
	s_mov_b32 s46, s40
	v_mfma_f32_32x32x16_bf16 v[18:33], v[6:9], v[142:145], 0
	ds_read_b128 v[6:9], v67 offset:0x1000
	s_waitcnt lgkmcnt(4)
	s_mov_b32 s47, s40
	s_mov_b32 s48, s40
	s_mov_b32 s49, s40
	s_mov_b32 s50, s40
	s_mov_b32 s51, s40
	v_mfma_f32_32x32x16_bf16 v[34:49], v[10:13], v[138:141], v[34:49]
	ds_read_b128 v[10:13], v64 offset:0x2000
	s_mov_b32 s52, s40
	s_mov_b32 s53, s40
	s_mov_b32 s54, s40
	s_mov_b32 s55, s40
	v_mfma_f32_32x32x16_bf16 v[18:33], v[14:17], v[138:141], v[18:33]
	ds_read_b128 v[14:17], v64 offset:0x3000
	s_waitcnt lgkmcnt(4)
	s_nop 0
	v_mfma_f32_32x32x16_bf16 v[34:49], v[50:53], v[134:137], v[34:49]
	ds_read_b128 v[50:53], v65 offset:0x2000
	v_mfma_f32_32x32x16_bf16 v[18:33], v[54:57], v[134:137], v[18:33]
	ds_read_b128 v[54:57], v65 offset:0x3000
	s_waitcnt lgkmcnt(4)
	s_nop 0
	v_mfma_f32_32x32x16_bf16 v[34:49], v[2:5], v[130:133], v[34:49]
	ds_read_b128 v[2:5], v66 offset:0x2000
	v_mfma_f32_32x32x16_bf16 v[18:33], v[6:9], v[130:133], v[18:33]
	ds_read_b128 v[6:9], v66 offset:0x3000
	s_waitcnt lgkmcnt(4)
	s_nop 0
	v_mfma_f32_32x32x16_bf16 v[34:49], v[10:13], v[126:129], v[34:49]
	ds_read_b128 v[10:13], v67 offset:0x2000
	v_mfma_f32_32x32x16_bf16 v[18:33], v[14:17], v[126:129], v[18:33]
	ds_read_b128 v[14:17], v67 offset:0x3000
	s_waitcnt lgkmcnt(4)
	s_nop 0
	v_mfma_f32_32x32x16_bf16 v[34:49], v[50:53], v[122:125], v[34:49]
	ds_read_b128 v[50:53], v64 offset:0x4000
	v_mfma_f32_32x32x16_bf16 v[18:33], v[54:57], v[122:125], v[18:33]
	ds_read_b128 v[54:57], v64 offset:0x5000
	s_waitcnt lgkmcnt(4)
	s_nop 0
	v_mfma_f32_32x32x16_bf16 v[34:49], v[2:5], v[118:121], v[34:49]
	ds_read_b128 v[2:5], v65 offset:0x4000
	v_mfma_f32_32x32x16_bf16 v[18:33], v[6:9], v[118:121], v[18:33]
	ds_read_b128 v[6:9], v65 offset:0x5000
	s_waitcnt lgkmcnt(4)
	s_nop 0
	v_mfma_f32_32x32x16_bf16 v[34:49], v[10:13], v[114:117], v[34:49]
	ds_read_b128 v[10:13], v66 offset:0x4000
	v_mfma_f32_32x32x16_bf16 v[18:33], v[14:17], v[114:117], v[18:33]
	ds_read_b128 v[14:17], v66 offset:0x5000
	s_waitcnt lgkmcnt(4)
	s_nop 0
	v_mfma_f32_32x32x16_bf16 v[34:49], v[50:53], v[110:113], v[34:49]
	ds_read_b128 v[50:53], v67 offset:0x4000
	v_mfma_f32_32x32x16_bf16 v[18:33], v[54:57], v[110:113], v[18:33]
	ds_read_b128 v[54:57], v67 offset:0x5000
	s_waitcnt lgkmcnt(4)
	s_waitcnt lgkmcnt(2)
	s_nop 0
	s_waitcnt lgkmcnt(0)
	v_mfma_f32_32x32x16_bf16 v[34:49], v[2:5], v[106:109], v[34:49]
	v_mfma_f32_32x32x16_bf16 v[18:33], v[6:9], v[106:109], v[18:33]
	v_mfma_f32_32x32x16_bf16 v[34:49], v[10:13], v[102:105], v[34:49]
	v_mfma_f32_32x32x16_bf16 v[18:33], v[14:17], v[102:105], v[18:33]
	v_mov_b64_e32 v[2:3], s[40:41]
	v_mov_b64_e32 v[4:5], s[42:43]
	v_mov_b64_e32 v[6:7], s[44:45]
	v_mov_b64_e32 v[8:9], s[46:47]
	v_mov_b64_e32 v[10:11], s[48:49]
	v_mov_b64_e32 v[12:13], s[50:51]
	v_mov_b64_e32 v[14:15], s[52:53]
	v_mfma_f32_32x32x16_bf16 v[34:49], v[50:53], v[98:101], v[34:49]
	v_mov_b64_e32 v[16:17], s[54:55]
	v_mfma_f32_32x32x16_bf16 v[18:33], v[54:57], v[98:101], v[18:33]
	s_setprio 0
	s_nop 8
	v_max_f32_e32 v50, v35, v35
	v_max_f32_e32 v51, v34, v34
	v_max_f32_e32 v50, v51, v50
	v_max3_f32 v50, v50, v36, v37
	v_max3_f32 v50, v50, v38, v39
	v_max3_f32 v50, v50, v40, v41
	v_max3_f32 v50, v50, v42, v43
	v_max3_f32 v50, v50, v44, v45
	v_max3_f32 v50, v50, v46, v47
	v_max3_f32 v50, v50, v48, v49
	v_max3_f32 v50, v50, v18, v19
	v_max3_f32 v50, v50, v20, v21
	v_max3_f32 v50, v50, v22, v23
	v_max3_f32 v50, v50, v24, v25
	v_max3_f32 v50, v50, v26, v27
	v_max3_f32 v50, v50, v28, v29
	v_max3_f32 v50, v50, v30, v31
	v_max3_f32 v50, v50, v32, v33
	v_mov_b32_e32 v51, v50
	s_nop 1
	v_permlane32_swap_b32_e32 v50, v51
	v_max_f32_e32 v51, v51, v51
	v_max_f32_e32 v50, v50, v50
	v_max_f32_e32 v50, v50, v51
	v_add_f32_e32 v51, 0x7149f2ca, v50
	v_max_f32_e32 v50, 0xf149f2ca, v50
	v_cmp_ge_f32_e32 vcc, s27, v51
	v_sub_f32_e32 v51, 0xf149f2ca, v50
	v_mul_f32_e32 v51, 0x3dd53b94, v51
	v_exp_f32_e32 v51, v51
	s_cmp_eq_u64 vcc, exec
	s_cselect_b64 vcc, -1, 0
	v_mov_b32_e32 v52, 0xf149f2ca
	v_cndmask_b32_e32 v202, v50, v52, vcc
	v_mul_f32_e32 v50, 0xbdd53b94, v202
	v_cndmask_b32_e64 v201, v51, 1.0, vcc
	v_mov_b32_e32 v51, v50
	v_fmamk_f32 v34, v34, 0x3dd53b94, v50
	v_fmamk_f32 v35, v35, 0x3dd53b94, v50
	v_fmamk_f32 v36, v36, 0x3dd53b94, v50
	v_fmamk_f32 v37, v37, 0x3dd53b94, v50
	v_fmamk_f32 v38, v38, 0x3dd53b94, v50
	v_fmamk_f32 v39, v39, 0x3dd53b94, v50
	v_fmamk_f32 v40, v40, 0x3dd53b94, v50
	v_fmamk_f32 v41, v41, 0x3dd53b94, v50
	v_fmamk_f32 v42, v42, 0x3dd53b94, v50
	v_fmamk_f32 v43, v43, 0x3dd53b94, v50
	v_fmamk_f32 v44, v44, 0x3dd53b94, v50
	v_fmamk_f32 v45, v45, 0x3dd53b94, v50
	v_fmamk_f32 v46, v46, 0x3dd53b94, v50
	v_fmamk_f32 v47, v47, 0x3dd53b94, v50
	v_fmamk_f32 v48, v48, 0x3dd53b94, v50
	v_fmac_f32_e32 v51, 0x3dd53b94, v49
	v_mad_i64_i32 v[164:165], s[14:15], v59, s20, v[0:1]
	v_bitop3_b32 v0, v60, 7, v58 bitop3:0x48
	v_pk_fma_f32 v[186:187], v[18:19], s[26:27], v[50:51] op_sel_hi:[1,0,0]
	v_exp_f32_e32 v216, v34
	v_exp_f32_e32 v218, v35
	v_exp_f32_e32 v214, v36
	v_exp_f32_e32 v217, v37
	v_exp_f32_e32 v212, v38
	v_exp_f32_e32 v215, v39
	v_exp_f32_e32 v211, v40
	v_exp_f32_e32 v213, v41
	v_exp_f32_e32 v208, v42
	v_exp_f32_e32 v210, v43
	v_exp_f32_e32 v206, v44
	v_exp_f32_e32 v209, v45
	v_exp_f32_e32 v204, v46
	v_exp_f32_e32 v207, v47
	v_exp_f32_e32 v203, v48
	v_exp_f32_e32 v205, v51
	v_lshl_or_b32 v164, v0, 4, v164
	v_or3_b32 v18, v62, s2, v61
	s_and_b32 s1, s1, 64
	v_and_b32_e32 v0, 32, v58
	v_ashrrev_i32_e32 v19, 31, v18
	v_or3_b32 v0, s1, v0, v63
	v_pk_fma_f32 v[172:173], v[32:33], s[26:27], v[50:51] op_sel_hi:[1,0,0]
	v_pk_fma_f32 v[174:175], v[30:31], s[26:27], v[50:51] op_sel_hi:[1,0,0]
	v_pk_fma_f32 v[176:177], v[28:29], s[26:27], v[50:51] op_sel_hi:[1,0,0]
	v_pk_fma_f32 v[178:179], v[26:27], s[26:27], v[50:51] op_sel_hi:[1,0,0]
	v_pk_fma_f32 v[180:181], v[24:25], s[26:27], v[50:51] op_sel_hi:[1,0,0]
	v_pk_fma_f32 v[182:183], v[22:23], s[26:27], v[50:51] op_sel_hi:[1,0,0]
	v_pk_fma_f32 v[184:185], v[20:21], s[26:27], v[50:51] op_sel_hi:[1,0,0]
	v_readlane_b32 s20, v254, 38
	v_lshlrev_b64 v[166:167], 11, v[18:19]
	v_lshlrev_b32_e32 v0, 1, v0
	v_mov_b64_e32 v[64:65], v[16:17]
	v_mov_b64_e32 v[48:49], v[16:17]
	v_mov_b64_e32 v[32:33], v[16:17]
	v_cmp_gt_u32_e64 s[36:37], 32, v163
	v_lshl_add_u32 v194, v191, 2, s60
	v_readlane_b32 s21, v254, 39
	v_or3_b32 v166, v166, s0, v0
	v_mov_b32_e32 v195, 0
	v_mov_b64_e32 v[62:63], v[14:15]
	v_mov_b64_e32 v[60:61], v[12:13]
	v_mov_b64_e32 v[58:59], v[10:11]
	v_mov_b64_e32 v[56:57], v[8:9]
	v_mov_b64_e32 v[54:55], v[6:7]
	v_mov_b64_e32 v[52:53], v[4:5]
	v_mov_b64_e32 v[50:51], v[2:3]
	v_mov_b64_e32 v[46:47], v[14:15]
	v_mov_b64_e32 v[44:45], v[12:13]
	v_mov_b64_e32 v[42:43], v[10:11]
	v_mov_b64_e32 v[40:41], v[8:9]
	v_mov_b64_e32 v[38:39], v[6:7]
	v_mov_b64_e32 v[36:37], v[4:5]
	v_mov_b64_e32 v[34:35], v[2:3]
	v_mov_b64_e32 v[30:31], v[14:15]
	v_mov_b64_e32 v[28:29], v[12:13]
	v_mov_b64_e32 v[26:27], v[10:11]
	v_mov_b64_e32 v[24:25], v[8:9]
	v_mov_b64_e32 v[22:23], v[6:7]
	v_mov_b64_e32 v[20:21], v[4:5]
	v_mov_b64_e32 v[18:19], v[2:3]
	s_mov_b32 s11, 1

.LBB2_356:
	s_or_b64 exec, exec, s[2:3]
	s_waitcnt lgkmcnt(0)
	ds_read_b128 v[66:69], v200
	ds_read_b128 v[70:73], v200 offset:32
	v_lshl_add_u32 v83, v178, 13, 0
	v_lshlrev_b32_e32 v84, 10, v180
	v_lshlrev_b32_e32 v85, 1, v179
	s_waitcnt lgkmcnt(0)
	v_rcp_f32_e32 v0, v66
	v_rcp_f32_e32 v74, v67
	v_add3_u32 v84, v83, v84, v85
	v_rcp_f32_e32 v75, v68
	v_mul_f32_e32 v50, v50, v0
	v_mul_f32_e32 v34, v34, v0
	v_mul_f32_e32 v18, v18, v0
	v_mul_f32_e32 v0, v2, v0
	v_bfe_u32 v2, v0, 16, 1
	v_add3_u32 v0, v0, v2, s33
	ds_write_b16_d16_hi v84, v0 offset:192
	v_mul_f32_e32 v0, v51, v74
	v_bfe_u32 v2, v0, 16, 1
	v_add3_u32 v0, v0, v2, s33
	ds_write_b16_d16_hi v84, v0 offset:256
	v_mul_f32_e32 v0, v35, v74
	v_bfe_u32 v2, v0, 16, 1
	v_add3_u32 v0, v0, v2, s33
	ds_write_b16_d16_hi v84, v0 offset:320
	v_mul_f32_e32 v0, v19, v74
	v_bfe_u32 v2, v0, 16, 1
	v_add3_u32 v0, v0, v2, s33
	ds_write_b16_d16_hi v84, v0 offset:384
	v_mul_f32_e32 v0, v3, v74
	v_bfe_u32 v2, v0, 16, 1
	v_add3_u32 v0, v0, v2, s33
	ds_write_b16_d16_hi v84, v0 offset:448
	v_mul_f32_e32 v0, v52, v75
	v_bfe_u32 v2, v0, 16, 1
	v_add3_u32 v0, v0, v2, s33
	ds_write_b16_d16_hi v84, v0 offset:512
	v_mul_f32_e32 v0, v36, v75
	v_bfe_u32 v2, v0, 16, 1
	v_add3_u32 v0, v0, v2, s33
	ds_write_b16_d16_hi v84, v0 offset:576
	v_mul_f32_e32 v0, v20, v75
	v_bfe_u32 v2, v0, 16, 1
	v_rcp_f32_e32 v76, v69
	v_add3_u32 v0, v0, v2, s33
	ds_write_b16_d16_hi v84, v0 offset:640
	v_mul_f32_e32 v0, v4, v75
	v_bfe_u32 v2, v0, 16, 1
	v_add3_u32 v0, v0, v2, s33
	ds_write_b16_d16_hi v84, v0 offset:704
	v_mul_f32_e32 v0, v53, v76
	v_bfe_u32 v2, v0, 16, 1
	v_add3_u32 v0, v0, v2, s33
	ds_write_b16_d16_hi v84, v0 offset:768
	v_mul_f32_e32 v0, v37, v76
	v_bfe_u32 v2, v0, 16, 1
	v_add3_u32 v0, v0, v2, s33
	ds_write_b16_d16_hi v84, v0 offset:832
	v_mul_f32_e32 v0, v21, v76
	v_bfe_u32 v2, v0, 16, 1
	v_rcp_f32_e32 v77, v70
	v_add3_u32 v0, v0, v2, s33
	ds_write_b16_d16_hi v84, v0 offset:896
	v_mul_f32_e32 v0, v5, v76
	v_bfe_u32 v2, v0, 16, 1
	v_add3_u32 v0, v0, v2, s33
	ds_write_b16_d16_hi v84, v0 offset:960
	v_mul_f32_e32 v0, v54, v77
	v_bfe_u32 v2, v0, 16, 1
	v_add3_u32 v0, v0, v2, s33
	ds_write_b16_d16_hi v84, v0 offset:2048
	v_mul_f32_e32 v0, v38, v77
	v_bfe_u32 v2, v0, 16, 1
	v_add3_u32 v0, v0, v2, s33
	ds_write_b16_d16_hi v84, v0 offset:2112
	v_mul_f32_e32 v0, v22, v77
	v_bfe_u32 v2, v0, 16, 1
	v_rcp_f32_e32 v78, v71
	v_add3_u32 v0, v0, v2, s33
	ds_write_b16_d16_hi v84, v0 offset:2176
	v_mul_f32_e32 v0, v6, v77
	v_bfe_u32 v2, v0, 16, 1
	v_add3_u32 v0, v0, v2, s33
	ds_write_b16_d16_hi v84, v0 offset:2240
	v_mul_f32_e32 v0, v55, v78
	v_bfe_u32 v2, v0, 16, 1
	v_add3_u32 v0, v0, v2, s33
	ds_write_b16_d16_hi v84, v0 offset:2304
	v_mul_f32_e32 v0, v39, v78
	v_bfe_u32 v2, v0, 16, 1
	v_add3_u32 v0, v0, v2, s33
	ds_write_b16_d16_hi v84, v0 offset:2368
	v_mul_f32_e32 v0, v23, v78
	v_bfe_u32 v2, v0, 16, 1
	v_rcp_f32_e32 v79, v72
	v_add3_u32 v0, v0, v2, s33
	ds_write_b16_d16_hi v84, v0 offset:2432
	v_mul_f32_e32 v0, v7, v78
	v_bfe_u32 v2, v0, 16, 1
	v_add3_u32 v0, v0, v2, s33
	ds_write_b16_d16_hi v84, v0 offset:2496
	v_mul_f32_e32 v0, v56, v79
	v_bfe_u32 v2, v0, 16, 1
	v_add3_u32 v0, v0, v2, s33
	ds_write_b16_d16_hi v84, v0 offset:2560
	v_mul_f32_e32 v0, v40, v79
	v_bfe_u32 v2, v0, 16, 1
	v_add3_u32 v0, v0, v2, s33
	ds_write_b16_d16_hi v84, v0 offset:2624
	v_mul_f32_e32 v0, v24, v79
	v_bfe_u32 v2, v0, 16, 1
	v_rcp_f32_e32 v80, v73
	v_add3_u32 v0, v0, v2, s33
	ds_write_b16_d16_hi v84, v0 offset:2688
	v_mul_f32_e32 v0, v8, v79
	v_bfe_u32 v2, v0, 16, 1
	v_add3_u32 v0, v0, v2, s33
	ds_write_b16_d16_hi v84, v0 offset:2752
	v_mul_f32_e32 v0, v57, v80
	v_bfe_u32 v2, v0, 16, 1
	v_add3_u32 v0, v0, v2, s33
	ds_read_b128 v[66:69], v200 offset:64
	ds_read_b128 v[70:73], v200 offset:96
	ds_write_b16_d16_hi v84, v0 offset:2816
	v_mul_f32_e32 v0, v41, v80
	v_bfe_u32 v2, v0, 16, 1
	v_add3_u32 v0, v0, v2, s33
	ds_write_b16_d16_hi v84, v0 offset:2880
	v_mul_f32_e32 v0, v25, v80
	v_bfe_u32 v2, v0, 16, 1
	s_waitcnt lgkmcnt(0)
	v_rcp_f32_e32 v81, v66
	v_add3_u32 v0, v0, v2, s33
	ds_write_b16_d16_hi v84, v0 offset:2944
	v_mul_f32_e32 v0, v9, v80
	v_bfe_u32 v2, v0, 16, 1
	v_add3_u32 v0, v0, v2, s33
	ds_write_b16_d16_hi v84, v0 offset:3008
	v_mul_f32_e32 v0, v58, v81
	v_bfe_u32 v2, v0, 16, 1
	v_add3_u32 v0, v0, v2, s33
	ds_write_b16_d16_hi v84, v0 offset:4096
	v_mul_f32_e32 v0, v42, v81
	v_bfe_u32 v2, v0, 16, 1
	v_add3_u32 v0, v0, v2, s33
	ds_write_b16_d16_hi v84, v0 offset:4160
	v_mul_f32_e32 v0, v26, v81
	v_bfe_u32 v2, v0, 16, 1
	v_rcp_f32_e32 v82, v67
	v_add3_u32 v0, v0, v2, s33
	ds_write_b16_d16_hi v84, v0 offset:4224
	v_mul_f32_e32 v0, v10, v81
	v_bfe_u32 v2, v0, 16, 1
	v_add3_u32 v0, v0, v2, s33
	ds_write_b16_d16_hi v84, v0 offset:4288
	v_mul_f32_e32 v0, v59, v82
	v_bfe_u32 v2, v0, 16, 1
	v_add3_u32 v0, v0, v2, s33
	ds_write_b16_d16_hi v84, v0 offset:4352
	v_mul_f32_e32 v0, v43, v82
	v_bfe_u32 v2, v0, 16, 1
	v_add3_u32 v0, v0, v2, s33
	ds_write_b16_d16_hi v84, v0 offset:4416
	v_mul_f32_e32 v0, v27, v82
	v_bfe_u32 v2, v0, 16, 1
	v_rcp_f32_e32 v68, v68
	v_add3_u32 v0, v0, v2, s33
	ds_write_b16_d16_hi v84, v0 offset:4480
	v_mul_f32_e32 v0, v11, v82
	v_bfe_u32 v2, v0, 16, 1
	v_add3_u32 v0, v0, v2, s33
	ds_write_b16_d16_hi v84, v0 offset:4544
	v_mul_f32_e32 v0, v60, v68
	v_bfe_u32 v2, v0, 16, 1
	v_add3_u32 v0, v0, v2, s33
	ds_write_b16_d16_hi v84, v0 offset:4608
	v_mul_f32_e32 v0, v44, v68
	v_bfe_u32 v2, v0, 16, 1
	v_add3_u32 v0, v0, v2, s33
	ds_write_b16_d16_hi v84, v0 offset:4672
	v_mul_f32_e32 v0, v28, v68
	v_bfe_u32 v2, v0, 16, 1
	v_rcp_f32_e32 v69, v69
	v_add3_u32 v0, v0, v2, s33
	ds_write_b16_d16_hi v84, v0 offset:4736
	v_mul_f32_e32 v0, v12, v68
	v_bfe_u32 v2, v0, 16, 1
	v_add3_u32 v0, v0, v2, s33
	ds_write_b16_d16_hi v84, v0 offset:4800
	v_mul_f32_e32 v0, v61, v69
	v_bfe_u32 v2, v0, 16, 1
	v_add3_u32 v0, v0, v2, s33
	ds_write_b16_d16_hi v84, v0 offset:4864
	v_mul_f32_e32 v0, v45, v69
	v_bfe_u32 v2, v0, 16, 1
	v_add3_u32 v0, v0, v2, s33
	ds_write_b16_d16_hi v84, v0 offset:4928
	v_mul_f32_e32 v0, v29, v69
	v_bfe_u32 v2, v0, 16, 1
	v_rcp_f32_e32 v70, v70
	v_add3_u32 v0, v0, v2, s33
	ds_write_b16_d16_hi v84, v0 offset:4992
	v_mul_f32_e32 v0, v13, v69
	v_bfe_u32 v2, v0, 16, 1
	v_add3_u32 v0, v0, v2, s33
	ds_write_b16_d16_hi v84, v0 offset:5056
	v_mul_f32_e32 v0, v62, v70
	v_bfe_u32 v2, v0, 16, 1
	v_add3_u32 v0, v0, v2, s33
	ds_write_b16_d16_hi v84, v0 offset:6144
	v_mul_f32_e32 v0, v46, v70
	v_bfe_u32 v2, v0, 16, 1
	v_add3_u32 v0, v0, v2, s33
	ds_write_b16_d16_hi v84, v0 offset:6208
	v_mul_f32_e32 v0, v30, v70
	v_bfe_u32 v2, v0, 16, 1
	v_rcp_f32_e32 v71, v71
	v_add3_u32 v0, v0, v2, s33
	ds_write_b16_d16_hi v84, v0 offset:6272
	v_mul_f32_e32 v0, v14, v70
	v_bfe_u32 v2, v0, 16, 1
	v_add3_u32 v0, v0, v2, s33
	ds_write_b16_d16_hi v84, v0 offset:6336
	v_mul_f32_e32 v0, v63, v71
	v_bfe_u32 v2, v0, 16, 1
	v_add3_u32 v0, v0, v2, s33
	ds_write_b16_d16_hi v84, v0 offset:6400
	v_mul_f32_e32 v0, v47, v71
	v_bfe_u32 v2, v0, 16, 1
	v_add3_u32 v0, v0, v2, s33
	ds_write_b16_d16_hi v84, v0 offset:6464
	v_mul_f32_e32 v0, v31, v71
	v_bfe_u32 v2, v0, 16, 1
	v_rcp_f32_e32 v72, v72
	v_add3_u32 v0, v0, v2, s33
	ds_write_b16_d16_hi v84, v0 offset:6528
	v_mul_f32_e32 v0, v15, v71
	v_bfe_u32 v2, v0, 16, 1
	v_add3_u32 v0, v0, v2, s33
	ds_write_b16_d16_hi v84, v0 offset:6592
	v_mul_f32_e32 v0, v64, v72
	v_bfe_u32 v2, v0, 16, 1
	v_add3_u32 v0, v0, v2, s33
	ds_write_b16_d16_hi v84, v0 offset:6656
	v_mul_f32_e32 v0, v48, v72
	v_bfe_u32 v2, v0, 16, 1
	v_add3_u32 v0, v0, v2, s33
	ds_write_b16_d16_hi v84, v0 offset:6720
	v_mul_f32_e32 v0, v32, v72
	v_bfe_u32 v2, v0, 16, 1
	v_rcp_f32_e32 v73, v73
	v_add3_u32 v0, v0, v2, s33
	ds_write_b16_d16_hi v84, v0 offset:6784
	v_mul_f32_e32 v0, v16, v72
	v_bfe_u32 v2, v0, 16, 1
	v_add3_u32 v0, v0, v2, s33
	ds_write_b16_d16_hi v84, v0 offset:6848
	v_mul_f32_e32 v0, v65, v73
	v_bfe_u32 v2, v0, 16, 1
	v_add3_u32 v0, v0, v2, s33
	ds_write_b16_d16_hi v84, v0 offset:6912
	v_mul_f32_e32 v0, v49, v73
	v_bfe_u32 v2, v0, 16, 1
	v_add3_u32 v0, v0, v2, s33
	ds_write_b16_d16_hi v84, v0 offset:6976
	v_mul_f32_e32 v0, v33, v73
	v_bfe_u32 v85, v50, 16, 1
	v_bfe_u32 v2, v0, 16, 1
	s_lshl_b64 s[0:1], s[18:19], 1
	v_readlane_b32 s2, v255, 1
	v_add3_u32 v50, v50, v85, s33
	v_add3_u32 v0, v0, v2, s33
	s_add_u32 s0, s2, s0
	v_readlane_b32 s2, v255, 2
	ds_write_b16_d16_hi v84, v50
	v_bfe_u32 v50, v34, 16, 1
	ds_write_b16_d16_hi v84, v0 offset:7040
	v_mul_f32_e32 v0, v17, v73
	s_addc_u32 s1, s2, s1
	s_lshl_b32 s2, s28, 1
	v_add3_u32 v34, v34, v50, s33
	v_bfe_u32 v2, v0, 16, 1
	s_add_u32 s0, s0, s2
	v_ashrrev_i32_e32 v165, 31, v164
	ds_write_b16_d16_hi v84, v34 offset:64
	v_bfe_u32 v34, v18, 16, 1
	v_add3_u32 v0, v0, v2, s33
	s_addc_u32 s1, s1, 0
	v_lshlrev_b64 v[66:67], 11, v[164:165]
	v_add3_u32 v18, v18, v34, s33
	ds_write_b16_d16_hi v84, v0 offset:7104
	v_lshlrev_b32_e32 v0, 1, v160
	ds_write_b16_d16_hi v84, v18 offset:128
	v_lshl_add_u64 v[2:3], s[0:1], 0, v[66:67]
	v_lshrrev_b32_e32 v14, 4, v177
	v_add_u32_e32 v15, v83, v0
	s_waitcnt lgkmcnt(0)
	v_lshl_add_u64 v[10:11], v[2:3], 0, v[0:1]
	v_lshl_add_u32 v0, v14, 8, v15
	v_or_b32_e32 v16, 4, v14
	ds_read_b128 v[2:5], v0
	v_lshl_add_u32 v6, v16, 8, v15
	ds_read_b128 v[6:9], v6
	v_lshlrev_b32_e32 v0, 11, v14
	v_lshl_add_u64 v[12:13], v[10:11], 0, v[0:1]
	v_lshlrev_b32_e32 v0, 11, v16
	s_waitcnt lgkmcnt(0)
	global_store_dwordx4 v[12:13], v[2:5], off
	v_or_b32_e32 v16, 12, v14
	v_readlane_b32 s0, v252, 1
	v_lshl_add_u64 v[2:3], v[10:11], 0, v[0:1]
	v_or_b32_e32 v0, 8, v14
	global_store_dwordx4 v[2:3], v[6:9], off
	v_lshl_add_u32 v2, v0, 8, v15
	ds_read_b128 v[2:5], v2
	v_lshl_add_u32 v6, v16, 8, v15
	ds_read_b128 v[6:9], v6
	v_lshlrev_b32_e32 v0, 11, v0
	v_lshl_add_u64 v[12:13], v[10:11], 0, v[0:1]
	v_lshlrev_b32_e32 v0, 11, v16
	s_waitcnt lgkmcnt(0)
	global_store_dwordx4 v[12:13], v[2:5], off
	v_or_b32_e32 v16, 20, v14
	s_add_i32 s11, s11, s0
	v_lshl_add_u64 v[2:3], v[10:11], 0, v[0:1]
	v_or_b32_e32 v0, 16, v14
	global_store_dwordx4 v[2:3], v[6:9], off
	v_lshl_add_u32 v2, v0, 8, v15
	ds_read_b128 v[2:5], v2
	v_lshl_add_u32 v6, v16, 8, v15
	ds_read_b128 v[6:9], v6
	v_lshlrev_b32_e32 v0, 11, v0
	v_lshl_add_u64 v[12:13], v[10:11], 0, v[0:1]
	v_lshlrev_b32_e32 v0, 11, v16
	s_waitcnt lgkmcnt(0)
	global_store_dwordx4 v[12:13], v[2:5], off
	s_add_i32 s25, s25, s0
	s_cmpk_gt_i32 s11, 0xff
	v_lshl_add_u64 v[2:3], v[10:11], 0, v[0:1]
	v_or_b32_e32 v0, 24, v14
	global_store_dwordx4 v[2:3], v[6:9], off
	v_lshl_add_u32 v2, v0, 8, v15
	v_or_b32_e32 v14, 28, v14
	ds_read_b128 v[2:5], v2
	v_lshl_add_u32 v6, v14, 8, v15
	ds_read_b128 v[6:9], v6
	v_lshlrev_b32_e32 v0, 11, v0
	v_lshl_add_u64 v[12:13], v[10:11], 0, v[0:1]
	v_lshlrev_b32_e32 v0, 11, v14
	s_waitcnt lgkmcnt(0)
	global_store_dwordx4 v[12:13], v[2:5], off
	s_movk_i32 s75, 0x60
	v_readlane_b32 s1, v252, 2
	v_lshl_add_u64 v[2:3], v[10:11], 0, v[0:1]
	global_store_dwordx4 v[2:3], v[6:9], off
	s_waitcnt lgkmcnt(0)
	s_barrier
	s_cbranch_scc1 .LBB2_437

.LBB2_359:
	s_or_b64 exec, exec, s[2:3]
	s_and_b32 s1, s25, 7
	s_lshl_b32 s6, s1, 8
	s_ashr_i32 s1, s0, 31
	s_lshl_b64 s[18:19], s[0:1], 16
	s_lshl_b64 s[2:3], s[0:1], 17
	v_readlane_b32 s1, v254, 59
	s_add_u32 s1, s1, s2
	v_readlane_b32 s2, v254, 60
	s_addc_u32 s3, s2, s3
	s_lshl_b32 s28, s4, 7
	s_lshl_b32 s8, s4, 8
	v_mov_b32_e32 v22, v146
	s_waitcnt lgkmcnt(0)
	s_barrier
	s_add_u32 s2, s1, s8
	s_addc_u32 s3, s3, 0
	v_ashrrev_i32_e32 v0, 31, v22
	s_lshl_b32 s1, s24, 17
	v_readlane_b32 s4, v254, 61
	v_lshrrev_b32_e32 v0, 28, v0
	s_add_u32 s4, s4, s1
	v_readlane_b32 s5, v254, 62
	v_add_u32_e32 v0, v22, v0
	s_addc_u32 s5, s5, 0
	v_ashrrev_i32_e32 v16, 4, v0
	v_and_b32_e32 v0, -16, v0
	s_add_u32 s4, s4, s8
	v_sub_u32_e32 v24, v22, v0
	v_add_u32_e32 v0, 0x200, v22
	s_addc_u32 s5, s5, 0
	v_readlane_b32 s9, v254, 63
	v_ashrrev_i32_e32 v2, 31, v0
	s_add_u32 s1, s9, s1
	v_readlane_b32 s9, v255, 0
	v_lshrrev_b32_e32 v2, 28, v2
	s_addc_u32 s9, s9, 0
	v_ashrrev_i32_e32 v12, 4, v22
	v_add_u32_e32 v2, v0, v2
	s_add_u32 s8, s1, s8
	v_lshlrev_b32_e32 v23, 3, v22
	v_add_u32_e32 v14, 32, v12
	v_ashrrev_i32_e32 v18, 4, v2
	v_and_b32_e32 v2, -16, v2
	v_ashrrev_i32_e32 v13, 31, v12
	s_addc_u32 s9, s9, 0
	v_and_b32_e32 v160, 0x78, v23
	v_sub_u32_e32 v25, v0, v2
	v_lshlrev_b64 v[2:3], 11, v[12:13]
	v_ashrrev_i32_e32 v15, 31, v14
	v_lshl_add_u64 v[6:7], s[8:9], 0, v[2:3]
	v_lshlrev_b32_e32 v10, 1, v160
	v_mov_b32_e32 v11, v1
	v_lshlrev_b64 v[20:21], 11, v[14:15]
	v_lshlrev_b32_e32 v4, 3, v24
	v_lshl_add_u64 v[6:7], v[6:7], 0, v[10:11]
	v_lshl_add_u64 v[20:21], s[8:9], 0, v[20:21]
	v_ashrrev_i32_e32 v17, 31, v16
	v_lshl_add_u64 v[10:11], v[20:21], 0, v[10:11]
	global_load_dwordx4 v[98:101], v[6:7], off
	global_load_dwordx4 v[102:105], v[10:11], off
	v_ashrrev_i32_e32 v5, 31, v4
	v_lshlrev_b64 v[6:7], 11, v[16:17]
	v_lshl_add_u64 v[10:11], s[4:5], 0, v[6:7]
	v_lshlrev_b64 v[4:5], 1, v[4:5]
	v_lshlrev_b32_e32 v8, 3, v25
	v_lshl_add_u64 v[10:11], v[10:11], 0, v[4:5]
	v_ashrrev_i32_e32 v19, 31, v18
	global_load_dwordx4 v[106:109], v[10:11], off
	v_ashrrev_i32_e32 v9, 31, v8
	v_lshlrev_b64 v[10:11], 11, v[18:19]
	v_lshl_add_u64 v[20:21], s[4:5], 0, v[10:11]
	v_lshlrev_b64 v[8:9], 1, v[8:9]
	v_lshl_add_u64 v[20:21], v[20:21], 0, v[8:9]
	global_load_dwordx4 v[118:121], v[20:21], off
	v_ashrrev_i32_e32 v178, 6, v22
	v_add_u32_e32 v0, s0, v172
	v_and_b32_e32 v179, 31, v22
	v_lshlrev_b32_e32 v164, 5, v178
	v_max_i32_e32 v0, 4, v0
	v_or_b32_e32 v20, v164, v179
	v_add_u32_e32 v0, -4, v0
	v_ashrrev_i32_e32 v21, 31, v20
	v_min_u32_e32 v165, 0x78, v0
	v_bfe_u32 v180, v22, 5, 1
	v_and_b32_e32 v0, 0x3fffffc0, v22
	s_add_i32 s1, 0, 0x10000
	v_lshlrev_b64 v[20:21], 11, v[20:21]
	v_lshl_add_u32 v13, v0, 2, s1
	v_lshl_add_u64 v[20:21], s[2:3], 0, v[20:21]
	v_lshlrev_b32_e32 v0, 4, v180
	v_lshl_add_u64 v[20:21], v[20:21], 0, v[0:1]
	global_load_dwordx4 v[110:113], v[20:21], off
	global_load_dwordx4 v[114:117], v[20:21], off offset:32
	global_load_dwordx4 v[122:125], v[20:21], off offset:64
	global_load_dwordx4 v[126:129], v[20:21], off offset:96
	global_load_dwordx4 v[130:133], v[20:21], off offset:128
	global_load_dwordx4 v[134:137], v[20:21], off offset:160
	global_load_dwordx4 v[138:141], v[20:21], off offset:192
	global_load_dwordx4 v[142:145], v[20:21], off offset:224
	v_and_b32_e32 v15, 0xfffff0, v12
	v_lshlrev_b32_e32 v17, 1, v12
	v_and_or_b32 v15, v17, 8, v15
	v_lshrrev_b32_e32 v17, 1, v12
	v_and_b32_e32 v12, 3, v12
	v_and_or_b32 v12, v17, 4, v12
	v_and_b32_e32 v17, 0xfffff0, v14
	v_lshlrev_b32_e32 v14, 1, v14
	v_lshrrev_b32_e32 v15, 1, v15
	v_bfe_u32 v19, v23, 5, 2
	v_and_or_b32 v14, v14, 8, v17
	v_or_b32_e32 v15, v15, v19
	v_lshrrev_b32_e32 v14, 1, v14
	v_lshlrev_b32_e32 v17, 4, v22
	v_lshlrev_b32_e32 v15, 9, v15
	v_lshlrev_b32_e32 v12, 6, v12
	v_or_b32_e32 v14, v14, v19
	v_and_b32_e32 v19, 48, v17
	v_lshlrev_b32_e32 v14, 9, v14
	v_or3_b32 v182, v15, v12, v19
	v_or3_b32 v181, v14, v12, v19
	v_add_u32_e32 v15, 0, v182
	s_waitcnt vmcnt(0)
	v_lshlrev_b32_e32 v183, 8, v16
	v_lshlrev_b32_e32 v185, 8, v18
	s_movk_i32 s1, 0x70
	v_bitop3_b32 v192, v0, v17, s1 bitop3:0x78
	s_movk_i32 s1, 0x80
	v_lshlrev_b32_e32 v14, 1, v22
	v_and_b32_e32 v14, 32, v14
	s_cmp_lg_u32 0, -1
	v_and_b32_e32 v12, 0xc0, v17
	v_add_u32_e32 v200, v13, v0
	v_and_b32_e32 v177, 63, v22
	v_lshl_add_u32 v203, v179, 2, v13
	v_mov_b32_e32 v13, v1
	v_add_u32_e32 v187, 8, v165
	v_lshlrev_b32_e32 v191, 8, v179
	v_mov_b32_e32 v237, 0
	v_mov_b32_e32 v236, 0xf149f2ca
	s_mov_b64 s[2:3], 0
	s_waitcnt vmcnt(0) lgkmcnt(0)
	ds_write_b128 v15, v[98:101]
	v_add_u32_e32 v15, 0, v181
	ds_write_b128 v15, v[102:105]
	v_bitop3_b32 v15, v16, v24, 7 bitop3:0x6c
	v_lshlrev_b32_e32 v184, 4, v15
	v_add3_u32 v15, 0, v183, v184
	ds_write_b128 v15, v[106:109] offset:32768
	v_bitop3_b32 v15, v18, v25, 7 bitop3:0x6c
	v_lshlrev_b32_e32 v186, 4, v15
	v_add3_u32 v15, 0, v185, v186
	ds_write_b128 v15, v[118:121] offset:32768
	v_and_b32_e32 v15, 0x70, v17
	v_bitop3_b32 v196, v0, v15, s1 bitop3:0x36
	s_movk_i32 s1, 0xa0
	v_bitop3_b32 v197, v0, v15, s1 bitop3:0x36
	s_movk_i32 s1, 0xc0
	v_bitop3_b32 v198, v0, v15, s1 bitop3:0x36
	s_movk_i32 s1, 0xe0
	v_bitop3_b32 v193, v0, v15, 32 bitop3:0x36
	v_bitop3_b32 v194, v0, v15, 64 bitop3:0x36
	v_bitop3_b32 v195, v0, v15, s75 bitop3:0x36
	v_bitop3_b32 v199, v0, v15, s1 bitop3:0x36
	v_lshlrev_b32_e32 v15, 2, v180
	v_or_b32_e32 v18, 1, v15
	v_or_b32_e32 v19, 33, v15
	v_sub_u32_e32 v20, v18, v174
	v_cmp_gt_u32_e64 s[42:43], 16, v20
	v_sub_u32_e32 v20, v19, v174
	v_cmp_gt_u32_e64 s[44:45], 16, v20
	v_or_b32_e32 v20, 2, v15
	v_or_b32_e32 v21, 34, v15
	v_sub_u32_e32 v24, v20, v174
	v_cmp_gt_u32_e64 s[46:47], 16, v24
	v_sub_u32_e32 v24, v21, v174
	v_cmp_gt_u32_e64 s[48:49], 16, v24
	v_or_b32_e32 v24, 3, v15
	v_or_b32_e32 v25, 35, v15
	v_sub_u32_e32 v26, v24, v174
	v_cmp_gt_u32_e64 s[50:51], 16, v26
	v_sub_u32_e32 v26, v25, v174
	v_cmp_gt_u32_e64 s[52:53], 16, v26
	v_or_b32_e32 v26, 8, v15
	v_or_b32_e32 v27, 40, v15
	v_sub_u32_e32 v28, v26, v174
	v_cmp_gt_u32_e64 s[54:55], 16, v28
	v_sub_u32_e32 v28, v27, v174
	v_cmp_gt_u32_e64 s[56:57], 16, v28
	v_or_b32_e32 v28, 9, v15
	v_or_b32_e32 v29, 41, v15
	v_sub_u32_e32 v30, v28, v174
	v_cmp_gt_u32_e64 s[58:59], 16, v30
	v_sub_u32_e32 v30, v29, v174
	v_cmp_gt_u32_e64 s[60:61], 16, v30
	v_or_b32_e32 v30, 10, v15
	v_or_b32_e32 v31, 42, v15
	v_sub_u32_e32 v32, v30, v174
	v_cmp_gt_u32_e64 s[62:63], 16, v32
	v_sub_u32_e32 v32, v31, v174
	v_cmp_gt_u32_e64 s[64:65], 16, v32
	v_or_b32_e32 v32, 11, v15
	v_or_b32_e32 v33, 43, v15
	v_sub_u32_e32 v34, v32, v174
	v_cmp_gt_u32_e64 s[66:67], 16, v34
	v_sub_u32_e32 v34, v33, v174
	v_cmp_gt_u32_e64 s[68:69], 16, v34
	v_or_b32_e32 v34, 16, v15
	v_sub_u32_e32 v36, v34, v174
	v_cmp_gt_u32_e64 s[70:71], 16, v36
	v_or_b32_e32 v36, 17, v15
	v_sub_u32_e32 v38, v36, v174
	v_cmp_gt_u32_e64 s[74:75], 16, v38
	v_or_b32_e32 v38, 18, v15
	v_sub_u32_e32 v40, v38, v174
	v_cmp_gt_u32_e64 s[78:79], 16, v40
	v_or_b32_e32 v40, 19, v15
	v_sub_u32_e32 v42, v40, v174
	v_cmp_gt_u32_e64 s[82:83], 16, v42
	v_or_b32_e32 v42, 24, v15
	v_sub_u32_e32 v44, v42, v174
	v_cmp_gt_u32_e64 s[86:87], 16, v44
	v_or_b32_e32 v44, 25, v15
	v_sub_u32_e32 v46, v44, v174
	v_cmp_gt_u32_e64 s[90:91], 16, v46
	v_or_b32_e32 v46, 26, v15
	v_sub_u32_e32 v48, v46, v174
	v_cmp_gt_u32_e64 s[94:95], 16, v48
	v_add_u32_e32 v48, s24, v176
	v_subrev_u32_e32 v201, s0, v48
	s_movk_i32 s0, 0x118
	v_and_or_b32 v14, v23, s0, v14
	s_cselect_b32 s0, 0, 0
	s_cmpk_lt_u32 s7, 0x74
	v_add3_u32 v202, v12, s0, v14
	s_cselect_b32 s0, s7, 0x74
	v_or_b32_e32 v16, 32, v15
	v_sub_u32_e32 v17, v15, v174
	v_or_b32_e32 v48, 27, v15
	s_lshl_b32 s16, s0, 17
	v_cmp_gt_u32_e64 s[38:39], 16, v17
	v_sub_u32_e32 v17, v16, v174
	v_or_b32_e32 v35, 48, v15
	v_or_b32_e32 v37, 49, v15
	v_or_b32_e32 v39, 50, v15
	v_or_b32_e32 v41, 51, v15
	v_or_b32_e32 v43, 56, v15
	v_or_b32_e32 v45, 57, v15
	v_or_b32_e32 v47, 58, v15
	v_or_b32_e32 v66, 59, v15
	v_sub_u32_e32 v14, v48, v173
	v_lshl_add_u64 v[10:11], s[16:17], 0, v[10:11]
	v_lshl_add_u64 v[6:7], s[16:17], 0, v[6:7]
	v_and_b32_e32 v0, 15, v22
	v_cmp_gt_u32_e64 s[40:41], 16, v17
	v_sub_u32_e32 v17, v15, v173
	v_sub_u32_e32 v19, v19, v173
	v_sub_u32_e32 v18, v18, v173
	v_sub_u32_e32 v21, v21, v173
	v_sub_u32_e32 v20, v20, v173
	v_sub_u32_e32 v25, v25, v173
	v_sub_u32_e32 v24, v24, v173
	v_sub_u32_e32 v27, v27, v173
	v_sub_u32_e32 v26, v26, v173
	v_sub_u32_e32 v29, v29, v173
	v_sub_u32_e32 v28, v28, v173
	v_sub_u32_e32 v31, v31, v173
	v_sub_u32_e32 v30, v30, v173
	v_sub_u32_e32 v33, v33, v173
	v_sub_u32_e32 v32, v32, v173
	v_cmp_lt_u32_e64 s[72:73], v35, v175
	v_sub_u32_e32 v35, v35, v173
	v_sub_u32_e32 v34, v34, v173
	v_cmp_lt_u32_e64 s[76:77], v37, v175
	v_sub_u32_e32 v37, v37, v173
	v_sub_u32_e32 v36, v36, v173
	v_cmp_lt_u32_e64 s[80:81], v39, v175
	v_sub_u32_e32 v39, v39, v173
	v_sub_u32_e32 v38, v38, v173
	v_cmp_lt_u32_e64 s[84:85], v41, v175
	v_sub_u32_e32 v41, v41, v173
	v_sub_u32_e32 v40, v40, v173
	v_cmp_lt_u32_e64 s[88:89], v43, v175
	v_sub_u32_e32 v43, v43, v173
	v_sub_u32_e32 v42, v42, v173
	v_cmp_lt_u32_e64 s[92:93], v45, v175
	v_sub_u32_e32 v45, v45, v173
	v_sub_u32_e32 v44, v44, v173
	v_cmp_lt_u32_e64 s[96:97], v47, v175
	v_sub_u32_e32 v47, v47, v173
	v_sub_u32_e32 v46, v46, v173
	v_sub_u32_e32 v15, v48, v174
	v_sub_u32_e32 v12, v66, v173
	v_med3_i32 v14, v14, -15, 15
	v_or_b32_e32 v10, s6, v10
	v_or_b32_e32 v6, s6, v6
	v_lshl_add_u64 v[2:3], s[16:17], 0, v[2:3]
	v_lshlrev_b32_e32 v0, 4, v0
	v_sub_u32_e32 v16, v16, v173
	v_med3_i32 v19, v19, -15, 15
	v_med3_i32 v18, v18, -15, 15
	v_med3_i32 v21, v21, -15, 15
	v_med3_i32 v20, v20, -15, 15
	v_med3_i32 v25, v25, -15, 15
	v_med3_i32 v24, v24, -15, 15
	v_med3_i32 v27, v27, -15, 15
	v_med3_i32 v26, v26, -15, 15
	v_med3_i32 v29, v29, -15, 15
	v_med3_i32 v28, v28, -15, 15
	v_med3_i32 v31, v31, -15, 15
	v_med3_i32 v30, v30, -15, 15
	v_med3_i32 v33, v33, -15, 15
	v_med3_i32 v32, v32, -15, 15
	v_med3_i32 v35, v35, -15, 15
	v_med3_i32 v34, v34, -15, 15
	v_med3_i32 v37, v37, -15, 15
	v_med3_i32 v36, v36, -15, 15
	v_med3_i32 v39, v39, -15, 15
	v_med3_i32 v38, v38, -15, 15
	v_med3_i32 v41, v41, -15, 15
	v_med3_i32 v40, v40, -15, 15
	v_med3_i32 v43, v43, -15, 15
	v_med3_i32 v42, v42, -15, 15
	v_med3_i32 v45, v45, -15, 15
	v_med3_i32 v44, v44, -15, 15
	v_med3_i32 v47, v47, -15, 15
	v_med3_i32 v46, v46, -15, 15
	v_cmp_gt_u32_e64 s[98:99], 16, v15
	v_med3_i32 v12, v12, -15, 15
	v_lshl_add_u32 v234, v14, 2, s10
	v_or3_b32 v2, v2, s6, v0
	v_lshl_add_u64 v[8:9], v[10:11], 0, v[8:9]
	v_lshl_add_u64 v[4:5], v[6:7], 0, v[4:5]
	v_mov_b32_e32 v14, v1
	v_mov_b32_e32 v15, v1
	v_med3_i32 v16, v16, -15, 15
	v_med3_i32 v17, v17, -15, 15
	v_lshl_add_u32 v206, v18, 2, s10
	v_lshl_add_u32 v207, v19, 2, s10
	v_lshl_add_u32 v208, v20, 2, s10
	v_lshl_add_u32 v209, v21, 2, s10
	v_lshl_add_u32 v210, v24, 2, s10
	v_lshl_add_u32 v211, v25, 2, s10
	v_lshl_add_u32 v212, v26, 2, s10
	v_lshl_add_u32 v213, v27, 2, s10
	v_lshl_add_u32 v214, v28, 2, s10
	v_lshl_add_u32 v215, v29, 2, s10
	v_lshl_add_u32 v216, v30, 2, s10
	v_lshl_add_u32 v217, v31, 2, s10
	v_lshl_add_u32 v218, v32, 2, s10
	v_lshl_add_u32 v219, v33, 2, s10
	v_lshl_add_u32 v220, v34, 2, s10
	v_lshl_add_u32 v221, v35, 2, s10
	v_lshl_add_u32 v222, v36, 2, s10
	v_lshl_add_u32 v223, v37, 2, s10
	v_lshl_add_u32 v224, v38, 2, s10
	v_lshl_add_u32 v225, v39, 2, s10
	v_lshl_add_u32 v226, v40, 2, s10
	v_lshl_add_u32 v227, v41, 2, s10
	v_lshl_add_u32 v228, v42, 2, s10
	v_lshl_add_u32 v229, v43, 2, s10
	v_lshl_add_u32 v230, v44, 2, s10
	v_lshl_add_u32 v231, v45, 2, s10
	v_lshl_add_u32 v232, v46, 2, s10
	v_lshl_add_u32 v233, v47, 2, s10
	v_lshl_add_u32 v235, v12, 2, s10
	v_lshl_add_u64 v[166:167], s[30:31], 0, v[8:9]
	v_lshl_add_u64 v[168:169], s[30:31], 0, v[4:5]
	v_lshl_add_u64 v[170:171], s[12:13], 0, v[2:3]
	v_mov_b32_e32 v0, v1
	v_mov_b32_e32 v2, v1
	v_mov_b32_e32 v3, v1
	v_mov_b32_e32 v4, v1
	v_mov_b32_e32 v5, v1
	v_mov_b32_e32 v6, v1
	v_mov_b32_e32 v7, v1
	v_mov_b32_e32 v8, v1
	v_mov_b32_e32 v9, v1
	v_mov_b32_e32 v10, v1
	v_mov_b32_e32 v11, v1
	v_mov_b32_e32 v12, v1
	v_mov_b64_e32 v[64:65], v[14:15]
	v_mov_b64_e32 v[48:49], v[14:15]
	v_mov_b64_e32 v[32:33], v[14:15]
	v_lshl_add_u32 v204, v17, 2, s10
	v_lshl_add_u32 v205, v16, 2, s10
	v_mov_b64_e32 v[62:63], v[12:13]
	v_mov_b64_e32 v[60:61], v[10:11]
	v_mov_b64_e32 v[58:59], v[8:9]
	v_mov_b64_e32 v[56:57], v[6:7]
	v_mov_b64_e32 v[54:55], v[4:5]
	v_mov_b64_e32 v[52:53], v[2:3]
	v_mov_b64_e32 v[50:51], v[0:1]
	v_mov_b64_e32 v[46:47], v[12:13]
	v_mov_b64_e32 v[44:45], v[10:11]
	v_mov_b64_e32 v[42:43], v[8:9]
	v_mov_b64_e32 v[40:41], v[6:7]
	v_mov_b64_e32 v[38:39], v[4:5]
	v_mov_b64_e32 v[36:37], v[2:3]
	v_mov_b64_e32 v[34:35], v[0:1]
	v_mov_b64_e32 v[30:31], v[12:13]
	v_mov_b64_e32 v[28:29], v[10:11]
	v_mov_b64_e32 v[26:27], v[8:9]
	v_mov_b64_e32 v[24:25], v[6:7]
	v_mov_b64_e32 v[22:23], v[4:5]
	v_mov_b64_e32 v[20:21], v[2:3]
	v_mov_b64_e32 v[18:19], v[0:1]
	v_mov_b64_e32 v[16:17], v[14:15]
	s_mov_b32 s16, 0
	v_mov_b64_e32 v[14:15], v[12:13]
	v_mov_b64_e32 v[12:13], v[10:11]
	v_mov_b64_e32 v[10:11], v[8:9]
	v_mov_b64_e32 v[8:9], v[6:7]
	v_mov_b64_e32 v[6:7], v[4:5]
	v_mov_b64_e32 v[4:5], v[2:3]
	v_mov_b64_e32 v[2:3], v[0:1]
	v_cmp_lt_u32_e64 s[6:7], v66, v175
	v_cmp_gt_u32_e64 s[0:1], 32, v177
	s_waitcnt lgkmcnt(0)
	s_barrier
	s_branch .LBB2_361

.LBB2_361:
	s_cmp_lg_u32 s2, 0x160000
	s_cselect_b64 s[8:9], -1, 0
	s_cmp_eq_u32 s2, 0x160000
	s_cbranch_scc1 .LBB2_363
	v_lshl_add_u64 v[66:67], v[170:171], 0, s[2:3]
	v_add_co_u32_e32 v68, vcc, 0x6820000, v66
	s_nop 1
	v_addc_co_u32_e32 v69, vcc, 0, v67, vcc
	v_add_co_u32_e32 v66, vcc, 0x6830000, v66
	s_nop 1
	v_addc_co_u32_e32 v67, vcc, 0, v67, vcc
	s_waitcnt vmcnt(0)
	global_load_dwordx4 v[98:101], v[68:69], off
	global_load_dwordx4 v[102:105], v[66:67], off
	v_lshl_add_u64 v[66:67], v[168:169], 0, s[2:3]
	v_lshl_add_u64 v[68:69], v[166:167], 0, s[2:3]
	global_load_dwordx4 v[106:109], v[66:67], off
	global_load_dwordx4 v[118:121], v[68:69], off

.LBB2_451:
	s_cmp_lg_u32 s11, 0
	s_cselect_b64 s[0:1], -1, 0
	s_cmp_eq_u32 s11, 0
	v_lshl_add_u32 v168, s12, 8, v143
	s_cselect_b64 s[2:3], -1, 0
	s_and_b64 s[8:9], s[2:3], exec
	v_ashrrev_i32_e32 v169, 31, v168
	s_cselect_b32 s11, 0, 8
	s_cmp_gt_i32 s74, 3
	v_lshlrev_b64 v[130:131], 6, v[168:169]
	s_cselect_b64 s[12:13], -1, 0
	v_lshl_add_u64 v[130:131], s[46:47], 0, v[130:131]
	s_lshl_b32 s58, s11, 2
	s_mov_b32 s59, s17
	v_lshl_add_u64 v[156:157], v[130:131], 0, s[58:59]
	global_load_dwordx4 v[130:133], v[156:157], off
	global_load_dwordx4 v[170:173], v[156:157], off offset:16
	s_and_b64 s[2:3], s[2:3], s[12:13]
	s_lshl_b32 s51, s74, 1
	v_readlane_b32 s20, v254, 38
	s_mov_b64 s[8:9], -1
	s_add_i32 s51, s51, -8
	v_readlane_b32 s22, v254, 36
	v_readlane_b32 s21, v254, 39
	v_readlane_b32 s23, v254, 37
	s_waitcnt vmcnt(0) lgkmcnt(0)
	v_mov_b32_e32 v156, v130
	v_mov_b32_e32 v157, v170
	v_mov_b32_e32 v170, v131
	v_pk_add_f32 v[130:131], v[156:157], v[170:171]
	v_mov_b32_e32 v156, v132
	v_mov_b32_e32 v157, v172
	v_mov_b32_e32 v172, v133
	v_pk_add_f32 v[132:133], v[156:157], v[172:173]
	s_nop 0
	v_pk_add_f32 v[130:131], v[130:131], v[132:133]
	s_nop 0
	v_add_f32_e32 v0, v130, v131
	v_fmamk_f32 v0, v0, 0x3b000000, v147
	v_cmp_gt_f32_e32 vcc, s29, v0
	v_mul_f32_e32 v130, 0x4b800000, v0
	s_nop 0
	v_cndmask_b32_e32 v0, v0, v130, vcc
	v_rsq_f32_e32 v0, v0
	s_nop 0
	v_mul_f32_e32 v130, 0x45800000, v0
	v_cndmask_b32_e32 v170, v0, v130, vcc
	s_and_b64 vcc, exec, s[2:3]
	s_cbranch_vccnz .LBB2_469
	s_movk_i32 s8, 0xc00
	v_mad_i64_i32 v[130:131], s[8:9], v168, s8, 0
	v_lshlrev_b64 v[132:133], 11, v[168:169]
	s_mov_b64 s[8:9], -1
	s_and_b64 vcc, exec, s[0:1]
	s_cbranch_vccz .LBB2_458
	s_and_b64 vcc, exec, s[12:13]
	s_cbranch_vccz .LBB2_455
	v_lshl_add_u64 v[156:157], s[44:45], 0, v[132:133]
	s_lshl_b32 s16, s51, 7
	v_lshl_add_u64 v[172:173], s[16:17], 1, v[156:157]
	s_mov_b64 s[8:9], 0

.LBB2_460:
	v_lshlrev_b32_e32 v0, 1, v144
	v_pk_mul_f32 v[178:179], v[122:123], v[170:171] op_sel_hi:[1,0]
	v_lshl_add_u64 v[172:173], v[172:173], 0, v[0:1]
	s_andn2_b64 vcc, exec, s[0:1]
	s_mov_b64 s[8:9], -1
	v_pk_mul_f32 v[156:157], v[128:129], v[170:171] op_sel_hi:[1,0]
	v_pk_mul_f32 v[158:159], v[126:127], v[170:171] op_sel_hi:[1,0]
	v_pk_mul_f32 v[180:181], v[124:125], v[170:171] op_sel_hi:[1,0]
	v_cvt_pk_bf16_f32 v176, v158, v159
	v_cvt_pk_bf16_f32 v177, v156, v157
	v_cvt_pk_bf16_f32 v178, v178, v179
	s_nop 0
	v_cvt_pk_bf16_f32 v179, v180, v181
	global_store_dwordx4 v[172:173], v[176:179], off
	s_cbranch_vccnz .LBB2_466
	s_andn2_b64 vcc, exec, s[12:13]
	s_cbranch_vccnz .LBB2_463
	v_lshl_add_u64 v[132:133], s[44:45], 0, v[132:133]
	s_lshl_b32 s16, s74, 9
	s_movk_i32 s8, 0xf900
	v_lshl_add_u64 v[132:133], v[132:133], 0, s[16:17]
	s_mov_b32 s9, -1
	v_lshl_add_u64 v[172:173], v[132:133], 0, s[8:9]
	s_mov_b64 s[8:9], 0

.LBB2_468:
	v_mov_b32_e32 v130, v170
	v_mov_b32_e32 v131, v170
	v_mov_b32_e32 v171, v170
	v_pk_mul_f32 v[132:133], v[120:121], v[130:131]
	v_lshl_add_u64 v[172:173], v[172:173], 0, v[0:1]
	s_mov_b64 s[8:9], 0
	v_pk_mul_f32 v[156:157], v[118:119], v[170:171]
	v_pk_mul_f32 v[158:159], v[116:117], v[130:131]
	v_pk_mul_f32 v[166:167], v[114:115], v[170:171]
	v_cvt_pk_bf16_f32 v130, v156, v157
	v_cvt_pk_bf16_f32 v131, v132, v133
	s_nop 0
	v_cvt_pk_bf16_f32 v132, v166, v167
	v_cvt_pk_bf16_f32 v133, v158, v159
	global_store_dwordx4 v[172:173], v[130:133], off
.LBB2_469:
	s_lshl_b32 s11, s74, 2
	s_add_i32 s11, s71, s11
	s_mul_i32 s16, s11, 0xc0
	s_and_b64 vcc, exec, s[8:9]
	v_lshlrev_b32_e32 v166, 1, v142
	s_cbranch_vccz .LBB2_471
	v_lshlrev_b64 v[130:131], 8, v[168:169]
	v_lshl_add_u64 v[156:157], v[160:161], 0, v[130:131]
	global_load_dwordx4 v[130:133], v[156:157], off offset:48
	global_load_dwordx4 v[242:245], v[156:157], off offset:16
	global_load_dwordx4 v[246:249], v[156:157], off
	global_load_dwordx4 v[176:179], v[156:157], off offset:32
	v_mov_b32_e32 v158, v116
	v_mov_b32_e32 v159, v124
	v_pk_mul_f32 v[158:159], v[158:159], v[170:171] op_sel_hi:[1,0]
	v_mov_b32_e32 v124, v117
	s_movk_i32 s8, 0xc00
	s_waitcnt vmcnt(0) lgkmcnt(0)
	v_pk_mul_f32 v[172:173], v[158:159], v[130:131]
	v_pk_mul_f32 v[130:131], v[158:159], v[130:131] op_sel:[1,0] op_sel_hi:[0,1]
	v_sub_f32_e32 v167, v130, v131
	v_mov_b32_e32 v130, v115
	v_mov_b32_e32 v131, v123
	v_mov_b32_e32 v115, v122
	v_pk_mul_f32 v[130:131], v[130:131], v[170:171] op_sel_hi:[1,0]
	v_pk_mul_f32 v[114:115], v[114:115], v[170:171] op_sel_hi:[1,0]
	v_pk_mul_f32 v[158:159], v[130:131], v[178:179]
	v_pk_mul_f32 v[130:131], v[130:131], v[178:179] op_sel:[1,0] op_sel_hi:[0,1]
	v_pk_mul_f32 v[122:123], v[114:115], v[176:177]
	v_pk_mul_f32 v[114:115], v[114:115], v[176:177] op_sel:[1,0] op_sel_hi:[0,1]
	v_mov_b32_e32 v176, v242
	v_mov_b32_e32 v177, v243
	v_mov_b32_e32 v178, v244
	v_mov_b32_e32 v179, v245
	v_add_f32_e32 v158, v158, v159
	v_sub_f32_e32 v159, v114, v115
	v_mov_b32_e32 v114, v121
	v_mov_b32_e32 v115, v129
	v_pk_mul_f32 v[114:115], v[114:115], v[170:171] op_sel_hi:[1,0]
	v_sub_f32_e32 v130, v130, v131
	v_add_f32_e32 v131, v122, v123
	v_mov_b32_e32 v121, v128
	v_add_f32_e32 v0, v172, v173
	s_waitcnt vmcnt(0) lgkmcnt(0)
	v_pk_mul_f32 v[122:123], v[114:115], v[178:179]
	v_pk_mul_f32 v[114:115], v[114:115], v[178:179] op_sel:[1,0] op_sel_hi:[0,1]
	v_sub_f32_e32 v171, v114, v115
	v_pk_mul_f32 v[114:115], v[120:121], v[170:171] op_sel_hi:[1,0]
	v_add_f32_e32 v169, v122, v123
	v_pk_mul_f32 v[120:121], v[114:115], v[176:177]
	v_pk_mul_f32 v[114:115], v[114:115], v[176:177] op_sel:[1,0] op_sel_hi:[0,1]
	v_add_f32_e32 v172, v120, v121
	v_mov_b32_e32 v120, v246
	v_mov_b32_e32 v121, v247
	v_mov_b32_e32 v122, v248
	v_mov_b32_e32 v123, v249
	v_sub_f32_e32 v173, v114, v115
	v_mov_b32_e32 v114, v119
	v_mov_b32_e32 v115, v127
	v_pk_mul_f32 v[114:115], v[114:115], v[170:171] op_sel_hi:[1,0]
	v_mov_b32_e32 v119, v126
	s_waitcnt vmcnt(0) lgkmcnt(0)
	v_pk_mul_f32 v[128:129], v[114:115], v[122:123]
	v_pk_mul_f32 v[114:115], v[114:115], v[122:123] op_sel:[1,0] op_sel_hi:[0,1]
	v_sub_f32_e32 v122, v114, v115
	v_pk_mul_f32 v[114:115], v[118:119], v[170:171] op_sel_hi:[1,0]
	v_add_f32_e32 v127, v128, v129
	v_pk_mul_f32 v[118:119], v[114:115], v[120:121]
	v_pk_mul_f32 v[114:115], v[114:115], v[120:121] op_sel:[1,0] op_sel_hi:[0,1]
	v_add_f32_e32 v118, v118, v119
	v_sub_f32_e32 v119, v114, v115
	v_pk_mul_f32 v[114:115], v[124:125], v[170:171] op_sel_hi:[1,0]
	s_nop 0
	v_pk_mul_f32 v[116:117], v[114:115], v[132:133] op_sel:[1,0] op_sel_hi:[0,1]
	v_pk_mul_f32 v[114:115], v[114:115], v[132:133]
	v_sub_f32_e32 v117, v116, v117
	v_add_f32_e32 v121, v114, v115
	v_cvt_pk_bf16_f32 v114, v119, v122
	v_mov_b64_e32 v[122:123], s[6:7]
	v_mad_i64_i32 v[122:123], s[8:9], v168, s8, v[122:123]
	v_cvt_pk_bf16_f32 v115, v173, v171
	v_cvt_pk_bf16_f32 v116, v159, v130
	v_cvt_pk_bf16_f32 v117, v167, v117
	v_lshl_add_u64 v[122:123], s[16:17], 1, v[122:123]
	v_mov_b32_e32 v167, v1
	v_lshl_add_u64 v[122:123], v[122:123], 0, v[166:167]
	v_cvt_pk_bf16_f32 v118, v118, v127
	v_cvt_pk_bf16_f32 v119, v172, v169
	v_cvt_pk_bf16_f32 v120, v131, v158
	v_cvt_pk_bf16_f32 v121, v0, v121
	global_store_dwordx4 v[122:123], v[114:117], off offset:256
	global_store_dwordx4 v[122:123], v[118:121], off offset:320
.LBB2_471:
	s_nop 1
	v_or_b32_e32 v118, 16, v168
	v_ashrrev_i32_e32 v119, 31, v118
	v_lshlrev_b64 v[114:115], 6, v[118:119]
	v_lshl_add_u64 v[114:115], s[46:47], 0, v[114:115]
	s_mov_b32 s59, s17
	v_lshl_add_u64 v[120:121], v[114:115], 0, s[58:59]
	global_load_dwordx4 v[114:117], v[120:121], off
	s_nop 0
	global_load_dwordx4 v[120:123], v[120:121], off offset:16
	s_xor_b64 s[2:3], s[2:3], -1
	s_mov_b64 s[8:9], -1
	s_waitcnt vmcnt(0) lgkmcnt(0)
	v_mov_b32_e32 v124, v114
	v_mov_b32_e32 v125, v120
	v_mov_b32_e32 v120, v115
	v_pk_add_f32 v[114:115], v[124:125], v[120:121]
	v_mov_b32_e32 v120, v116
	v_mov_b32_e32 v121, v122
	v_mov_b32_e32 v122, v117
	v_pk_add_f32 v[116:117], v[120:121], v[122:123]
	s_nop 0
	v_pk_add_f32 v[114:115], v[114:115], v[116:117]
	s_nop 0
	v_add_f32_e32 v0, v114, v115
	v_fmamk_f32 v0, v0, 0x3b000000, v147
	v_cmp_gt_f32_e32 vcc, s29, v0
	v_mul_f32_e32 v114, 0x4b800000, v0
	s_nop 0
	v_cndmask_b32_e32 v0, v0, v114, vcc
	v_rsq_f32_e32 v0, v0
	s_nop 0
	v_mul_f32_e32 v114, 0x45800000, v0
	v_cndmask_b32_e32 v120, v0, v114, vcc
	v_cndmask_b32_e64 v0, 0, 1, s[2:3]
	v_cmp_ne_u32_e64 s[40:41], 1, v0
	v_cndmask_b32_e64 v0, 0, 1, s[0:1]
	s_andn2_b64 vcc, exec, s[2:3]
	v_cmp_ne_u32_e64 s[38:39], 1, v0
	s_movk_i32 s2, 0xc00
	s_cbranch_vccnz .LBB2_489
	v_mad_i64_i32 v[114:115], s[0:1], v118, s2, 0
	v_lshlrev_b64 v[116:117], 11, v[118:119]
	s_and_b64 vcc, exec, s[38:39]
	s_mov_b64 s[0:1], -1
	s_cbranch_vccnz .LBB2_478
	s_andn2_b64 vcc, exec, s[12:13]
	s_cbranch_vccnz .LBB2_475
	v_lshl_add_u64 v[122:123], s[44:45], 0, v[116:117]
	s_lshl_b32 s0, s51, 7
	s_mov_b32 s1, s17
	v_lshl_add_u64 v[124:125], s[0:1], 1, v[122:123]
	s_mov_b64 s[0:1], 0

.LBB2_480:
	v_lshlrev_b32_e32 v0, 1, v144
	v_pk_mul_f32 v[126:127], v[112:113], v[120:121] op_sel_hi:[1,0]
	v_pk_mul_f32 v[128:129], v[110:111], v[120:121] op_sel_hi:[1,0]
	v_lshl_add_u64 v[156:157], v[124:125], 0, v[0:1]
	v_cvt_pk_bf16_f32 v124, v128, v129
	v_cvt_pk_bf16_f32 v125, v126, v127
	s_and_b64 vcc, exec, s[38:39]
	s_mov_b64 s[0:1], -1
	v_pk_mul_f32 v[130:131], v[108:109], v[120:121] op_sel_hi:[1,0]
	v_pk_mul_f32 v[132:133], v[106:107], v[120:121] op_sel_hi:[1,0]
	s_nop 0
	v_cvt_pk_bf16_f32 v126, v132, v133
	v_cvt_pk_bf16_f32 v127, v130, v131
	global_store_dwordx4 v[156:157], v[124:127], off
	s_cbranch_vccnz .LBB2_486
	s_andn2_b64 vcc, exec, s[12:13]
	s_cbranch_vccnz .LBB2_483
	v_lshl_add_u64 v[116:117], s[44:45], 0, v[116:117]
	s_lshl_b32 s0, s74, 9
	s_mov_b32 s1, s17
	v_lshl_add_u64 v[116:117], v[116:117], 0, s[0:1]
	s_movk_i32 s0, 0xf900
	s_mov_b32 s1, -1
	v_lshl_add_u64 v[124:125], v[116:117], 0, s[0:1]
	s_mov_b64 s[0:1], 0

.LBB2_488:
	v_mov_b32_e32 v114, v120
	v_mov_b32_e32 v115, v120
	v_mov_b32_e32 v121, v120
	v_pk_mul_f32 v[116:117], v[104:105], v[114:115]
	v_lshl_add_u64 v[124:125], v[124:125], 0, v[0:1]
	s_mov_b64 s[8:9], 0
	v_pk_mul_f32 v[122:123], v[102:103], v[120:121]
	v_pk_mul_f32 v[126:127], v[100:101], v[114:115]
	v_pk_mul_f32 v[128:129], v[98:99], v[120:121]
	v_cvt_pk_bf16_f32 v114, v122, v123
	v_cvt_pk_bf16_f32 v115, v116, v117
	s_nop 0
	v_cvt_pk_bf16_f32 v116, v128, v129
	v_cvt_pk_bf16_f32 v117, v126, v127
	global_store_dwordx4 v[124:125], v[114:117], off
.LBB2_489:
	s_and_b64 vcc, exec, s[8:9]
	s_cbranch_vccz .LBB2_491
	v_lshlrev_b64 v[114:115], 8, v[118:119]
	v_lshl_add_u64 v[126:127], v[160:161], 0, v[114:115]
	global_load_dwordx4 v[114:117], v[126:127], off offset:48
	global_load_dwordx4 v[238:241], v[126:127], off offset:32
	global_load_dwordx4 v[242:245], v[126:127], off offset:16
	global_load_dwordx4 v[246:249], v[126:127], off
	v_mov_b32_e32 v122, v100
	v_mov_b32_e32 v123, v108
	v_pk_mul_f32 v[122:123], v[122:123], v[120:121] op_sel_hi:[1,0]
	v_mov_b32_e32 v108, v101
	v_mov_b32_e32 v167, v1
	s_waitcnt vmcnt(0) lgkmcnt(0)
	v_pk_mul_f32 v[124:125], v[122:123], v[114:115]
	s_nop 0
	v_add_f32_e32 v0, v124, v125
	v_pk_mul_f32 v[114:115], v[122:123], v[114:115] op_sel:[1,0] op_sel_hi:[0,1]
	v_mov_b32_e32 v122, v238
	v_mov_b32_e32 v123, v239
	v_mov_b32_e32 v124, v240
	v_mov_b32_e32 v125, v241
	v_sub_f32_e32 v119, v114, v115
	v_mov_b32_e32 v114, v99
	v_mov_b32_e32 v115, v107
	v_pk_mul_f32 v[114:115], v[114:115], v[120:121] op_sel_hi:[1,0]
	v_mov_b32_e32 v99, v106
	s_waitcnt vmcnt(0) lgkmcnt(0)
	v_pk_mul_f32 v[128:129], v[114:115], v[124:125]
	s_nop 0
	v_add_f32_e32 v121, v128, v129
	v_pk_mul_f32 v[98:99], v[98:99], v[120:121] op_sel_hi:[1,0]
	v_pk_mul_f32 v[114:115], v[114:115], v[124:125] op_sel:[1,0] op_sel_hi:[0,1]
	v_pk_mul_f32 v[106:107], v[98:99], v[122:123]
	v_pk_mul_f32 v[98:99], v[98:99], v[122:123] op_sel:[1,0] op_sel_hi:[0,1]
	v_mov_b32_e32 v122, v242
	v_mov_b32_e32 v123, v243
	v_mov_b32_e32 v124, v244
	v_mov_b32_e32 v125, v245
	v_sub_f32_e32 v128, v98, v99
	v_mov_b32_e32 v98, v105
	v_mov_b32_e32 v99, v113
	v_pk_mul_f32 v[98:99], v[98:99], v[120:121] op_sel_hi:[1,0]
	v_sub_f32_e32 v114, v114, v115
	v_add_f32_e32 v115, v106, v107
	v_mov_b32_e32 v105, v112
	s_waitcnt vmcnt(0) lgkmcnt(0)
	v_pk_mul_f32 v[106:107], v[98:99], v[124:125]
	v_pk_mul_f32 v[98:99], v[98:99], v[124:125] op_sel:[1,0] op_sel_hi:[0,1]
	v_sub_f32_e32 v124, v98, v99
	v_pk_mul_f32 v[98:99], v[104:105], v[120:121] op_sel_hi:[1,0]
	v_add_f32_e32 v129, v106, v107
	v_pk_mul_f32 v[104:105], v[98:99], v[122:123]
	v_pk_mul_f32 v[98:99], v[98:99], v[122:123] op_sel:[1,0] op_sel_hi:[0,1]
	v_add_f32_e32 v125, v104, v105
	v_mov_b32_e32 v104, v246
	v_mov_b32_e32 v105, v247
	v_mov_b32_e32 v106, v248
	v_mov_b32_e32 v107, v249
	v_sub_f32_e32 v122, v98, v99
	v_mov_b32_e32 v98, v103
	v_mov_b32_e32 v99, v111
	v_pk_mul_f32 v[98:99], v[98:99], v[120:121] op_sel_hi:[1,0]
	v_mov_b32_e32 v103, v110
	s_waitcnt vmcnt(0) lgkmcnt(0)
	v_pk_mul_f32 v[112:113], v[98:99], v[106:107]
	v_pk_mul_f32 v[98:99], v[98:99], v[106:107] op_sel:[1,0] op_sel_hi:[0,1]
	v_sub_f32_e32 v106, v98, v99
	v_pk_mul_f32 v[98:99], v[102:103], v[120:121] op_sel_hi:[1,0]
	v_add_f32_e32 v111, v112, v113
	v_pk_mul_f32 v[102:103], v[98:99], v[104:105]
	v_pk_mul_f32 v[98:99], v[98:99], v[104:105] op_sel:[1,0] op_sel_hi:[0,1]
	v_add_f32_e32 v102, v102, v103
	v_sub_f32_e32 v103, v98, v99
	v_pk_mul_f32 v[98:99], v[108:109], v[120:121] op_sel_hi:[1,0]
	s_nop 0
	v_pk_mul_f32 v[100:101], v[98:99], v[116:117] op_sel:[1,0] op_sel_hi:[0,1]
	v_pk_mul_f32 v[98:99], v[98:99], v[116:117]
	v_sub_f32_e32 v101, v100, v101
	v_add_f32_e32 v105, v98, v99
	v_cvt_pk_bf16_f32 v98, v103, v106
	v_mov_b64_e32 v[106:107], s[6:7]
	v_mad_i64_i32 v[106:107], s[0:1], v118, s2, v[106:107]
	v_lshl_add_u64 v[106:107], s[16:17], 1, v[106:107]
	v_cvt_pk_bf16_f32 v99, v122, v124
	v_cvt_pk_bf16_f32 v100, v128, v114
	v_cvt_pk_bf16_f32 v101, v119, v101
	v_lshl_add_u64 v[106:107], v[106:107], 0, v[166:167]
	v_cvt_pk_bf16_f32 v102, v102, v111
	v_cvt_pk_bf16_f32 v103, v125, v129
	v_cvt_pk_bf16_f32 v104, v115, v121
	v_cvt_pk_bf16_f32 v105, v0, v105
	global_store_dwordx4 v[106:107], v[98:101], off offset:256
	global_store_dwordx4 v[106:107], v[102:105], off offset:320
.LBB2_491:
	s_nop 1
	v_or_b32_e32 v102, 32, v168
	v_ashrrev_i32_e32 v103, 31, v102
	v_lshlrev_b64 v[98:99], 6, v[102:103]
	v_lshl_add_u64 v[98:99], s[46:47], 0, v[98:99]
	s_mov_b32 s59, s17
	v_lshl_add_u64 v[104:105], v[98:99], 0, s[58:59]
	global_load_dwordx4 v[98:101], v[104:105], off
	s_nop 0
	global_load_dwordx4 v[104:107], v[104:105], off offset:16
	s_and_b64 vcc, exec, s[40:41]
	s_waitcnt vmcnt(0) lgkmcnt(0)
	v_mov_b32_e32 v108, v98
	v_mov_b32_e32 v109, v104
	v_mov_b32_e32 v104, v99
	v_mov_b32_e32 v98, v100
	v_mov_b32_e32 v99, v106
	v_mov_b32_e32 v106, v101
	v_pk_add_f32 v[100:101], v[108:109], v[104:105]
	v_pk_add_f32 v[98:99], v[98:99], v[106:107]
	s_nop 0
	v_pk_add_f32 v[98:99], v[100:101], v[98:99]
	s_nop 0
	v_add_f32_e32 v0, v98, v99
	v_fmamk_f32 v0, v0, 0x3b000000, v147
	v_mul_f32_e32 v98, 0x4b800000, v0
	v_cmp_gt_f32_e64 s[0:1], s29, v0
	s_nop 1
	v_cndmask_b32_e64 v0, v0, v98, s[0:1]
	v_rsq_f32_e32 v0, v0
	s_nop 0
	v_mul_f32_e32 v98, 0x45800000, v0
	v_cndmask_b32_e64 v104, v0, v98, s[0:1]
	s_mov_b64 s[0:1], -1
	s_cbranch_vccnz .LBB2_509
	v_mad_i64_i32 v[98:99], s[0:1], v102, s2, 0
	v_lshlrev_b64 v[100:101], 11, v[102:103]
	s_and_b64 vcc, exec, s[38:39]
	s_mov_b64 s[0:1], -1
	s_cbranch_vccnz .LBB2_498
	s_andn2_b64 vcc, exec, s[12:13]
	s_cbranch_vccnz .LBB2_495
	v_lshl_add_u64 v[106:107], s[44:45], 0, v[100:101]
	s_lshl_b32 s0, s51, 7
	s_mov_b32 s1, s17
	v_lshl_add_u64 v[108:109], s[0:1], 1, v[106:107]
	s_mov_b64 s[0:1], 0

.LBB2_500:
	v_lshlrev_b32_e32 v0, 1, v144
	v_pk_mul_f32 v[110:111], v[96:97], v[104:105] op_sel_hi:[1,0]
	v_pk_mul_f32 v[112:113], v[94:95], v[104:105] op_sel_hi:[1,0]
	v_lshl_add_u64 v[118:119], v[108:109], 0, v[0:1]
	v_cvt_pk_bf16_f32 v108, v112, v113
	v_cvt_pk_bf16_f32 v109, v110, v111
	s_and_b64 vcc, exec, s[38:39]
	s_mov_b64 s[0:1], -1
	v_pk_mul_f32 v[114:115], v[92:93], v[104:105] op_sel_hi:[1,0]
	v_pk_mul_f32 v[116:117], v[90:91], v[104:105] op_sel_hi:[1,0]
	s_nop 0
	v_cvt_pk_bf16_f32 v110, v116, v117
	v_cvt_pk_bf16_f32 v111, v114, v115
	global_store_dwordx4 v[118:119], v[108:111], off
	s_cbranch_vccnz .LBB2_506
	s_andn2_b64 vcc, exec, s[12:13]
	s_cbranch_vccnz .LBB2_503
	v_lshl_add_u64 v[100:101], s[44:45], 0, v[100:101]
	s_lshl_b32 s0, s74, 9
	s_mov_b32 s1, s17
	v_lshl_add_u64 v[100:101], v[100:101], 0, s[0:1]
	s_movk_i32 s0, 0xf900
	s_mov_b32 s1, -1
	v_lshl_add_u64 v[108:109], v[100:101], 0, s[0:1]
	s_mov_b64 s[0:1], 0

.LBB2_508:
	v_mov_b32_e32 v98, v104
	v_mov_b32_e32 v99, v104
	v_mov_b32_e32 v105, v104
	v_pk_mul_f32 v[100:101], v[88:89], v[98:99]
	v_lshl_add_u64 v[108:109], v[108:109], 0, v[0:1]
	s_mov_b64 s[0:1], 0
	v_pk_mul_f32 v[106:107], v[86:87], v[104:105]
	v_pk_mul_f32 v[110:111], v[84:85], v[98:99]
	v_pk_mul_f32 v[112:113], v[82:83], v[104:105]
	v_cvt_pk_bf16_f32 v98, v106, v107
	v_cvt_pk_bf16_f32 v99, v100, v101
	s_nop 0
	v_cvt_pk_bf16_f32 v100, v112, v113
	v_cvt_pk_bf16_f32 v101, v110, v111
	global_store_dwordx4 v[108:109], v[98:101], off
.LBB2_509:
	s_and_b64 vcc, exec, s[0:1]
	s_cbranch_vccz .LBB2_511
	v_lshlrev_b64 v[98:99], 8, v[102:103]
	v_lshl_add_u64 v[110:111], v[160:161], 0, v[98:99]
	global_load_dwordx4 v[98:101], v[110:111], off offset:48
	global_load_dwordx4 v[238:241], v[110:111], off offset:32
	global_load_dwordx4 v[242:245], v[110:111], off offset:16
	global_load_dwordx4 v[246:249], v[110:111], off
	v_mov_b32_e32 v106, v84
	v_mov_b32_e32 v107, v92
	v_pk_mul_f32 v[106:107], v[106:107], v[104:105] op_sel_hi:[1,0]
	v_mov_b32_e32 v92, v85
	v_mov_b32_e32 v167, v1
	s_waitcnt vmcnt(0) lgkmcnt(0)
	v_pk_mul_f32 v[108:109], v[106:107], v[98:99]
	s_nop 0
	v_add_f32_e32 v0, v108, v109
	v_pk_mul_f32 v[98:99], v[106:107], v[98:99] op_sel:[1,0] op_sel_hi:[0,1]
	v_mov_b32_e32 v106, v238
	v_mov_b32_e32 v107, v239
	v_mov_b32_e32 v108, v240
	v_mov_b32_e32 v109, v241
	v_sub_f32_e32 v103, v98, v99
	v_mov_b32_e32 v98, v83
	v_mov_b32_e32 v99, v91
	v_pk_mul_f32 v[98:99], v[98:99], v[104:105] op_sel_hi:[1,0]
	v_mov_b32_e32 v83, v90
	s_waitcnt vmcnt(0) lgkmcnt(0)
	v_pk_mul_f32 v[112:113], v[98:99], v[108:109]
	s_nop 0
	v_add_f32_e32 v105, v112, v113
	v_pk_mul_f32 v[82:83], v[82:83], v[104:105] op_sel_hi:[1,0]
	v_pk_mul_f32 v[98:99], v[98:99], v[108:109] op_sel:[1,0] op_sel_hi:[0,1]
	v_pk_mul_f32 v[90:91], v[82:83], v[106:107]
	v_pk_mul_f32 v[82:83], v[82:83], v[106:107] op_sel:[1,0] op_sel_hi:[0,1]
	v_mov_b32_e32 v106, v242
	v_mov_b32_e32 v107, v243
	v_mov_b32_e32 v108, v244
	v_mov_b32_e32 v109, v245
	v_sub_f32_e32 v112, v82, v83
	v_mov_b32_e32 v82, v89
	v_mov_b32_e32 v83, v97
	v_pk_mul_f32 v[82:83], v[82:83], v[104:105] op_sel_hi:[1,0]
	v_sub_f32_e32 v98, v98, v99
	v_add_f32_e32 v99, v90, v91
	v_mov_b32_e32 v89, v96
	s_waitcnt vmcnt(0) lgkmcnt(0)
	v_pk_mul_f32 v[90:91], v[82:83], v[108:109]
	v_pk_mul_f32 v[82:83], v[82:83], v[108:109] op_sel:[1,0] op_sel_hi:[0,1]
	v_sub_f32_e32 v108, v82, v83
	v_pk_mul_f32 v[82:83], v[88:89], v[104:105] op_sel_hi:[1,0]
	v_add_f32_e32 v113, v90, v91
	v_pk_mul_f32 v[88:89], v[82:83], v[106:107]
	v_pk_mul_f32 v[82:83], v[82:83], v[106:107] op_sel:[1,0] op_sel_hi:[0,1]
	v_add_f32_e32 v109, v88, v89
	v_mov_b32_e32 v88, v246
	v_mov_b32_e32 v89, v247
	v_mov_b32_e32 v90, v248
	v_mov_b32_e32 v91, v249
	v_sub_f32_e32 v106, v82, v83
	v_mov_b32_e32 v82, v87
	v_mov_b32_e32 v83, v95
	v_pk_mul_f32 v[82:83], v[82:83], v[104:105] op_sel_hi:[1,0]
	v_mov_b32_e32 v87, v94
	s_waitcnt vmcnt(0) lgkmcnt(0)
	v_pk_mul_f32 v[96:97], v[82:83], v[90:91]
	v_pk_mul_f32 v[82:83], v[82:83], v[90:91] op_sel:[1,0] op_sel_hi:[0,1]
	v_sub_f32_e32 v90, v82, v83
	v_pk_mul_f32 v[82:83], v[86:87], v[104:105] op_sel_hi:[1,0]
	v_add_f32_e32 v95, v96, v97
	v_pk_mul_f32 v[86:87], v[82:83], v[88:89]
	v_pk_mul_f32 v[82:83], v[82:83], v[88:89] op_sel:[1,0] op_sel_hi:[0,1]
	v_add_f32_e32 v86, v86, v87
	v_sub_f32_e32 v87, v82, v83
	v_pk_mul_f32 v[82:83], v[92:93], v[104:105] op_sel_hi:[1,0]
	s_nop 0
	v_pk_mul_f32 v[84:85], v[82:83], v[100:101] op_sel:[1,0] op_sel_hi:[0,1]
	v_pk_mul_f32 v[82:83], v[82:83], v[100:101]
	v_sub_f32_e32 v85, v84, v85
	v_add_f32_e32 v89, v82, v83
	v_cvt_pk_bf16_f32 v82, v87, v90
	v_mov_b64_e32 v[90:91], s[6:7]
	v_mad_i64_i32 v[90:91], s[0:1], v102, s2, v[90:91]
	v_lshl_add_u64 v[90:91], s[16:17], 1, v[90:91]
	v_cvt_pk_bf16_f32 v83, v106, v108
	v_cvt_pk_bf16_f32 v84, v112, v98
	v_cvt_pk_bf16_f32 v85, v103, v85
	v_lshl_add_u64 v[90:91], v[90:91], 0, v[166:167]
	v_cvt_pk_bf16_f32 v86, v86, v95
	v_cvt_pk_bf16_f32 v87, v109, v113
	v_cvt_pk_bf16_f32 v88, v99, v105
	v_cvt_pk_bf16_f32 v89, v0, v89
	global_store_dwordx4 v[90:91], v[82:85], off offset:256
	global_store_dwordx4 v[90:91], v[86:89], off offset:320
.LBB2_511:
	s_nop 1
	v_or_b32_e32 v86, 48, v168
	v_ashrrev_i32_e32 v87, 31, v86
	v_lshlrev_b64 v[82:83], 6, v[86:87]
	v_lshl_add_u64 v[82:83], s[46:47], 0, v[82:83]
	s_mov_b32 s59, s17
	v_lshl_add_u64 v[88:89], v[82:83], 0, s[58:59]
	global_load_dwordx4 v[82:85], v[88:89], off
	s_nop 0
	global_load_dwordx4 v[88:91], v[88:89], off offset:16
	s_and_b64 vcc, exec, s[40:41]
	s_waitcnt vmcnt(0) lgkmcnt(0)
	v_mov_b32_e32 v92, v82
	v_mov_b32_e32 v93, v88
	v_mov_b32_e32 v88, v83
	v_mov_b32_e32 v82, v84
	v_mov_b32_e32 v83, v90
	v_mov_b32_e32 v90, v85
	v_pk_add_f32 v[84:85], v[92:93], v[88:89]
	v_pk_add_f32 v[82:83], v[82:83], v[90:91]
	s_nop 0
	v_pk_add_f32 v[82:83], v[84:85], v[82:83]
	s_nop 0
	v_add_f32_e32 v0, v82, v83
	v_fmamk_f32 v0, v0, 0x3b000000, v147
	v_mul_f32_e32 v82, 0x4b800000, v0
	v_cmp_gt_f32_e64 s[0:1], s29, v0
	s_nop 1
	v_cndmask_b32_e64 v0, v0, v82, s[0:1]
	v_rsq_f32_e32 v0, v0
	s_nop 0
	v_mul_f32_e32 v82, 0x45800000, v0
	v_cndmask_b32_e64 v88, v0, v82, s[0:1]
	s_mov_b64 s[0:1], -1
	s_cbranch_vccnz .LBB2_529
	v_mad_i64_i32 v[82:83], s[0:1], v86, s2, 0
	v_lshlrev_b64 v[84:85], 11, v[86:87]
	s_and_b64 vcc, exec, s[38:39]
	s_mov_b64 s[0:1], -1
	s_cbranch_vccnz .LBB2_518
	s_andn2_b64 vcc, exec, s[12:13]
	s_cbranch_vccnz .LBB2_515
	v_lshl_add_u64 v[90:91], s[44:45], 0, v[84:85]
	s_lshl_b32 s0, s51, 7
	s_mov_b32 s1, s17
	v_lshl_add_u64 v[92:93], s[0:1], 1, v[90:91]
	s_mov_b64 s[0:1], 0

.LBB2_520:
	v_lshlrev_b32_e32 v0, 1, v144
	v_pk_mul_f32 v[94:95], v[80:81], v[88:89] op_sel_hi:[1,0]
	v_pk_mul_f32 v[96:97], v[78:79], v[88:89] op_sel_hi:[1,0]
	v_lshl_add_u64 v[102:103], v[92:93], 0, v[0:1]
	v_cvt_pk_bf16_f32 v92, v96, v97
	v_cvt_pk_bf16_f32 v93, v94, v95
	s_and_b64 vcc, exec, s[38:39]
	s_mov_b64 s[0:1], -1
	v_pk_mul_f32 v[98:99], v[76:77], v[88:89] op_sel_hi:[1,0]
	v_pk_mul_f32 v[100:101], v[74:75], v[88:89] op_sel_hi:[1,0]
	s_nop 0
	v_cvt_pk_bf16_f32 v94, v100, v101
	v_cvt_pk_bf16_f32 v95, v98, v99
	global_store_dwordx4 v[102:103], v[92:95], off
	s_cbranch_vccnz .LBB2_526
	s_andn2_b64 vcc, exec, s[12:13]
	s_cbranch_vccnz .LBB2_523
	v_lshl_add_u64 v[84:85], s[44:45], 0, v[84:85]
	s_lshl_b32 s0, s74, 9
	s_mov_b32 s1, s17
	v_lshl_add_u64 v[84:85], v[84:85], 0, s[0:1]
	s_movk_i32 s0, 0xf900
	s_mov_b32 s1, -1
	v_lshl_add_u64 v[92:93], v[84:85], 0, s[0:1]
	s_mov_b64 s[0:1], 0

.LBB2_528:
	v_mov_b32_e32 v82, v88
	v_mov_b32_e32 v83, v88
	v_mov_b32_e32 v89, v88
	v_pk_mul_f32 v[84:85], v[72:73], v[82:83]
	v_lshl_add_u64 v[92:93], v[92:93], 0, v[0:1]
	s_mov_b64 s[0:1], 0
	v_pk_mul_f32 v[90:91], v[70:71], v[88:89]
	v_pk_mul_f32 v[94:95], v[68:69], v[82:83]
	v_pk_mul_f32 v[96:97], v[66:67], v[88:89]
	v_cvt_pk_bf16_f32 v82, v90, v91
	v_cvt_pk_bf16_f32 v83, v84, v85
	s_nop 0
	v_cvt_pk_bf16_f32 v84, v96, v97
	v_cvt_pk_bf16_f32 v85, v94, v95
	global_store_dwordx4 v[92:93], v[82:85], off
.LBB2_529:
	s_and_b64 vcc, exec, s[0:1]
	s_cbranch_vccz .LBB2_531
	v_lshlrev_b64 v[82:83], 8, v[86:87]
	v_lshl_add_u64 v[94:95], v[160:161], 0, v[82:83]
	global_load_dwordx4 v[82:85], v[94:95], off offset:48
	global_load_dwordx4 v[238:241], v[94:95], off offset:32
	global_load_dwordx4 v[242:245], v[94:95], off offset:16
	global_load_dwordx4 v[246:249], v[94:95], off
	v_mov_b32_e32 v90, v68
	v_mov_b32_e32 v91, v76
	v_pk_mul_f32 v[90:91], v[90:91], v[88:89] op_sel_hi:[1,0]
	v_mov_b32_e32 v76, v69
	v_mov_b32_e32 v167, v1
	s_waitcnt vmcnt(0) lgkmcnt(0)
	v_pk_mul_f32 v[92:93], v[90:91], v[82:83]
	s_nop 0
	v_add_f32_e32 v0, v92, v93
	v_pk_mul_f32 v[82:83], v[90:91], v[82:83] op_sel:[1,0] op_sel_hi:[0,1]
	v_mov_b32_e32 v90, v238
	v_mov_b32_e32 v91, v239
	v_mov_b32_e32 v92, v240
	v_mov_b32_e32 v93, v241
	v_sub_f32_e32 v87, v82, v83
	v_mov_b32_e32 v82, v67
	v_mov_b32_e32 v83, v75
	v_pk_mul_f32 v[82:83], v[82:83], v[88:89] op_sel_hi:[1,0]
	v_mov_b32_e32 v67, v74
	s_waitcnt vmcnt(0) lgkmcnt(0)
	v_pk_mul_f32 v[96:97], v[82:83], v[92:93]
	s_nop 0
	v_add_f32_e32 v89, v96, v97
	v_pk_mul_f32 v[66:67], v[66:67], v[88:89] op_sel_hi:[1,0]
	v_pk_mul_f32 v[82:83], v[82:83], v[92:93] op_sel:[1,0] op_sel_hi:[0,1]
	v_pk_mul_f32 v[74:75], v[66:67], v[90:91]
	v_pk_mul_f32 v[66:67], v[66:67], v[90:91] op_sel:[1,0] op_sel_hi:[0,1]
	v_mov_b32_e32 v90, v242
	v_mov_b32_e32 v91, v243
	v_mov_b32_e32 v92, v244
	v_mov_b32_e32 v93, v245
	v_sub_f32_e32 v96, v66, v67
	v_mov_b32_e32 v66, v73
	v_mov_b32_e32 v67, v81
	v_pk_mul_f32 v[66:67], v[66:67], v[88:89] op_sel_hi:[1,0]
	v_sub_f32_e32 v82, v82, v83
	v_add_f32_e32 v83, v74, v75
	v_mov_b32_e32 v73, v80
	s_waitcnt vmcnt(0) lgkmcnt(0)
	v_pk_mul_f32 v[74:75], v[66:67], v[92:93]
	v_pk_mul_f32 v[66:67], v[66:67], v[92:93] op_sel:[1,0] op_sel_hi:[0,1]
	v_sub_f32_e32 v92, v66, v67
	v_pk_mul_f32 v[66:67], v[72:73], v[88:89] op_sel_hi:[1,0]
	v_add_f32_e32 v97, v74, v75
	v_pk_mul_f32 v[72:73], v[66:67], v[90:91]
	v_pk_mul_f32 v[66:67], v[66:67], v[90:91] op_sel:[1,0] op_sel_hi:[0,1]
	v_add_f32_e32 v93, v72, v73
	v_mov_b32_e32 v72, v246
	v_mov_b32_e32 v73, v247
	v_mov_b32_e32 v74, v248
	v_mov_b32_e32 v75, v249
	v_sub_f32_e32 v90, v66, v67
	v_mov_b32_e32 v66, v71
	v_mov_b32_e32 v67, v79
	v_pk_mul_f32 v[66:67], v[66:67], v[88:89] op_sel_hi:[1,0]
	v_mov_b32_e32 v71, v78
	s_waitcnt vmcnt(0) lgkmcnt(0)
	v_pk_mul_f32 v[80:81], v[66:67], v[74:75]
	v_pk_mul_f32 v[66:67], v[66:67], v[74:75] op_sel:[1,0] op_sel_hi:[0,1]
	v_sub_f32_e32 v74, v66, v67
	v_pk_mul_f32 v[66:67], v[70:71], v[88:89] op_sel_hi:[1,0]
	v_add_f32_e32 v79, v80, v81
	v_pk_mul_f32 v[70:71], v[66:67], v[72:73]
	v_pk_mul_f32 v[66:67], v[66:67], v[72:73] op_sel:[1,0] op_sel_hi:[0,1]
	v_add_f32_e32 v70, v70, v71
	v_sub_f32_e32 v71, v66, v67
	v_pk_mul_f32 v[66:67], v[76:77], v[88:89] op_sel_hi:[1,0]
	s_nop 0
	v_pk_mul_f32 v[68:69], v[66:67], v[84:85] op_sel:[1,0] op_sel_hi:[0,1]
	v_pk_mul_f32 v[66:67], v[66:67], v[84:85]
	v_sub_f32_e32 v69, v68, v69
	v_add_f32_e32 v73, v66, v67
	v_cvt_pk_bf16_f32 v66, v71, v74
	v_mov_b64_e32 v[74:75], s[6:7]
	v_mad_i64_i32 v[74:75], s[0:1], v86, s2, v[74:75]
	v_lshl_add_u64 v[74:75], s[16:17], 1, v[74:75]
	v_cvt_pk_bf16_f32 v67, v90, v92
	v_cvt_pk_bf16_f32 v68, v96, v82
	v_cvt_pk_bf16_f32 v69, v87, v69
	v_lshl_add_u64 v[74:75], v[74:75], 0, v[166:167]
	v_cvt_pk_bf16_f32 v70, v70, v79
	v_cvt_pk_bf16_f32 v71, v93, v97
	v_cvt_pk_bf16_f32 v72, v83, v89
	v_cvt_pk_bf16_f32 v73, v0, v73
	global_store_dwordx4 v[74:75], v[66:69], off offset:256
	global_store_dwordx4 v[74:75], v[70:73], off offset:320
.LBB2_531:
	s_nop 1
	v_add_u32_e32 v70, 0x80, v168
	v_ashrrev_i32_e32 v71, 31, v70
	v_lshlrev_b64 v[66:67], 6, v[70:71]
	v_lshl_add_u64 v[66:67], s[46:47], 0, v[66:67]
	s_mov_b32 s59, s17
	v_lshl_add_u64 v[72:73], v[66:67], 0, s[58:59]
	global_load_dwordx4 v[66:69], v[72:73], off
	s_nop 0
	global_load_dwordx4 v[72:75], v[72:73], off offset:16
	s_and_b64 vcc, exec, s[40:41]
	s_waitcnt vmcnt(0) lgkmcnt(0)
	v_mov_b32_e32 v76, v66
	v_mov_b32_e32 v77, v72
	v_mov_b32_e32 v72, v67
	v_mov_b32_e32 v66, v68
	v_mov_b32_e32 v67, v74
	v_mov_b32_e32 v74, v69
	v_pk_add_f32 v[68:69], v[76:77], v[72:73]
	v_pk_add_f32 v[66:67], v[66:67], v[74:75]
	s_nop 0
	v_pk_add_f32 v[66:67], v[68:69], v[66:67]
	s_nop 0
	v_add_f32_e32 v0, v66, v67
	v_fmamk_f32 v0, v0, 0x3b000000, v147
	v_mul_f32_e32 v66, 0x4b800000, v0
	v_cmp_gt_f32_e64 s[0:1], s29, v0
	s_nop 1
	v_cndmask_b32_e64 v0, v0, v66, s[0:1]
	v_rsq_f32_e32 v0, v0
	s_nop 0
	v_mul_f32_e32 v66, 0x45800000, v0
	v_cndmask_b32_e64 v72, v0, v66, s[0:1]
	s_mov_b64 s[0:1], -1
	s_cbranch_vccnz .LBB2_549
	v_mad_i64_i32 v[66:67], s[0:1], v70, s2, 0
	v_lshlrev_b64 v[68:69], 11, v[70:71]
	s_and_b64 vcc, exec, s[38:39]
	s_mov_b64 s[0:1], -1
	s_cbranch_vccnz .LBB2_538
	s_andn2_b64 vcc, exec, s[12:13]
	s_cbranch_vccnz .LBB2_535
	v_lshl_add_u64 v[74:75], s[44:45], 0, v[68:69]
	s_lshl_b32 s0, s51, 7
	s_mov_b32 s1, s17
	v_lshl_add_u64 v[76:77], s[0:1], 1, v[74:75]
	s_mov_b64 s[0:1], 0

.LBB2_540:
	v_lshlrev_b32_e32 v0, 1, v144
	v_pk_mul_f32 v[78:79], v[64:65], v[72:73] op_sel_hi:[1,0]
	v_pk_mul_f32 v[80:81], v[62:63], v[72:73] op_sel_hi:[1,0]
	v_lshl_add_u64 v[86:87], v[76:77], 0, v[0:1]
	v_cvt_pk_bf16_f32 v76, v80, v81
	v_cvt_pk_bf16_f32 v77, v78, v79
	s_and_b64 vcc, exec, s[38:39]
	s_mov_b64 s[0:1], -1
	v_pk_mul_f32 v[82:83], v[60:61], v[72:73] op_sel_hi:[1,0]
	v_pk_mul_f32 v[84:85], v[58:59], v[72:73] op_sel_hi:[1,0]
	s_nop 0
	v_cvt_pk_bf16_f32 v78, v84, v85
	v_cvt_pk_bf16_f32 v79, v82, v83
	global_store_dwordx4 v[86:87], v[76:79], off
	s_cbranch_vccnz .LBB2_546
	s_andn2_b64 vcc, exec, s[12:13]
	s_cbranch_vccnz .LBB2_543
	v_lshl_add_u64 v[68:69], s[44:45], 0, v[68:69]
	s_lshl_b32 s0, s74, 9
	s_mov_b32 s1, s17
	v_lshl_add_u64 v[68:69], v[68:69], 0, s[0:1]
	s_movk_i32 s0, 0xf900
	s_mov_b32 s1, -1
	v_lshl_add_u64 v[76:77], v[68:69], 0, s[0:1]
	s_mov_b64 s[0:1], 0

.LBB2_548:
	v_mov_b32_e32 v66, v72
	v_mov_b32_e32 v67, v72
	v_mov_b32_e32 v73, v72
	v_pk_mul_f32 v[68:69], v[56:57], v[66:67]
	v_lshl_add_u64 v[76:77], v[76:77], 0, v[0:1]
	s_mov_b64 s[0:1], 0
	v_pk_mul_f32 v[74:75], v[54:55], v[72:73]
	v_pk_mul_f32 v[78:79], v[52:53], v[66:67]
	v_pk_mul_f32 v[80:81], v[50:51], v[72:73]
	v_cvt_pk_bf16_f32 v66, v74, v75
	v_cvt_pk_bf16_f32 v67, v68, v69
	s_nop 0
	v_cvt_pk_bf16_f32 v68, v80, v81
	v_cvt_pk_bf16_f32 v69, v78, v79
	global_store_dwordx4 v[76:77], v[66:69], off
.LBB2_549:
	s_and_b64 vcc, exec, s[0:1]
	s_cbranch_vccz .LBB2_551
	v_lshlrev_b64 v[66:67], 8, v[70:71]
	v_lshl_add_u64 v[78:79], v[160:161], 0, v[66:67]
	global_load_dwordx4 v[66:69], v[78:79], off offset:48
	global_load_dwordx4 v[238:241], v[78:79], off offset:32
	global_load_dwordx4 v[242:245], v[78:79], off offset:16
	global_load_dwordx4 v[246:249], v[78:79], off
	v_mov_b32_e32 v74, v52
	v_mov_b32_e32 v75, v60
	v_pk_mul_f32 v[74:75], v[74:75], v[72:73] op_sel_hi:[1,0]
	v_mov_b32_e32 v60, v53
	v_mov_b32_e32 v167, v1
	s_waitcnt vmcnt(0) lgkmcnt(0)
	v_pk_mul_f32 v[76:77], v[74:75], v[66:67]
	s_nop 0
	v_add_f32_e32 v0, v76, v77
	v_pk_mul_f32 v[66:67], v[74:75], v[66:67] op_sel:[1,0] op_sel_hi:[0,1]
	v_mov_b32_e32 v74, v238
	v_mov_b32_e32 v75, v239
	v_mov_b32_e32 v76, v240
	v_mov_b32_e32 v77, v241
	v_sub_f32_e32 v71, v66, v67
	v_mov_b32_e32 v66, v51
	v_mov_b32_e32 v67, v59
	v_pk_mul_f32 v[66:67], v[66:67], v[72:73] op_sel_hi:[1,0]
	v_mov_b32_e32 v51, v58
	s_waitcnt vmcnt(0) lgkmcnt(0)
	v_pk_mul_f32 v[80:81], v[66:67], v[76:77]
	s_nop 0
	v_add_f32_e32 v73, v80, v81
	v_pk_mul_f32 v[50:51], v[50:51], v[72:73] op_sel_hi:[1,0]
	v_pk_mul_f32 v[66:67], v[66:67], v[76:77] op_sel:[1,0] op_sel_hi:[0,1]
	v_pk_mul_f32 v[58:59], v[50:51], v[74:75]
	v_pk_mul_f32 v[50:51], v[50:51], v[74:75] op_sel:[1,0] op_sel_hi:[0,1]
	v_mov_b32_e32 v74, v242
	v_mov_b32_e32 v75, v243
	v_mov_b32_e32 v76, v244
	v_mov_b32_e32 v77, v245
	v_sub_f32_e32 v80, v50, v51
	v_mov_b32_e32 v50, v57
	v_mov_b32_e32 v51, v65
	v_pk_mul_f32 v[50:51], v[50:51], v[72:73] op_sel_hi:[1,0]
	v_sub_f32_e32 v66, v66, v67
	v_add_f32_e32 v67, v58, v59
	v_mov_b32_e32 v57, v64
	s_waitcnt vmcnt(0) lgkmcnt(0)
	v_pk_mul_f32 v[58:59], v[50:51], v[76:77]
	v_pk_mul_f32 v[50:51], v[50:51], v[76:77] op_sel:[1,0] op_sel_hi:[0,1]
	v_sub_f32_e32 v76, v50, v51
	v_pk_mul_f32 v[50:51], v[56:57], v[72:73] op_sel_hi:[1,0]
	v_add_f32_e32 v81, v58, v59
	v_pk_mul_f32 v[56:57], v[50:51], v[74:75]
	v_pk_mul_f32 v[50:51], v[50:51], v[74:75] op_sel:[1,0] op_sel_hi:[0,1]
	v_add_f32_e32 v77, v56, v57
	v_mov_b32_e32 v56, v246
	v_mov_b32_e32 v57, v247
	v_mov_b32_e32 v58, v248
	v_mov_b32_e32 v59, v249
	v_sub_f32_e32 v74, v50, v51
	v_mov_b32_e32 v50, v55
	v_mov_b32_e32 v51, v63
	v_pk_mul_f32 v[50:51], v[50:51], v[72:73] op_sel_hi:[1,0]
	v_mov_b32_e32 v55, v62
	s_waitcnt vmcnt(0) lgkmcnt(0)
	v_pk_mul_f32 v[64:65], v[50:51], v[58:59]
	v_pk_mul_f32 v[50:51], v[50:51], v[58:59] op_sel:[1,0] op_sel_hi:[0,1]
	v_sub_f32_e32 v58, v50, v51
	v_pk_mul_f32 v[50:51], v[54:55], v[72:73] op_sel_hi:[1,0]
	v_add_f32_e32 v63, v64, v65
	v_pk_mul_f32 v[54:55], v[50:51], v[56:57]
	v_pk_mul_f32 v[50:51], v[50:51], v[56:57] op_sel:[1,0] op_sel_hi:[0,1]
	v_add_f32_e32 v54, v54, v55
	v_sub_f32_e32 v55, v50, v51
	v_pk_mul_f32 v[50:51], v[60:61], v[72:73] op_sel_hi:[1,0]
	s_nop 0
	v_pk_mul_f32 v[52:53], v[50:51], v[68:69] op_sel:[1,0] op_sel_hi:[0,1]
	v_pk_mul_f32 v[50:51], v[50:51], v[68:69]
	v_sub_f32_e32 v53, v52, v53
	v_add_f32_e32 v57, v50, v51
	v_cvt_pk_bf16_f32 v50, v55, v58
	v_mov_b64_e32 v[58:59], s[6:7]
	v_mad_i64_i32 v[58:59], s[0:1], v70, s2, v[58:59]
	v_lshl_add_u64 v[58:59], s[16:17], 1, v[58:59]
	v_cvt_pk_bf16_f32 v51, v74, v76
	v_cvt_pk_bf16_f32 v52, v80, v66
	v_cvt_pk_bf16_f32 v53, v71, v53
	v_lshl_add_u64 v[58:59], v[58:59], 0, v[166:167]
	v_cvt_pk_bf16_f32 v54, v54, v63
	v_cvt_pk_bf16_f32 v55, v77, v81
	v_cvt_pk_bf16_f32 v56, v67, v73
	v_cvt_pk_bf16_f32 v57, v0, v57
	global_store_dwordx4 v[58:59], v[50:53], off offset:256
	global_store_dwordx4 v[58:59], v[54:57], off offset:320
.LBB2_551:
	s_nop 1
	v_add_u32_e32 v54, 0x90, v168
	v_ashrrev_i32_e32 v55, 31, v54
	v_lshlrev_b64 v[50:51], 6, v[54:55]
	v_lshl_add_u64 v[50:51], s[46:47], 0, v[50:51]
	s_mov_b32 s59, s17
	v_lshl_add_u64 v[56:57], v[50:51], 0, s[58:59]
	global_load_dwordx4 v[50:53], v[56:57], off
	s_nop 0
	global_load_dwordx4 v[56:59], v[56:57], off offset:16
	s_and_b64 vcc, exec, s[40:41]
	s_waitcnt vmcnt(0) lgkmcnt(0)
	v_mov_b32_e32 v60, v50
	v_mov_b32_e32 v61, v56
	v_mov_b32_e32 v56, v51
	v_mov_b32_e32 v50, v52
	v_mov_b32_e32 v51, v58
	v_mov_b32_e32 v58, v53
	v_pk_add_f32 v[52:53], v[60:61], v[56:57]
	v_pk_add_f32 v[50:51], v[50:51], v[58:59]
	s_nop 0
	v_pk_add_f32 v[50:51], v[52:53], v[50:51]
	s_nop 0
	v_add_f32_e32 v0, v50, v51
	v_fmamk_f32 v0, v0, 0x3b000000, v147
	v_mul_f32_e32 v50, 0x4b800000, v0
	v_cmp_gt_f32_e64 s[0:1], s29, v0
	s_nop 1
	v_cndmask_b32_e64 v0, v0, v50, s[0:1]
	v_rsq_f32_e32 v0, v0
	s_nop 0
	v_mul_f32_e32 v50, 0x45800000, v0
	v_cndmask_b32_e64 v56, v0, v50, s[0:1]
	s_mov_b64 s[0:1], -1
	s_cbranch_vccnz .LBB2_569
	v_mad_i64_i32 v[50:51], s[0:1], v54, s2, 0
	v_lshlrev_b64 v[52:53], 11, v[54:55]
	s_and_b64 vcc, exec, s[38:39]
	s_mov_b64 s[0:1], -1
	s_cbranch_vccnz .LBB2_558
	s_andn2_b64 vcc, exec, s[12:13]
	s_cbranch_vccnz .LBB2_555
	v_lshl_add_u64 v[58:59], s[44:45], 0, v[52:53]
	s_lshl_b32 s0, s51, 7
	s_mov_b32 s1, s17
	v_lshl_add_u64 v[60:61], s[0:1], 1, v[58:59]
	s_mov_b64 s[0:1], 0

.LBB2_560:
	v_lshlrev_b32_e32 v0, 1, v144
	v_pk_mul_f32 v[62:63], v[48:49], v[56:57] op_sel_hi:[1,0]
	v_pk_mul_f32 v[64:65], v[46:47], v[56:57] op_sel_hi:[1,0]
	v_lshl_add_u64 v[70:71], v[60:61], 0, v[0:1]
	v_cvt_pk_bf16_f32 v60, v64, v65
	v_cvt_pk_bf16_f32 v61, v62, v63
	s_and_b64 vcc, exec, s[38:39]
	s_mov_b64 s[0:1], -1
	v_pk_mul_f32 v[66:67], v[44:45], v[56:57] op_sel_hi:[1,0]
	v_pk_mul_f32 v[68:69], v[42:43], v[56:57] op_sel_hi:[1,0]
	s_nop 0
	v_cvt_pk_bf16_f32 v62, v68, v69
	v_cvt_pk_bf16_f32 v63, v66, v67
	global_store_dwordx4 v[70:71], v[60:63], off
	s_cbranch_vccnz .LBB2_566
	s_andn2_b64 vcc, exec, s[12:13]
	s_cbranch_vccnz .LBB2_563
	v_lshl_add_u64 v[52:53], s[44:45], 0, v[52:53]
	s_lshl_b32 s0, s74, 9
	s_mov_b32 s1, s17
	v_lshl_add_u64 v[52:53], v[52:53], 0, s[0:1]
	s_movk_i32 s0, 0xf900
	s_mov_b32 s1, -1
	v_lshl_add_u64 v[60:61], v[52:53], 0, s[0:1]
	s_mov_b64 s[0:1], 0

.LBB2_568:
	v_mov_b32_e32 v50, v56
	v_mov_b32_e32 v51, v56
	v_mov_b32_e32 v57, v56
	v_pk_mul_f32 v[52:53], v[40:41], v[50:51]
	v_lshl_add_u64 v[60:61], v[60:61], 0, v[0:1]
	s_mov_b64 s[0:1], 0
	v_pk_mul_f32 v[58:59], v[38:39], v[56:57]
	v_pk_mul_f32 v[62:63], v[36:37], v[50:51]
	v_pk_mul_f32 v[64:65], v[34:35], v[56:57]
	v_cvt_pk_bf16_f32 v50, v58, v59
	v_cvt_pk_bf16_f32 v51, v52, v53
	s_nop 0
	v_cvt_pk_bf16_f32 v52, v64, v65
	v_cvt_pk_bf16_f32 v53, v62, v63
	global_store_dwordx4 v[60:61], v[50:53], off
.LBB2_569:
	s_and_b64 vcc, exec, s[0:1]
	s_cbranch_vccz .LBB2_571
	v_lshlrev_b64 v[50:51], 8, v[54:55]
	v_lshl_add_u64 v[62:63], v[160:161], 0, v[50:51]
	global_load_dwordx4 v[50:53], v[62:63], off offset:48
	global_load_dwordx4 v[238:241], v[62:63], off offset:32
	global_load_dwordx4 v[242:245], v[62:63], off offset:16
	global_load_dwordx4 v[246:249], v[62:63], off
	v_mov_b32_e32 v58, v36
	v_mov_b32_e32 v59, v44
	v_pk_mul_f32 v[58:59], v[58:59], v[56:57] op_sel_hi:[1,0]
	v_mov_b32_e32 v44, v37
	v_mov_b32_e32 v167, v1
	s_waitcnt vmcnt(0) lgkmcnt(0)
	v_pk_mul_f32 v[60:61], v[58:59], v[50:51]
	s_nop 0
	v_add_f32_e32 v0, v60, v61
	v_pk_mul_f32 v[50:51], v[58:59], v[50:51] op_sel:[1,0] op_sel_hi:[0,1]
	v_mov_b32_e32 v58, v238
	v_mov_b32_e32 v59, v239
	v_mov_b32_e32 v60, v240
	v_mov_b32_e32 v61, v241
	v_sub_f32_e32 v55, v50, v51
	v_mov_b32_e32 v50, v35
	v_mov_b32_e32 v51, v43
	v_pk_mul_f32 v[50:51], v[50:51], v[56:57] op_sel_hi:[1,0]
	v_mov_b32_e32 v35, v42
	s_waitcnt vmcnt(0) lgkmcnt(0)
	v_pk_mul_f32 v[64:65], v[50:51], v[60:61]
	s_nop 0
	v_add_f32_e32 v57, v64, v65
	v_pk_mul_f32 v[34:35], v[34:35], v[56:57] op_sel_hi:[1,0]
	v_pk_mul_f32 v[50:51], v[50:51], v[60:61] op_sel:[1,0] op_sel_hi:[0,1]
	v_pk_mul_f32 v[42:43], v[34:35], v[58:59]
	v_pk_mul_f32 v[34:35], v[34:35], v[58:59] op_sel:[1,0] op_sel_hi:[0,1]
	v_mov_b32_e32 v58, v242
	v_mov_b32_e32 v59, v243
	v_mov_b32_e32 v60, v244
	v_mov_b32_e32 v61, v245
	v_sub_f32_e32 v64, v34, v35
	v_mov_b32_e32 v34, v41
	v_mov_b32_e32 v35, v49
	v_pk_mul_f32 v[34:35], v[34:35], v[56:57] op_sel_hi:[1,0]
	v_sub_f32_e32 v50, v50, v51
	v_add_f32_e32 v51, v42, v43
	v_mov_b32_e32 v41, v48
	s_waitcnt vmcnt(0) lgkmcnt(0)
	v_pk_mul_f32 v[42:43], v[34:35], v[60:61]
	v_pk_mul_f32 v[34:35], v[34:35], v[60:61] op_sel:[1,0] op_sel_hi:[0,1]
	v_sub_f32_e32 v60, v34, v35
	v_pk_mul_f32 v[34:35], v[40:41], v[56:57] op_sel_hi:[1,0]
	v_add_f32_e32 v65, v42, v43
	v_pk_mul_f32 v[40:41], v[34:35], v[58:59]
	v_pk_mul_f32 v[34:35], v[34:35], v[58:59] op_sel:[1,0] op_sel_hi:[0,1]
	v_add_f32_e32 v61, v40, v41
	v_mov_b32_e32 v40, v246
	v_mov_b32_e32 v41, v247
	v_mov_b32_e32 v42, v248
	v_mov_b32_e32 v43, v249
	v_sub_f32_e32 v58, v34, v35
	v_mov_b32_e32 v34, v39
	v_mov_b32_e32 v35, v47
	v_pk_mul_f32 v[34:35], v[34:35], v[56:57] op_sel_hi:[1,0]
	v_mov_b32_e32 v39, v46
	s_waitcnt vmcnt(0) lgkmcnt(0)
	v_pk_mul_f32 v[48:49], v[34:35], v[42:43]
	v_pk_mul_f32 v[34:35], v[34:35], v[42:43] op_sel:[1,0] op_sel_hi:[0,1]
	v_sub_f32_e32 v42, v34, v35
	v_pk_mul_f32 v[34:35], v[38:39], v[56:57] op_sel_hi:[1,0]
	v_add_f32_e32 v47, v48, v49
	v_pk_mul_f32 v[38:39], v[34:35], v[40:41]
	v_pk_mul_f32 v[34:35], v[34:35], v[40:41] op_sel:[1,0] op_sel_hi:[0,1]
	v_add_f32_e32 v38, v38, v39
	v_sub_f32_e32 v39, v34, v35
	v_pk_mul_f32 v[34:35], v[44:45], v[56:57] op_sel_hi:[1,0]
	s_nop 0
	v_pk_mul_f32 v[36:37], v[34:35], v[52:53] op_sel:[1,0] op_sel_hi:[0,1]
	v_pk_mul_f32 v[34:35], v[34:35], v[52:53]
	v_sub_f32_e32 v37, v36, v37
	v_add_f32_e32 v41, v34, v35
	v_cvt_pk_bf16_f32 v34, v39, v42
	v_mov_b64_e32 v[42:43], s[6:7]
	v_mad_i64_i32 v[42:43], s[0:1], v54, s2, v[42:43]
	v_lshl_add_u64 v[42:43], s[16:17], 1, v[42:43]
	v_cvt_pk_bf16_f32 v35, v58, v60
	v_cvt_pk_bf16_f32 v36, v64, v50
	v_cvt_pk_bf16_f32 v37, v55, v37
	v_lshl_add_u64 v[42:43], v[42:43], 0, v[166:167]
	v_cvt_pk_bf16_f32 v38, v38, v47
	v_cvt_pk_bf16_f32 v39, v61, v65
	v_cvt_pk_bf16_f32 v40, v51, v57
	v_cvt_pk_bf16_f32 v41, v0, v41
	global_store_dwordx4 v[42:43], v[34:37], off offset:256
	global_store_dwordx4 v[42:43], v[38:41], off offset:320
.LBB2_571:
	s_nop 1
	v_add_u32_e32 v38, 0xa0, v168
	v_ashrrev_i32_e32 v39, 31, v38
	v_lshlrev_b64 v[34:35], 6, v[38:39]
	v_lshl_add_u64 v[34:35], s[46:47], 0, v[34:35]
	s_mov_b32 s59, s17
	v_lshl_add_u64 v[40:41], v[34:35], 0, s[58:59]
	global_load_dwordx4 v[34:37], v[40:41], off
	s_nop 0
	global_load_dwordx4 v[40:43], v[40:41], off offset:16
	s_and_b64 vcc, exec, s[40:41]
	s_waitcnt vmcnt(0) lgkmcnt(0)
	v_mov_b32_e32 v44, v34
	v_mov_b32_e32 v45, v40
	v_mov_b32_e32 v40, v35
	v_mov_b32_e32 v34, v36
	v_mov_b32_e32 v35, v42
	v_mov_b32_e32 v42, v37
	v_pk_add_f32 v[36:37], v[44:45], v[40:41]
	v_pk_add_f32 v[34:35], v[34:35], v[42:43]
	s_nop 0
	v_pk_add_f32 v[34:35], v[36:37], v[34:35]
	s_nop 0
	v_add_f32_e32 v0, v34, v35
	v_fmamk_f32 v0, v0, 0x3b000000, v147
	v_mul_f32_e32 v34, 0x4b800000, v0
	v_cmp_gt_f32_e64 s[0:1], s29, v0
	s_nop 1
	v_cndmask_b32_e64 v0, v0, v34, s[0:1]
	v_rsq_f32_e32 v0, v0
	s_nop 0
	v_mul_f32_e32 v34, 0x45800000, v0
	v_cndmask_b32_e64 v40, v0, v34, s[0:1]
	s_mov_b64 s[0:1], -1
	s_cbranch_vccnz .LBB2_589
	v_mad_i64_i32 v[34:35], s[0:1], v38, s2, 0
	v_lshlrev_b64 v[36:37], 11, v[38:39]
	s_and_b64 vcc, exec, s[38:39]
	s_mov_b64 s[0:1], -1
	s_cbranch_vccnz .LBB2_578
	s_andn2_b64 vcc, exec, s[12:13]
	s_cbranch_vccnz .LBB2_575
	v_lshl_add_u64 v[42:43], s[44:45], 0, v[36:37]
	s_lshl_b32 s0, s51, 7
	s_mov_b32 s1, s17
	v_lshl_add_u64 v[44:45], s[0:1], 1, v[42:43]
	s_mov_b64 s[0:1], 0

.LBB2_580:
	v_lshlrev_b32_e32 v0, 1, v144
	v_pk_mul_f32 v[46:47], v[32:33], v[40:41] op_sel_hi:[1,0]
	v_pk_mul_f32 v[48:49], v[30:31], v[40:41] op_sel_hi:[1,0]
	v_lshl_add_u64 v[54:55], v[44:45], 0, v[0:1]
	v_cvt_pk_bf16_f32 v44, v48, v49
	v_cvt_pk_bf16_f32 v45, v46, v47
	s_and_b64 vcc, exec, s[38:39]
	s_mov_b64 s[0:1], -1
	v_pk_mul_f32 v[50:51], v[28:29], v[40:41] op_sel_hi:[1,0]
	v_pk_mul_f32 v[52:53], v[26:27], v[40:41] op_sel_hi:[1,0]
	s_nop 0
	v_cvt_pk_bf16_f32 v46, v52, v53
	v_cvt_pk_bf16_f32 v47, v50, v51
	global_store_dwordx4 v[54:55], v[44:47], off
	s_cbranch_vccnz .LBB2_586
	s_andn2_b64 vcc, exec, s[12:13]
	s_cbranch_vccnz .LBB2_583
	v_lshl_add_u64 v[36:37], s[44:45], 0, v[36:37]
	s_lshl_b32 s0, s74, 9
	s_mov_b32 s1, s17
	v_lshl_add_u64 v[36:37], v[36:37], 0, s[0:1]
	s_movk_i32 s0, 0xf900
	s_mov_b32 s1, -1
	v_lshl_add_u64 v[44:45], v[36:37], 0, s[0:1]
	s_mov_b64 s[0:1], 0

.LBB2_588:
	v_mov_b32_e32 v34, v40
	v_mov_b32_e32 v35, v40
	v_mov_b32_e32 v41, v40
	v_pk_mul_f32 v[36:37], v[24:25], v[34:35]
	v_lshl_add_u64 v[44:45], v[44:45], 0, v[0:1]
	s_mov_b64 s[0:1], 0
	v_pk_mul_f32 v[42:43], v[22:23], v[40:41]
	v_pk_mul_f32 v[46:47], v[20:21], v[34:35]
	v_pk_mul_f32 v[48:49], v[18:19], v[40:41]
	v_cvt_pk_bf16_f32 v34, v42, v43
	v_cvt_pk_bf16_f32 v35, v36, v37
	s_nop 0
	v_cvt_pk_bf16_f32 v36, v48, v49
	v_cvt_pk_bf16_f32 v37, v46, v47
	global_store_dwordx4 v[44:45], v[34:37], off
.LBB2_589:
	s_and_b64 vcc, exec, s[0:1]
	s_cbranch_vccz .LBB2_591
	v_lshlrev_b64 v[34:35], 8, v[38:39]
	v_lshl_add_u64 v[46:47], v[160:161], 0, v[34:35]
	global_load_dwordx4 v[34:37], v[46:47], off offset:48
	global_load_dwordx4 v[238:241], v[46:47], off offset:32
	global_load_dwordx4 v[242:245], v[46:47], off offset:16
	global_load_dwordx4 v[246:249], v[46:47], off
	v_mov_b32_e32 v42, v20
	v_mov_b32_e32 v43, v28
	v_pk_mul_f32 v[42:43], v[42:43], v[40:41] op_sel_hi:[1,0]
	v_mov_b32_e32 v28, v21
	v_mov_b32_e32 v167, v1
	s_waitcnt vmcnt(0) lgkmcnt(0)
	v_pk_mul_f32 v[44:45], v[42:43], v[34:35]
	s_nop 0
	v_add_f32_e32 v0, v44, v45
	v_pk_mul_f32 v[34:35], v[42:43], v[34:35] op_sel:[1,0] op_sel_hi:[0,1]
	v_mov_b32_e32 v42, v238
	v_mov_b32_e32 v43, v239
	v_mov_b32_e32 v44, v240
	v_mov_b32_e32 v45, v241
	v_sub_f32_e32 v39, v34, v35
	v_mov_b32_e32 v34, v19
	v_mov_b32_e32 v35, v27
	v_pk_mul_f32 v[34:35], v[34:35], v[40:41] op_sel_hi:[1,0]
	v_mov_b32_e32 v19, v26
	s_waitcnt vmcnt(0) lgkmcnt(0)
	v_pk_mul_f32 v[48:49], v[34:35], v[44:45]
	s_nop 0
	v_add_f32_e32 v41, v48, v49
	v_pk_mul_f32 v[18:19], v[18:19], v[40:41] op_sel_hi:[1,0]
	v_pk_mul_f32 v[34:35], v[34:35], v[44:45] op_sel:[1,0] op_sel_hi:[0,1]
	v_pk_mul_f32 v[26:27], v[18:19], v[42:43]
	v_pk_mul_f32 v[18:19], v[18:19], v[42:43] op_sel:[1,0] op_sel_hi:[0,1]
	v_mov_b32_e32 v42, v242
	v_mov_b32_e32 v43, v243
	v_mov_b32_e32 v44, v244
	v_mov_b32_e32 v45, v245
	v_sub_f32_e32 v48, v18, v19
	v_mov_b32_e32 v18, v25
	v_mov_b32_e32 v19, v33
	v_pk_mul_f32 v[18:19], v[18:19], v[40:41] op_sel_hi:[1,0]
	v_sub_f32_e32 v34, v34, v35
	v_add_f32_e32 v35, v26, v27
	v_mov_b32_e32 v25, v32
	s_waitcnt vmcnt(0) lgkmcnt(0)
	v_pk_mul_f32 v[26:27], v[18:19], v[44:45]
	v_pk_mul_f32 v[18:19], v[18:19], v[44:45] op_sel:[1,0] op_sel_hi:[0,1]
	v_sub_f32_e32 v44, v18, v19
	v_pk_mul_f32 v[18:19], v[24:25], v[40:41] op_sel_hi:[1,0]
	v_add_f32_e32 v49, v26, v27
	v_pk_mul_f32 v[24:25], v[18:19], v[42:43]
	v_pk_mul_f32 v[18:19], v[18:19], v[42:43] op_sel:[1,0] op_sel_hi:[0,1]
	v_add_f32_e32 v45, v24, v25
	v_mov_b32_e32 v24, v246
	v_mov_b32_e32 v25, v247
	v_mov_b32_e32 v26, v248
	v_mov_b32_e32 v27, v249
	v_sub_f32_e32 v42, v18, v19
	v_mov_b32_e32 v18, v23
	v_mov_b32_e32 v19, v31
	v_pk_mul_f32 v[18:19], v[18:19], v[40:41] op_sel_hi:[1,0]
	v_mov_b32_e32 v23, v30
	s_waitcnt vmcnt(0) lgkmcnt(0)
	v_pk_mul_f32 v[32:33], v[18:19], v[26:27]
	v_pk_mul_f32 v[18:19], v[18:19], v[26:27] op_sel:[1,0] op_sel_hi:[0,1]
	v_sub_f32_e32 v26, v18, v19
	v_pk_mul_f32 v[18:19], v[22:23], v[40:41] op_sel_hi:[1,0]
	v_add_f32_e32 v31, v32, v33
	v_pk_mul_f32 v[22:23], v[18:19], v[24:25]
	v_pk_mul_f32 v[18:19], v[18:19], v[24:25] op_sel:[1,0] op_sel_hi:[0,1]
	v_add_f32_e32 v22, v22, v23
	v_sub_f32_e32 v23, v18, v19
	v_pk_mul_f32 v[18:19], v[28:29], v[40:41] op_sel_hi:[1,0]
	s_nop 0
	v_pk_mul_f32 v[20:21], v[18:19], v[36:37] op_sel:[1,0] op_sel_hi:[0,1]
	v_pk_mul_f32 v[18:19], v[18:19], v[36:37]
	v_sub_f32_e32 v21, v20, v21
	v_add_f32_e32 v25, v18, v19
	v_cvt_pk_bf16_f32 v18, v23, v26
	v_mov_b64_e32 v[26:27], s[6:7]
	v_mad_i64_i32 v[26:27], s[0:1], v38, s2, v[26:27]
	v_lshl_add_u64 v[26:27], s[16:17], 1, v[26:27]
	v_cvt_pk_bf16_f32 v19, v42, v44
	v_cvt_pk_bf16_f32 v20, v48, v34
	v_cvt_pk_bf16_f32 v21, v39, v21
	v_lshl_add_u64 v[26:27], v[26:27], 0, v[166:167]
	v_cvt_pk_bf16_f32 v22, v22, v31
	v_cvt_pk_bf16_f32 v23, v45, v49
	v_cvt_pk_bf16_f32 v24, v35, v41
	v_cvt_pk_bf16_f32 v25, v0, v25
	global_store_dwordx4 v[26:27], v[18:21], off offset:256
	global_store_dwordx4 v[26:27], v[22:25], off offset:320
.LBB2_591:
	s_nop 1
	v_add_u32_e32 v22, 0xb0, v168
	v_ashrrev_i32_e32 v23, 31, v22
	v_lshlrev_b64 v[18:19], 6, v[22:23]
	v_lshl_add_u64 v[18:19], s[46:47], 0, v[18:19]
	s_mov_b32 s59, s17
	v_lshl_add_u64 v[24:25], v[18:19], 0, s[58:59]
	global_load_dwordx4 v[18:21], v[24:25], off
	s_nop 0
	global_load_dwordx4 v[24:27], v[24:25], off offset:16
	s_and_b64 vcc, exec, s[40:41]
	s_waitcnt vmcnt(0) lgkmcnt(0)
	v_mov_b32_e32 v28, v18
	v_mov_b32_e32 v29, v24
	v_mov_b32_e32 v24, v19
	v_mov_b32_e32 v18, v20
	v_mov_b32_e32 v19, v26
	v_mov_b32_e32 v26, v21
	v_pk_add_f32 v[20:21], v[28:29], v[24:25]
	v_pk_add_f32 v[18:19], v[18:19], v[26:27]
	s_nop 0
	v_pk_add_f32 v[18:19], v[20:21], v[18:19]
	s_nop 0
	v_add_f32_e32 v0, v18, v19
	v_fmamk_f32 v0, v0, 0x3b000000, v147
	v_mul_f32_e32 v18, 0x4b800000, v0
	v_cmp_gt_f32_e64 s[0:1], s29, v0
	s_nop 1
	v_cndmask_b32_e64 v0, v0, v18, s[0:1]
	v_rsq_f32_e32 v0, v0
	s_nop 0
	v_mul_f32_e32 v18, 0x45800000, v0
	v_cndmask_b32_e64 v24, v0, v18, s[0:1]
	s_mov_b64 s[0:1], -1
	s_cbranch_vccz .LBB2_594
	s_and_b64 vcc, exec, s[0:1]
	s_cbranch_vccnz .LBB2_611

.LBB2_602:
	v_lshlrev_b32_e32 v0, 1, v144
	v_pk_mul_f32 v[30:31], v[16:17], v[24:25] op_sel_hi:[1,0]
	v_pk_mul_f32 v[32:33], v[14:15], v[24:25] op_sel_hi:[1,0]
	v_lshl_add_u64 v[38:39], v[28:29], 0, v[0:1]
	v_cvt_pk_bf16_f32 v28, v32, v33
	v_cvt_pk_bf16_f32 v29, v30, v31
	s_and_b64 vcc, exec, s[38:39]
	s_mov_b64 s[8:9], -1
	v_pk_mul_f32 v[34:35], v[12:13], v[24:25] op_sel_hi:[1,0]
	v_pk_mul_f32 v[36:37], v[10:11], v[24:25] op_sel_hi:[1,0]
	s_nop 0
	v_cvt_pk_bf16_f32 v30, v36, v37
	v_cvt_pk_bf16_f32 v31, v34, v35
	global_store_dwordx4 v[38:39], v[28:31], off
	s_cbranch_vccnz .LBB2_608
	s_and_b64 vcc, exec, s[0:1]
	s_mov_b64 s[0:1], -1
	s_cbranch_vccnz .LBB2_605
	v_lshl_add_u64 v[20:21], s[44:45], 0, v[20:21]
	s_lshl_b32 s0, s74, 9
	s_mov_b32 s1, s17
	v_lshl_add_u64 v[20:21], v[20:21], 0, s[0:1]
	s_movk_i32 s0, 0xf900
	s_mov_b32 s1, -1
	v_lshl_add_u64 v[28:29], v[20:21], 0, s[0:1]
	s_mov_b64 s[0:1], 0

.LBB2_610:
	v_mov_b32_e32 v18, v24
	v_mov_b32_e32 v19, v24
	v_mov_b32_e32 v25, v24
	v_pk_mul_f32 v[20:21], v[8:9], v[18:19]
	v_lshl_add_u64 v[28:29], v[28:29], 0, v[0:1]
	s_movk_i32 s2, 0xc00
	v_pk_mul_f32 v[26:27], v[6:7], v[24:25]
	v_pk_mul_f32 v[30:31], v[4:5], v[18:19]
	v_pk_mul_f32 v[32:33], v[2:3], v[24:25]
	v_cvt_pk_bf16_f32 v18, v26, v27
	v_cvt_pk_bf16_f32 v19, v20, v21
	s_nop 0
	v_cvt_pk_bf16_f32 v20, v32, v33
	v_cvt_pk_bf16_f32 v21, v30, v31
	global_store_dwordx4 v[28:29], v[18:21], off
	s_branch .LBB2_593
.LBB2_611:
	v_lshlrev_b64 v[18:19], 8, v[22:23]
	v_lshl_add_u64 v[30:31], v[160:161], 0, v[18:19]
	global_load_dwordx4 v[18:21], v[30:31], off offset:48
	global_load_dwordx4 v[238:241], v[30:31], off offset:32
	global_load_dwordx4 v[242:245], v[30:31], off offset:16
	global_load_dwordx4 v[246:249], v[30:31], off
	v_mov_b32_e32 v26, v4
	v_mov_b32_e32 v27, v12
	v_pk_mul_f32 v[26:27], v[26:27], v[24:25] op_sel_hi:[1,0]
	v_mov_b32_e32 v12, v5
	v_mov_b32_e32 v167, v1
	s_waitcnt vmcnt(0) lgkmcnt(0)
	v_pk_mul_f32 v[28:29], v[26:27], v[18:19]
	s_nop 0
	v_add_f32_e32 v0, v28, v29
	v_pk_mul_f32 v[18:19], v[26:27], v[18:19] op_sel:[1,0] op_sel_hi:[0,1]
	v_mov_b32_e32 v26, v238
	v_mov_b32_e32 v27, v239
	v_mov_b32_e32 v28, v240
	v_mov_b32_e32 v29, v241
	v_sub_f32_e32 v23, v18, v19
	v_mov_b32_e32 v18, v3
	v_mov_b32_e32 v19, v11
	v_pk_mul_f32 v[18:19], v[18:19], v[24:25] op_sel_hi:[1,0]
	v_mov_b32_e32 v3, v10
	s_waitcnt vmcnt(0) lgkmcnt(0)
	v_pk_mul_f32 v[32:33], v[18:19], v[28:29]
	s_nop 0
	v_add_f32_e32 v25, v32, v33
	v_pk_mul_f32 v[2:3], v[2:3], v[24:25] op_sel_hi:[1,0]
	v_pk_mul_f32 v[18:19], v[18:19], v[28:29] op_sel:[1,0] op_sel_hi:[0,1]
	v_pk_mul_f32 v[10:11], v[2:3], v[26:27]
	v_pk_mul_f32 v[2:3], v[2:3], v[26:27] op_sel:[1,0] op_sel_hi:[0,1]
	v_mov_b32_e32 v26, v242
	v_mov_b32_e32 v27, v243
	v_mov_b32_e32 v28, v244
	v_mov_b32_e32 v29, v245
	v_sub_f32_e32 v32, v2, v3
	v_mov_b32_e32 v2, v9
	v_mov_b32_e32 v3, v17
	v_pk_mul_f32 v[2:3], v[2:3], v[24:25] op_sel_hi:[1,0]
	v_sub_f32_e32 v18, v18, v19
	v_add_f32_e32 v19, v10, v11
	v_mov_b32_e32 v9, v16
	s_waitcnt vmcnt(0) lgkmcnt(0)
	v_pk_mul_f32 v[10:11], v[2:3], v[28:29]
	v_pk_mul_f32 v[2:3], v[2:3], v[28:29] op_sel:[1,0] op_sel_hi:[0,1]
	v_sub_f32_e32 v28, v2, v3
	v_pk_mul_f32 v[2:3], v[8:9], v[24:25] op_sel_hi:[1,0]
	v_add_f32_e32 v33, v10, v11
	v_pk_mul_f32 v[8:9], v[2:3], v[26:27]
	v_pk_mul_f32 v[2:3], v[2:3], v[26:27] op_sel:[1,0] op_sel_hi:[0,1]
	v_add_f32_e32 v29, v8, v9
	v_mov_b32_e32 v8, v246
	v_mov_b32_e32 v9, v247
	v_mov_b32_e32 v10, v248
	v_mov_b32_e32 v11, v249
	v_sub_f32_e32 v26, v2, v3
	v_mov_b32_e32 v2, v7
	v_mov_b32_e32 v3, v15
	v_pk_mul_f32 v[2:3], v[2:3], v[24:25] op_sel_hi:[1,0]
	v_mov_b32_e32 v7, v14
	s_waitcnt vmcnt(0) lgkmcnt(0)
	v_pk_mul_f32 v[16:17], v[2:3], v[10:11]
	v_pk_mul_f32 v[2:3], v[2:3], v[10:11] op_sel:[1,0] op_sel_hi:[0,1]
	v_sub_f32_e32 v10, v2, v3
	v_pk_mul_f32 v[2:3], v[6:7], v[24:25] op_sel_hi:[1,0]
	v_add_f32_e32 v15, v16, v17
	v_pk_mul_f32 v[6:7], v[2:3], v[8:9]
	v_pk_mul_f32 v[2:3], v[2:3], v[8:9] op_sel:[1,0] op_sel_hi:[0,1]
	v_add_f32_e32 v6, v6, v7
	v_sub_f32_e32 v7, v2, v3
	v_pk_mul_f32 v[2:3], v[12:13], v[24:25] op_sel_hi:[1,0]
	s_nop 0
	v_pk_mul_f32 v[4:5], v[2:3], v[20:21] op_sel:[1,0] op_sel_hi:[0,1]
	v_pk_mul_f32 v[2:3], v[2:3], v[20:21]
	v_sub_f32_e32 v5, v4, v5
	v_add_f32_e32 v9, v2, v3
	v_cvt_pk_bf16_f32 v2, v7, v10
	v_mov_b64_e32 v[10:11], s[6:7]
	v_mad_i64_i32 v[10:11], s[0:1], v22, s2, v[10:11]
	v_lshl_add_u64 v[10:11], s[16:17], 1, v[10:11]
	v_cvt_pk_bf16_f32 v3, v26, v28
	v_cvt_pk_bf16_f32 v4, v32, v18
	v_cvt_pk_bf16_f32 v5, v23, v5
	v_lshl_add_u64 v[10:11], v[10:11], 0, v[166:167]
	v_cvt_pk_bf16_f32 v6, v6, v15
	v_cvt_pk_bf16_f32 v7, v29, v33
	v_cvt_pk_bf16_f32 v8, v19, v25
	v_cvt_pk_bf16_f32 v9, v0, v9
	global_store_dwordx4 v[10:11], v[2:5], off offset:256
	global_store_dwordx4 v[10:11], v[6:9], off offset:320
	s_andn2_b64 vcc, exec, s[36:37]
	s_mov_b64 s[0:1], -1
	s_cbranch_vccnz .LBB2_444

.LBB2_634:
	v_readlane_b32 s20, v254, 38
	v_lshl_add_u32 v144, s11, 8, v139
	s_cmp_gt_i32 s16, 15
	s_mov_b64 s[0:1], -1
	v_readlane_b32 s22, v254, 36
	v_readlane_b32 s21, v254, 39
	v_readlane_b32 s23, v254, 37
	s_cbranch_scc0 .LBB2_638
	s_cmp_gt_u32 s16, 31
	s_cbranch_scc1 .LBB2_637
	s_cmp_lt_u32 s16, 24
	s_cselect_b64 s[0:1], -1, 0
	s_and_b64 s[0:1], s[0:1], exec
	s_mov_b32 s1, 0x7800000
	s_cselect_b32 s1, s1, 0x9800000
	v_readlane_b32 s2, v254, 48
	s_cselect_b32 s0, -16, 0xffffffe8
	v_readlane_b32 s3, v254, 49
	s_add_u32 s2, s2, s1
	s_addc_u32 s3, s3, 0
	s_add_i32 s0, s0, s16
	s_lshl_b32 s0, s0, 8
	s_ashr_i32 s1, s0, 31
	s_lshl_b64 s[0:1], s[0:1], 1
	s_add_u32 s0, s2, s0
	s_addc_u32 s1, s3, s1
	v_lshlrev_b32_e32 v0, 1, v138
	v_ashrrev_i32_e32 v145, 31, v144
	v_lshl_add_u64 v[162:163], s[0:1], 0, v[0:1]
	v_lshlrev_b64 v[156:157], 12, v[144:145]
	v_mul_f32_e32 v0, 0xbfb8aa3b, v126
	v_mul_f32_e32 v145, 0xbfb8aa3b, v127
	v_exp_f32_e32 v0, v0
	v_exp_f32_e32 v145, v145
	v_lshl_add_u64 v[160:161], v[162:163], 0, v[156:157]
	v_or_b32_e32 v156, 16, v144
	v_add_f32_e32 v0, 1.0, v0
	v_add_f32_e32 v145, 1.0, v145
	v_rcp_f32_e32 v0, v0
	v_rcp_f32_e32 v145, v145
	v_ashrrev_i32_e32 v157, 31, v156
	v_lshlrev_b64 v[156:157], 12, v[156:157]
	v_lshl_add_u64 v[164:165], v[162:163], 0, v[156:157]
	v_cvt_pk_f16_f32 v168, v0, v145
	v_mul_f32_e32 v0, 0xbfb8aa3b, v128
	v_mul_f32_e32 v145, 0xbfb8aa3b, v129
	v_exp_f32_e32 v0, v0
	v_exp_f32_e32 v145, v145
	v_or_b32_e32 v156, 32, v144
	v_ashrrev_i32_e32 v157, 31, v156
	v_add_f32_e32 v0, 1.0, v0
	v_add_f32_e32 v145, 1.0, v145
	v_rcp_f32_e32 v0, v0
	v_rcp_f32_e32 v145, v145
	v_lshlrev_b64 v[156:157], 12, v[156:157]
	s_mov_b64 s[0:1], 0x80000
	v_cvt_pk_f16_f32 v169, v0, v145
	v_mul_f32_e32 v0, 0xbfb8aa3b, v122
	v_mul_f32_e32 v145, 0xbfb8aa3b, v123
	v_exp_f32_e32 v0, v0
	v_exp_f32_e32 v145, v145
	v_add_f32_e32 v0, 1.0, v0
	v_add_f32_e32 v145, 1.0, v145
	v_rcp_f32_e32 v0, v0
	v_rcp_f32_e32 v145, v145
	s_nop 0
	v_cvt_pk_f16_f32 v170, v0, v145
	v_mul_f32_e32 v0, 0xbfb8aa3b, v124
	v_mul_f32_e32 v145, 0xbfb8aa3b, v125
	v_exp_f32_e32 v0, v0
	v_exp_f32_e32 v145, v145
	v_add_f32_e32 v0, 1.0, v0
	v_add_f32_e32 v145, 1.0, v145
	v_rcp_f32_e32 v0, v0
	v_rcp_f32_e32 v145, v145
	s_nop 0
	v_cvt_pk_f16_f32 v171, v0, v145
	v_mul_f32_e32 v0, 0xbfb8aa3b, v118
	v_mul_f32_e32 v145, 0xbfb8aa3b, v119
	v_exp_f32_e32 v0, v0
	v_exp_f32_e32 v145, v145
	global_store_dwordx4 v[160:161], v[168:171], off
	v_add_f32_e32 v0, 1.0, v0
	v_add_f32_e32 v145, 1.0, v145
	v_rcp_f32_e32 v0, v0
	v_rcp_f32_e32 v145, v145
	s_nop 0
	v_cvt_pk_f16_f32 v168, v0, v145
	v_mul_f32_e32 v0, 0xbfb8aa3b, v120
	v_mul_f32_e32 v145, 0xbfb8aa3b, v121
	v_exp_f32_e32 v0, v0
	v_exp_f32_e32 v145, v145
	v_add_f32_e32 v0, 1.0, v0
	v_add_f32_e32 v145, 1.0, v145
	v_rcp_f32_e32 v0, v0
	v_rcp_f32_e32 v145, v145
	s_nop 0
	v_cvt_pk_f16_f32 v169, v0, v145
	v_mul_f32_e32 v0, 0xbfb8aa3b, v114
	v_mul_f32_e32 v145, 0xbfb8aa3b, v115
	v_exp_f32_e32 v0, v0
	v_exp_f32_e32 v145, v145
	v_add_f32_e32 v0, 1.0, v0
	v_add_f32_e32 v145, 1.0, v145
	v_rcp_f32_e32 v0, v0
	v_rcp_f32_e32 v145, v145
	s_nop 0
	v_cvt_pk_f16_f32 v170, v0, v145
	v_mul_f32_e32 v0, 0xbfb8aa3b, v116
	v_mul_f32_e32 v145, 0xbfb8aa3b, v117
	v_exp_f32_e32 v0, v0
	v_exp_f32_e32 v145, v145
	v_add_f32_e32 v0, 1.0, v0
	v_add_f32_e32 v145, 1.0, v145
	v_rcp_f32_e32 v0, v0
	v_rcp_f32_e32 v145, v145
	s_nop 0
	v_cvt_pk_f16_f32 v171, v0, v145
	v_mul_f32_e32 v0, 0xbfb8aa3b, v110
	v_mul_f32_e32 v145, 0xbfb8aa3b, v111
	v_exp_f32_e32 v0, v0
	v_exp_f32_e32 v145, v145
	global_store_dwordx4 v[160:161], v[168:171], off offset:256
	v_add_f32_e32 v0, 1.0, v0
	v_add_f32_e32 v145, 1.0, v145
	v_rcp_f32_e32 v0, v0
	v_rcp_f32_e32 v145, v145
	s_nop 0
	v_cvt_pk_f16_f32 v168, v0, v145
	v_mul_f32_e32 v0, 0xbfb8aa3b, v112
	v_mul_f32_e32 v145, 0xbfb8aa3b, v113
	v_exp_f32_e32 v0, v0
	v_exp_f32_e32 v145, v145
	v_add_f32_e32 v0, 1.0, v0
	v_add_f32_e32 v145, 1.0, v145
	v_rcp_f32_e32 v0, v0
	v_rcp_f32_e32 v145, v145
	s_nop 0
	v_cvt_pk_f16_f32 v169, v0, v145
	v_mul_f32_e32 v0, 0xbfb8aa3b, v106
	v_mul_f32_e32 v145, 0xbfb8aa3b, v107
	v_exp_f32_e32 v0, v0
	v_exp_f32_e32 v145, v145
	v_add_f32_e32 v0, 1.0, v0
	v_add_f32_e32 v145, 1.0, v145
	v_rcp_f32_e32 v0, v0
	v_rcp_f32_e32 v145, v145
	s_nop 0
	v_cvt_pk_f16_f32 v170, v0, v145
	v_mul_f32_e32 v0, 0xbfb8aa3b, v108
	v_mul_f32_e32 v145, 0xbfb8aa3b, v109
	v_exp_f32_e32 v0, v0
	v_exp_f32_e32 v145, v145
	v_add_f32_e32 v0, 1.0, v0
	v_add_f32_e32 v145, 1.0, v145
	v_rcp_f32_e32 v0, v0
	v_rcp_f32_e32 v145, v145
	s_nop 0
	v_cvt_pk_f16_f32 v171, v0, v145
	v_mul_f32_e32 v0, 0xbfb8aa3b, v102
	v_mul_f32_e32 v145, 0xbfb8aa3b, v103
	v_exp_f32_e32 v0, v0
	v_exp_f32_e32 v145, v145
	global_store_dwordx4 v[164:165], v[168:171], off
	v_add_f32_e32 v0, 1.0, v0
	v_add_f32_e32 v145, 1.0, v145
	v_rcp_f32_e32 v0, v0
	v_rcp_f32_e32 v145, v145
	s_nop 0
	v_cvt_pk_f16_f32 v168, v0, v145
	v_mul_f32_e32 v0, 0xbfb8aa3b, v104
	v_mul_f32_e32 v145, 0xbfb8aa3b, v105
	v_exp_f32_e32 v0, v0
	v_exp_f32_e32 v145, v145
	v_add_f32_e32 v0, 1.0, v0
	v_add_f32_e32 v145, 1.0, v145
	v_rcp_f32_e32 v0, v0
	v_rcp_f32_e32 v145, v145
	s_nop 0
	v_cvt_pk_f16_f32 v169, v0, v145
	v_mul_f32_e32 v0, 0xbfb8aa3b, v98
	v_mul_f32_e32 v145, 0xbfb8aa3b, v99
	v_exp_f32_e32 v0, v0
	v_exp_f32_e32 v145, v145
	v_add_f32_e32 v0, 1.0, v0
	v_add_f32_e32 v145, 1.0, v145
	v_rcp_f32_e32 v0, v0
	v_rcp_f32_e32 v145, v145
	s_nop 0
	v_cvt_pk_f16_f32 v170, v0, v145
	v_mul_f32_e32 v0, 0xbfb8aa3b, v100
	v_mul_f32_e32 v145, 0xbfb8aa3b, v101
	v_exp_f32_e32 v0, v0
	v_exp_f32_e32 v145, v145
	v_add_f32_e32 v0, 1.0, v0
	v_add_f32_e32 v145, 1.0, v145
	v_rcp_f32_e32 v0, v0
	v_rcp_f32_e32 v145, v145
	s_nop 0
	v_cvt_pk_f16_f32 v171, v0, v145
	v_mul_f32_e32 v0, 0xbfb8aa3b, v94
	v_mul_f32_e32 v145, 0xbfb8aa3b, v95
	v_exp_f32_e32 v0, v0
	v_exp_f32_e32 v145, v145
	global_store_dwordx4 v[164:165], v[168:171], off offset:256
	v_lshl_add_u64 v[164:165], v[162:163], 0, v[156:157]
	v_add_f32_e32 v0, 1.0, v0
	v_add_f32_e32 v145, 1.0, v145
	v_rcp_f32_e32 v0, v0
	v_rcp_f32_e32 v145, v145
	v_or_b32_e32 v156, 48, v144
	v_ashrrev_i32_e32 v157, 31, v156
	v_lshlrev_b64 v[156:157], 12, v[156:157]
	v_cvt_pk_f16_f32 v168, v0, v145
	v_mul_f32_e32 v0, 0xbfb8aa3b, v96
	v_mul_f32_e32 v145, 0xbfb8aa3b, v97
	v_exp_f32_e32 v0, v0
	v_exp_f32_e32 v145, v145
	v_lshl_add_u64 v[162:163], v[162:163], 0, v[156:157]
	v_add_f32_e32 v0, 1.0, v0
	v_add_f32_e32 v145, 1.0, v145
	v_rcp_f32_e32 v0, v0
	v_rcp_f32_e32 v145, v145
	s_nop 0
	v_cvt_pk_f16_f32 v169, v0, v145
	v_mul_f32_e32 v0, 0xbfb8aa3b, v90
	v_mul_f32_e32 v145, 0xbfb8aa3b, v91
	v_exp_f32_e32 v0, v0
	v_exp_f32_e32 v145, v145
	v_add_f32_e32 v0, 1.0, v0
	v_add_f32_e32 v145, 1.0, v145
	v_rcp_f32_e32 v0, v0
	v_rcp_f32_e32 v145, v145
	s_nop 0
	v_cvt_pk_f16_f32 v170, v0, v145
	v_mul_f32_e32 v0, 0xbfb8aa3b, v92
	v_mul_f32_e32 v145, 0xbfb8aa3b, v93
	v_exp_f32_e32 v0, v0
	v_exp_f32_e32 v145, v145
	v_add_f32_e32 v0, 1.0, v0
	v_add_f32_e32 v145, 1.0, v145
	v_rcp_f32_e32 v0, v0
	v_rcp_f32_e32 v145, v145
	s_nop 0
	v_cvt_pk_f16_f32 v171, v0, v145
	v_mul_f32_e32 v0, 0xbfb8aa3b, v86
	v_mul_f32_e32 v145, 0xbfb8aa3b, v87
	v_exp_f32_e32 v0, v0
	v_exp_f32_e32 v145, v145
	global_store_dwordx4 v[164:165], v[168:171], off
	v_add_f32_e32 v0, 1.0, v0
	v_add_f32_e32 v145, 1.0, v145
	v_rcp_f32_e32 v0, v0
	v_rcp_f32_e32 v145, v145
	s_nop 0
	v_cvt_pk_f16_f32 v168, v0, v145
	v_mul_f32_e32 v0, 0xbfb8aa3b, v88
	v_mul_f32_e32 v145, 0xbfb8aa3b, v89
	v_exp_f32_e32 v0, v0
	v_exp_f32_e32 v145, v145
	v_add_f32_e32 v0, 1.0, v0
	v_add_f32_e32 v145, 1.0, v145
	v_rcp_f32_e32 v0, v0
	v_rcp_f32_e32 v145, v145
	s_nop 0
	v_cvt_pk_f16_f32 v169, v0, v145
	v_mul_f32_e32 v0, 0xbfb8aa3b, v82
	v_mul_f32_e32 v145, 0xbfb8aa3b, v83
	v_exp_f32_e32 v0, v0
	v_exp_f32_e32 v145, v145
	v_add_f32_e32 v0, 1.0, v0
	v_add_f32_e32 v145, 1.0, v145
	v_rcp_f32_e32 v0, v0
	v_rcp_f32_e32 v145, v145
	s_nop 0
	v_cvt_pk_f16_f32 v170, v0, v145
	v_mul_f32_e32 v0, 0xbfb8aa3b, v84
	v_mul_f32_e32 v145, 0xbfb8aa3b, v85
	v_exp_f32_e32 v0, v0
	v_exp_f32_e32 v145, v145
	v_add_f32_e32 v0, 1.0, v0
	v_add_f32_e32 v145, 1.0, v145
	v_rcp_f32_e32 v0, v0
	v_rcp_f32_e32 v145, v145
	s_nop 0
	v_cvt_pk_f16_f32 v171, v0, v145
	v_mul_f32_e32 v0, 0xbfb8aa3b, v78
	v_mul_f32_e32 v145, 0xbfb8aa3b, v79
	v_exp_f32_e32 v0, v0
	v_exp_f32_e32 v145, v145
	global_store_dwordx4 v[164:165], v[168:171], off offset:256
	v_add_f32_e32 v0, 1.0, v0
	v_add_f32_e32 v145, 1.0, v145
	v_rcp_f32_e32 v0, v0
	v_rcp_f32_e32 v145, v145
	s_nop 0
	v_cvt_pk_f16_f32 v168, v0, v145
	v_mul_f32_e32 v0, 0xbfb8aa3b, v80
	v_mul_f32_e32 v145, 0xbfb8aa3b, v81
	v_exp_f32_e32 v0, v0
	v_exp_f32_e32 v145, v145
	v_add_f32_e32 v0, 1.0, v0
	v_add_f32_e32 v145, 1.0, v145
	v_rcp_f32_e32 v0, v0
	v_rcp_f32_e32 v145, v145
	s_nop 0
	v_cvt_pk_f16_f32 v169, v0, v145
	v_mul_f32_e32 v0, 0xbfb8aa3b, v74
	v_mul_f32_e32 v145, 0xbfb8aa3b, v75
	v_exp_f32_e32 v0, v0
	v_exp_f32_e32 v145, v145
	v_add_f32_e32 v0, 1.0, v0
	v_add_f32_e32 v145, 1.0, v145
	v_rcp_f32_e32 v0, v0
	v_rcp_f32_e32 v145, v145
	s_nop 0
	v_cvt_pk_f16_f32 v170, v0, v145
	v_mul_f32_e32 v0, 0xbfb8aa3b, v76
	v_mul_f32_e32 v145, 0xbfb8aa3b, v77
	v_exp_f32_e32 v0, v0
	v_exp_f32_e32 v145, v145
	v_add_f32_e32 v0, 1.0, v0
	v_add_f32_e32 v145, 1.0, v145
	v_rcp_f32_e32 v0, v0
	v_rcp_f32_e32 v145, v145
	s_nop 0
	v_cvt_pk_f16_f32 v171, v0, v145
	v_mul_f32_e32 v0, 0xbfb8aa3b, v70
	v_mul_f32_e32 v145, 0xbfb8aa3b, v71
	v_exp_f32_e32 v0, v0
	v_exp_f32_e32 v145, v145
	global_store_dwordx4 v[162:163], v[168:171], off
	v_add_f32_e32 v0, 1.0, v0
	v_add_f32_e32 v145, 1.0, v145
	v_rcp_f32_e32 v0, v0
	v_rcp_f32_e32 v145, v145
	s_nop 0
	v_cvt_pk_f16_f32 v168, v0, v145
	v_mul_f32_e32 v0, 0xbfb8aa3b, v72
	v_mul_f32_e32 v145, 0xbfb8aa3b, v73
	v_exp_f32_e32 v0, v0
	v_exp_f32_e32 v145, v145
	v_add_f32_e32 v0, 1.0, v0
	v_add_f32_e32 v145, 1.0, v145
	v_rcp_f32_e32 v0, v0
	v_rcp_f32_e32 v145, v145
	s_nop 0
	v_cvt_pk_f16_f32 v169, v0, v145
	v_mul_f32_e32 v0, 0xbfb8aa3b, v66
	v_mul_f32_e32 v145, 0xbfb8aa3b, v67
	v_exp_f32_e32 v0, v0
	v_exp_f32_e32 v145, v145
	v_add_f32_e32 v0, 1.0, v0
	v_add_f32_e32 v145, 1.0, v145
	v_rcp_f32_e32 v0, v0
	v_rcp_f32_e32 v145, v145
	s_nop 0
	v_cvt_pk_f16_f32 v170, v0, v145
	v_mul_f32_e32 v0, 0xbfb8aa3b, v68
	v_mul_f32_e32 v145, 0xbfb8aa3b, v69
	v_exp_f32_e32 v0, v0
	v_exp_f32_e32 v145, v145
	v_add_f32_e32 v0, 1.0, v0
	v_add_f32_e32 v145, 1.0, v145
	v_rcp_f32_e32 v0, v0
	v_rcp_f32_e32 v145, v145
	s_nop 0
	v_cvt_pk_f16_f32 v171, v0, v145
	v_mul_f32_e32 v0, 0xbfb8aa3b, v62
	v_mul_f32_e32 v145, 0xbfb8aa3b, v63
	v_exp_f32_e32 v0, v0
	v_exp_f32_e32 v145, v145
	global_store_dwordx4 v[162:163], v[168:171], off offset:256
	v_lshl_add_u64 v[162:163], v[160:161], 0, s[0:1]
	v_add_f32_e32 v0, 1.0, v0
	v_add_f32_e32 v145, 1.0, v145
	v_rcp_f32_e32 v0, v0
	v_rcp_f32_e32 v145, v145
	s_mov_b32 s0, 0x80000
	v_add_co_u32_e32 v156, vcc, s0, v160
	v_cvt_pk_f16_f32 v168, v0, v145
	v_mul_f32_e32 v0, 0xbfb8aa3b, v64
	v_mul_f32_e32 v145, 0xbfb8aa3b, v65
	v_exp_f32_e32 v0, v0
	v_exp_f32_e32 v145, v145
	v_addc_co_u32_e32 v157, vcc, 0, v161, vcc
	v_add_f32_e32 v0, 1.0, v0
	v_add_f32_e32 v145, 1.0, v145
	v_rcp_f32_e32 v0, v0
	v_rcp_f32_e32 v145, v145
	s_mov_b64 s[0:1], 0x90000
	v_cvt_pk_f16_f32 v169, v0, v145
	v_mul_f32_e32 v0, 0xbfb8aa3b, v58
	v_mul_f32_e32 v145, 0xbfb8aa3b, v59
	v_exp_f32_e32 v0, v0
	v_exp_f32_e32 v145, v145
	v_add_f32_e32 v0, 1.0, v0
	v_add_f32_e32 v145, 1.0, v145
	v_rcp_f32_e32 v0, v0
	v_rcp_f32_e32 v145, v145
	s_nop 0
	v_cvt_pk_f16_f32 v170, v0, v145
	v_mul_f32_e32 v0, 0xbfb8aa3b, v60
	v_mul_f32_e32 v145, 0xbfb8aa3b, v61
	v_exp_f32_e32 v0, v0
	v_exp_f32_e32 v145, v145
	v_add_f32_e32 v0, 1.0, v0
	v_add_f32_e32 v145, 1.0, v145
	v_rcp_f32_e32 v0, v0
	v_rcp_f32_e32 v145, v145
	s_nop 0
	v_cvt_pk_f16_f32 v171, v0, v145
	v_mul_f32_e32 v0, 0xbfb8aa3b, v54
	v_mul_f32_e32 v145, 0xbfb8aa3b, v55
	v_exp_f32_e32 v0, v0
	v_exp_f32_e32 v145, v145
	global_store_dwordx4 v[156:157], v[168:171], off
	v_add_f32_e32 v0, 1.0, v0
	v_add_f32_e32 v145, 1.0, v145
	v_rcp_f32_e32 v0, v0
	v_rcp_f32_e32 v145, v145
	s_nop 0
	v_cvt_pk_f16_f32 v168, v0, v145
	v_mul_f32_e32 v0, 0xbfb8aa3b, v56
	v_mul_f32_e32 v145, 0xbfb8aa3b, v57
	v_exp_f32_e32 v0, v0
	v_exp_f32_e32 v145, v145
	v_add_f32_e32 v0, 1.0, v0
	v_add_f32_e32 v145, 1.0, v145
	v_rcp_f32_e32 v0, v0
	v_rcp_f32_e32 v145, v145
	s_nop 0
	v_cvt_pk_f16_f32 v169, v0, v145
	v_mul_f32_e32 v0, 0xbfb8aa3b, v50
	v_mul_f32_e32 v145, 0xbfb8aa3b, v51
	v_exp_f32_e32 v0, v0
	v_exp_f32_e32 v145, v145
	v_add_f32_e32 v0, 1.0, v0
	v_add_f32_e32 v145, 1.0, v145
	v_rcp_f32_e32 v0, v0
	v_rcp_f32_e32 v145, v145
	s_nop 0
	v_cvt_pk_f16_f32 v170, v0, v145
	v_mul_f32_e32 v0, 0xbfb8aa3b, v52
	v_mul_f32_e32 v145, 0xbfb8aa3b, v53
	v_exp_f32_e32 v0, v0
	v_exp_f32_e32 v145, v145
	v_add_f32_e32 v0, 1.0, v0
	v_add_f32_e32 v145, 1.0, v145
	v_rcp_f32_e32 v0, v0
	v_rcp_f32_e32 v145, v145
	s_nop 0
	v_cvt_pk_f16_f32 v171, v0, v145
	v_mul_f32_e32 v0, 0xbfb8aa3b, v46
	v_mul_f32_e32 v145, 0xbfb8aa3b, v47
	v_exp_f32_e32 v0, v0
	v_exp_f32_e32 v145, v145
	global_store_dwordx4 v[162:163], v[168:171], off offset:256
	v_lshl_add_u64 v[162:163], v[160:161], 0, s[0:1]
	v_add_f32_e32 v0, 1.0, v0
	v_add_f32_e32 v145, 1.0, v145
	v_rcp_f32_e32 v0, v0
	v_rcp_f32_e32 v145, v145
	s_mov_b32 s0, 0x90000
	v_add_co_u32_e32 v156, vcc, s0, v160
	v_cvt_pk_f16_f32 v168, v0, v145
	v_mul_f32_e32 v0, 0xbfb8aa3b, v48
	v_mul_f32_e32 v145, 0xbfb8aa3b, v49
	v_exp_f32_e32 v0, v0
	v_exp_f32_e32 v145, v145
	v_addc_co_u32_e32 v157, vcc, 0, v161, vcc
	v_add_f32_e32 v0, 1.0, v0
	v_add_f32_e32 v145, 1.0, v145
	v_rcp_f32_e32 v0, v0
	v_rcp_f32_e32 v145, v145
	s_mov_b64 s[0:1], 0xa0000
	v_cvt_pk_f16_f32 v169, v0, v145
	v_mul_f32_e32 v0, 0xbfb8aa3b, v42
	v_mul_f32_e32 v145, 0xbfb8aa3b, v43
	v_exp_f32_e32 v0, v0
	v_exp_f32_e32 v145, v145
	v_add_f32_e32 v0, 1.0, v0
	v_add_f32_e32 v145, 1.0, v145
	v_rcp_f32_e32 v0, v0
	v_rcp_f32_e32 v145, v145
	s_nop 0
	v_cvt_pk_f16_f32 v170, v0, v145
	v_mul_f32_e32 v0, 0xbfb8aa3b, v44
	v_mul_f32_e32 v145, 0xbfb8aa3b, v45
	v_exp_f32_e32 v0, v0
	v_exp_f32_e32 v145, v145
	v_add_f32_e32 v0, 1.0, v0
	v_add_f32_e32 v145, 1.0, v145
	v_rcp_f32_e32 v0, v0
	v_rcp_f32_e32 v145, v145
	s_nop 0
	v_cvt_pk_f16_f32 v171, v0, v145
	v_mul_f32_e32 v0, 0xbfb8aa3b, v38
	v_mul_f32_e32 v145, 0xbfb8aa3b, v39
	v_exp_f32_e32 v0, v0
	v_exp_f32_e32 v145, v145
	global_store_dwordx4 v[156:157], v[168:171], off
	v_add_f32_e32 v0, 1.0, v0
	v_add_f32_e32 v145, 1.0, v145
	v_rcp_f32_e32 v0, v0
	v_rcp_f32_e32 v145, v145
	s_nop 0
	v_cvt_pk_f16_f32 v168, v0, v145
	v_mul_f32_e32 v0, 0xbfb8aa3b, v40
	v_mul_f32_e32 v145, 0xbfb8aa3b, v41
	v_exp_f32_e32 v0, v0
	v_exp_f32_e32 v145, v145
	v_add_f32_e32 v0, 1.0, v0
	v_add_f32_e32 v145, 1.0, v145
	v_rcp_f32_e32 v0, v0
	v_rcp_f32_e32 v145, v145
	s_nop 0
	v_cvt_pk_f16_f32 v169, v0, v145
	v_mul_f32_e32 v0, 0xbfb8aa3b, v34
	v_mul_f32_e32 v145, 0xbfb8aa3b, v35
	v_exp_f32_e32 v0, v0
	v_exp_f32_e32 v145, v145
	v_add_f32_e32 v0, 1.0, v0
	v_add_f32_e32 v145, 1.0, v145
	v_rcp_f32_e32 v0, v0
	v_rcp_f32_e32 v145, v145
	s_nop 0
	v_cvt_pk_f16_f32 v170, v0, v145
	v_mul_f32_e32 v0, 0xbfb8aa3b, v36
	v_mul_f32_e32 v145, 0xbfb8aa3b, v37
	v_exp_f32_e32 v0, v0
	v_exp_f32_e32 v145, v145
	v_add_f32_e32 v0, 1.0, v0
	v_add_f32_e32 v145, 1.0, v145
	v_rcp_f32_e32 v0, v0
	v_rcp_f32_e32 v145, v145
	s_nop 0
	v_cvt_pk_f16_f32 v171, v0, v145
	v_mul_f32_e32 v0, 0xbfb8aa3b, v30
	v_mul_f32_e32 v145, 0xbfb8aa3b, v31
	v_exp_f32_e32 v0, v0
	v_exp_f32_e32 v145, v145
	global_store_dwordx4 v[162:163], v[168:171], off offset:256
	v_lshl_add_u64 v[162:163], v[160:161], 0, s[0:1]
	v_add_f32_e32 v0, 1.0, v0
	v_add_f32_e32 v145, 1.0, v145
	v_rcp_f32_e32 v0, v0
	v_rcp_f32_e32 v145, v145
	s_mov_b32 s0, 0xa0000
	v_add_co_u32_e32 v156, vcc, s0, v160
	v_cvt_pk_f16_f32 v168, v0, v145
	v_mul_f32_e32 v0, 0xbfb8aa3b, v32
	v_mul_f32_e32 v145, 0xbfb8aa3b, v33
	v_exp_f32_e32 v0, v0
	v_exp_f32_e32 v145, v145
	v_addc_co_u32_e32 v157, vcc, 0, v161, vcc
	v_add_f32_e32 v0, 1.0, v0
	v_add_f32_e32 v145, 1.0, v145
	v_rcp_f32_e32 v0, v0
	v_rcp_f32_e32 v145, v145
	s_mov_b64 s[0:1], 0xb0000
	v_cvt_pk_f16_f32 v169, v0, v145
	v_mul_f32_e32 v0, 0xbfb8aa3b, v26
	v_mul_f32_e32 v145, 0xbfb8aa3b, v27
	v_exp_f32_e32 v0, v0
	v_exp_f32_e32 v145, v145
	v_add_f32_e32 v0, 1.0, v0
	v_add_f32_e32 v145, 1.0, v145
	v_rcp_f32_e32 v0, v0
	v_rcp_f32_e32 v145, v145
	s_nop 0
	v_cvt_pk_f16_f32 v170, v0, v145
	v_mul_f32_e32 v0, 0xbfb8aa3b, v28
	v_mul_f32_e32 v145, 0xbfb8aa3b, v29
	v_exp_f32_e32 v0, v0
	v_exp_f32_e32 v145, v145
	v_add_f32_e32 v0, 1.0, v0
	v_add_f32_e32 v145, 1.0, v145
	v_rcp_f32_e32 v0, v0
	v_rcp_f32_e32 v145, v145
	s_nop 0
	v_cvt_pk_f16_f32 v171, v0, v145
	v_mul_f32_e32 v0, 0xbfb8aa3b, v22
	v_mul_f32_e32 v145, 0xbfb8aa3b, v23
	v_exp_f32_e32 v0, v0
	v_exp_f32_e32 v145, v145
	global_store_dwordx4 v[156:157], v[168:171], off
	v_add_f32_e32 v0, 1.0, v0
	v_add_f32_e32 v145, 1.0, v145
	v_rcp_f32_e32 v0, v0
	v_rcp_f32_e32 v145, v145
	s_nop 0
	v_cvt_pk_f16_f32 v168, v0, v145
	v_mul_f32_e32 v0, 0xbfb8aa3b, v24
	v_mul_f32_e32 v145, 0xbfb8aa3b, v25
	v_exp_f32_e32 v0, v0
	v_exp_f32_e32 v145, v145
	v_add_f32_e32 v0, 1.0, v0
	v_add_f32_e32 v145, 1.0, v145
	v_rcp_f32_e32 v0, v0
	v_rcp_f32_e32 v145, v145
	s_nop 0
	v_cvt_pk_f16_f32 v169, v0, v145
	v_mul_f32_e32 v0, 0xbfb8aa3b, v18
	v_mul_f32_e32 v145, 0xbfb8aa3b, v19
	v_exp_f32_e32 v0, v0
	v_exp_f32_e32 v145, v145
	v_add_f32_e32 v0, 1.0, v0
	v_add_f32_e32 v145, 1.0, v145
	v_rcp_f32_e32 v0, v0
	v_rcp_f32_e32 v145, v145
	s_nop 0
	v_cvt_pk_f16_f32 v170, v0, v145
	v_mul_f32_e32 v0, 0xbfb8aa3b, v20
	v_mul_f32_e32 v145, 0xbfb8aa3b, v21
	v_exp_f32_e32 v0, v0
	v_exp_f32_e32 v145, v145
	v_add_f32_e32 v0, 1.0, v0
	v_add_f32_e32 v145, 1.0, v145
	v_rcp_f32_e32 v0, v0
	v_rcp_f32_e32 v145, v145
	s_nop 0
	v_cvt_pk_f16_f32 v171, v0, v145
	v_mul_f32_e32 v0, 0xbfb8aa3b, v14
	v_mul_f32_e32 v145, 0xbfb8aa3b, v15
	v_exp_f32_e32 v0, v0
	v_exp_f32_e32 v145, v145
	global_store_dwordx4 v[162:163], v[168:171], off offset:256
	v_lshl_add_u64 v[162:163], v[160:161], 0, s[0:1]
	v_add_f32_e32 v0, 1.0, v0
	v_add_f32_e32 v145, 1.0, v145
	v_rcp_f32_e32 v0, v0
	v_rcp_f32_e32 v145, v145
	s_mov_b32 s0, 0xb0000
	v_add_co_u32_e32 v156, vcc, s0, v160
	v_cvt_pk_f16_f32 v168, v0, v145
	v_mul_f32_e32 v0, 0xbfb8aa3b, v16
	v_mul_f32_e32 v145, 0xbfb8aa3b, v17
	v_exp_f32_e32 v0, v0
	v_exp_f32_e32 v145, v145
	v_addc_co_u32_e32 v157, vcc, 0, v161, vcc
	v_add_f32_e32 v0, 1.0, v0
	v_add_f32_e32 v145, 1.0, v145
	v_rcp_f32_e32 v0, v0
	v_rcp_f32_e32 v145, v145
	s_nop 0
	v_cvt_pk_f16_f32 v169, v0, v145
	v_mul_f32_e32 v0, 0xbfb8aa3b, v10
	v_mul_f32_e32 v145, 0xbfb8aa3b, v11
	v_exp_f32_e32 v0, v0
	v_exp_f32_e32 v145, v145
	v_add_f32_e32 v0, 1.0, v0
	v_add_f32_e32 v145, 1.0, v145
	v_rcp_f32_e32 v0, v0
	v_rcp_f32_e32 v145, v145
	s_nop 0
	v_cvt_pk_f16_f32 v170, v0, v145
	v_mul_f32_e32 v0, 0xbfb8aa3b, v12
	v_mul_f32_e32 v145, 0xbfb8aa3b, v13
	v_exp_f32_e32 v0, v0
	v_exp_f32_e32 v145, v145
	v_add_f32_e32 v0, 1.0, v0
	v_add_f32_e32 v145, 1.0, v145
	v_rcp_f32_e32 v0, v0
	v_rcp_f32_e32 v145, v145
	s_nop 0
	v_cvt_pk_f16_f32 v171, v0, v145
	v_mul_f32_e32 v0, 0xbfb8aa3b, v6
	v_mul_f32_e32 v145, 0xbfb8aa3b, v7
	v_exp_f32_e32 v0, v0
	v_exp_f32_e32 v145, v145
	global_store_dwordx4 v[156:157], v[168:171], off
	v_add_f32_e32 v0, 1.0, v0
	v_add_f32_e32 v145, 1.0, v145
	v_rcp_f32_e32 v0, v0
	v_rcp_f32_e32 v145, v145
	s_nop 0
	v_cvt_pk_f16_f32 v168, v0, v145
	v_mul_f32_e32 v0, 0xbfb8aa3b, v8
	v_mul_f32_e32 v145, 0xbfb8aa3b, v9
	v_exp_f32_e32 v0, v0
	v_exp_f32_e32 v145, v145
	v_add_f32_e32 v0, 1.0, v0
	v_add_f32_e32 v145, 1.0, v145
	v_rcp_f32_e32 v0, v0
	v_rcp_f32_e32 v145, v145
	s_nop 0
	v_cvt_pk_f16_f32 v169, v0, v145
	v_mul_f32_e32 v0, 0xbfb8aa3b, v2
	v_mul_f32_e32 v145, 0xbfb8aa3b, v3
	v_exp_f32_e32 v0, v0
	v_exp_f32_e32 v145, v145
	v_add_f32_e32 v0, 1.0, v0
	v_add_f32_e32 v145, 1.0, v145
	v_rcp_f32_e32 v0, v0
	v_rcp_f32_e32 v145, v145
	s_nop 0
	v_cvt_pk_f16_f32 v170, v0, v145
	v_mul_f32_e32 v0, 0xbfb8aa3b, v4
	v_mul_f32_e32 v145, 0xbfb8aa3b, v5
	v_exp_f32_e32 v0, v0
	v_exp_f32_e32 v145, v145
	v_add_f32_e32 v0, 1.0, v0
	v_add_f32_e32 v145, 1.0, v145
	v_rcp_f32_e32 v0, v0
	v_rcp_f32_e32 v145, v145
	s_nop 0
	v_cvt_pk_f16_f32 v171, v0, v145
	global_store_dwordx4 v[162:163], v[168:171], off offset:256

.LBB2_655:
	s_ashr_i32 s1, s0, 31
	s_lshl_b64 s[0:1], s[0:1], 1
	s_add_u32 s0, s2, s0
	s_addc_u32 s1, s3, s1
	v_lshlrev_b32_e32 v0, 1, v138
	s_cmp_lt_i32 s16, 4
	v_ashrrev_i32_e32 v145, 31, v144
	v_lshl_add_u64 v[160:161], s[0:1], 0, v[0:1]
	s_cselect_b64 s[18:19], -1, 0
	s_lshl_b32 s2, s16, 2
	v_mul_lo_u32 v0, s9, v144
	v_mul_lo_u32 v158, s8, v145
	v_mad_u64_u32 v[156:157], s[0:1], s8, v144, 0
	s_ashr_i32 s3, s2, 31
	v_add3_u32 v157, v157, v158, v0
	s_cmp_gt_i32 s16, 3
	v_lshl_add_u64 v[156:157], v[156:157], 1, v[160:161]
	v_cvt_pk_bf16_f32 v162, v126, v127
	v_cvt_pk_bf16_f32 v163, v128, v129
	v_cvt_pk_bf16_f32 v164, v122, v123
	v_cvt_pk_bf16_f32 v165, v124, v125
	global_store_dwordx4 v[156:157], v[162:165], off
	s_nop 1
	v_cvt_pk_bf16_f32 v162, v118, v119
	v_cvt_pk_bf16_f32 v163, v120, v121
	v_cvt_pk_bf16_f32 v164, v114, v115
	v_cvt_pk_bf16_f32 v165, v116, v117
	global_store_dwordx4 v[156:157], v[162:165], off offset:256
	s_cbranch_scc1 .LBB2_659
	v_mul_f32_e32 v117, v117, v117
	v_mul_f32_e32 v0, v125, v125
	v_fmac_f32_e32 v117, v116, v116
	v_mul_f32_e32 v116, v119, v119
	v_fmac_f32_e32 v0, v124, v124
	v_mul_f32_e32 v124, v127, v127
	v_mul_f32_e32 v125, v129, v129
	v_fmac_f32_e32 v116, v118, v118
	v_mul_f32_e32 v118, v121, v121
	v_fmac_f32_e32 v124, v126, v126
	v_fmac_f32_e32 v125, v128, v128
	v_mul_f32_e32 v123, v123, v123
	v_fmac_f32_e32 v118, v120, v120
	v_mul_f32_e32 v115, v115, v115
	v_add_f32_e32 v124, v124, v125
	v_fmac_f32_e32 v123, v122, v122
	v_add_f32_e32 v116, v116, v118
	v_fmac_f32_e32 v115, v114, v114
	v_add_f32_e32 v122, v124, v123
	v_add_f32_e32 v114, v116, v115
	v_add_f32_e32 v0, v0, v122
	v_add_f32_e32 v114, v117, v114
	v_and_b32_e32 v115, 64, v189
	v_add_f32_e32 v0, v0, v114
	v_xor_b32_e32 v114, 16, v189
	v_add_u32_e32 v115, 64, v115
	v_cmp_lt_i32_e32 vcc, v114, v115
	s_nop 1
	v_cndmask_b32_e32 v114, v189, v114, vcc
	v_lshlrev_b32_e32 v114, 2, v114
	ds_bpermute_b32 v114, v114, v0
	s_waitcnt lgkmcnt(0)
	v_add_f32_e32 v0, v0, v114
	v_xor_b32_e32 v114, 32, v189
	v_cmp_lt_i32_e32 vcc, v114, v115
	s_nop 1
	v_cndmask_b32_e32 v114, v189, v114, vcc
	v_lshlrev_b32_e32 v114, 2, v114
	ds_bpermute_b32 v114, v114, v0
	s_and_saveexec_b64 s[0:1], s[36:37]
	s_cbranch_execz .LBB2_658
	v_lshlrev_b64 v[116:117], 6, v[144:145]
	v_lshl_add_u64 v[116:117], s[46:47], 0, v[116:117]
	v_lshl_add_u64 v[116:117], s[2:3], 2, v[116:117]
	s_lshl_b32 s16, s63, 2
	v_lshl_add_u64 v[116:117], v[116:117], 0, s[16:17]
	s_waitcnt lgkmcnt(0)
	v_add_f32_e32 v0, v0, v114
	global_store_dword v[116:117], v0, off

.LBB2_659:
	s_waitcnt lgkmcnt(0)
	v_or_b32_e32 v114, 16, v144
	v_ashrrev_i32_e32 v115, 31, v114
	v_mul_lo_u32 v0, s8, v115
	v_mul_lo_u32 v118, s9, v114
	v_mad_u64_u32 v[116:117], s[0:1], s8, v114, 0
	v_add3_u32 v117, v117, v0, v118
	v_cndmask_b32_e64 v0, 0, 1, s[18:19]
	v_lshl_add_u64 v[120:121], v[116:117], 1, v[160:161]
	v_cvt_pk_bf16_f32 v116, v110, v111
	v_cvt_pk_bf16_f32 v117, v112, v113
	v_cvt_pk_bf16_f32 v118, v106, v107
	v_cvt_pk_bf16_f32 v119, v108, v109
	v_cmp_ne_u32_e64 s[0:1], 1, v0
	s_andn2_b64 vcc, exec, s[18:19]
	global_store_dwordx4 v[120:121], v[116:119], off
	s_nop 1
	v_cvt_pk_bf16_f32 v116, v102, v103
	v_cvt_pk_bf16_f32 v117, v104, v105
	v_cvt_pk_bf16_f32 v118, v98, v99
	v_cvt_pk_bf16_f32 v119, v100, v101
	global_store_dwordx4 v[120:121], v[116:119], off offset:256
	s_cbranch_vccnz .LBB2_663
	v_mul_f32_e32 v101, v101, v101
	v_mul_f32_e32 v0, v109, v109
	v_fmac_f32_e32 v101, v100, v100
	v_mul_f32_e32 v100, v103, v103
	v_fmac_f32_e32 v0, v108, v108
	v_mul_f32_e32 v108, v111, v111
	v_mul_f32_e32 v109, v113, v113
	v_fmac_f32_e32 v100, v102, v102
	v_mul_f32_e32 v102, v105, v105
	v_fmac_f32_e32 v108, v110, v110
	v_fmac_f32_e32 v109, v112, v112
	v_mul_f32_e32 v107, v107, v107
	v_fmac_f32_e32 v102, v104, v104
	v_mul_f32_e32 v99, v99, v99
	v_add_f32_e32 v108, v108, v109
	v_fmac_f32_e32 v107, v106, v106
	v_add_f32_e32 v100, v100, v102
	v_fmac_f32_e32 v99, v98, v98
	v_add_f32_e32 v106, v108, v107
	v_add_f32_e32 v98, v100, v99
	v_add_f32_e32 v0, v0, v106
	v_add_f32_e32 v98, v101, v98
	v_and_b32_e32 v99, 64, v189
	v_add_f32_e32 v0, v0, v98
	v_xor_b32_e32 v98, 16, v189
	v_add_u32_e32 v99, 64, v99
	v_cmp_lt_i32_e32 vcc, v98, v99
	s_nop 1
	v_cndmask_b32_e32 v98, v189, v98, vcc
	v_lshlrev_b32_e32 v98, 2, v98
	ds_bpermute_b32 v98, v98, v0
	s_waitcnt lgkmcnt(0)
	v_add_f32_e32 v0, v0, v98
	v_xor_b32_e32 v98, 32, v189
	v_cmp_lt_i32_e32 vcc, v98, v99
	s_nop 1
	v_cndmask_b32_e32 v98, v189, v98, vcc
	v_lshlrev_b32_e32 v98, 2, v98
	ds_bpermute_b32 v98, v98, v0
	s_and_saveexec_b64 s[18:19], s[36:37]
	s_cbranch_execz .LBB2_662
	v_lshlrev_b64 v[100:101], 6, v[114:115]
	v_lshl_add_u64 v[100:101], s[46:47], 0, v[100:101]
	v_lshl_add_u64 v[100:101], s[2:3], 2, v[100:101]
	s_lshl_b32 s16, s63, 2
	v_lshl_add_u64 v[100:101], v[100:101], 0, s[16:17]
	s_waitcnt lgkmcnt(0)
	v_add_f32_e32 v0, v0, v98
	global_store_dword v[100:101], v0, off

.LBB2_663:
	s_waitcnt lgkmcnt(0)
	v_or_b32_e32 v98, 32, v144
	v_ashrrev_i32_e32 v99, 31, v98
	v_mul_lo_u32 v0, s8, v99
	v_mul_lo_u32 v102, s9, v98
	v_mad_u64_u32 v[100:101], s[14:15], s8, v98, 0
	v_add3_u32 v101, v101, v0, v102
	v_lshl_add_u64 v[104:105], v[100:101], 1, v[160:161]
	v_cvt_pk_bf16_f32 v100, v94, v95
	v_cvt_pk_bf16_f32 v101, v96, v97
	v_cvt_pk_bf16_f32 v102, v90, v91
	v_cvt_pk_bf16_f32 v103, v92, v93
	s_and_b64 vcc, exec, s[0:1]
	global_store_dwordx4 v[104:105], v[100:103], off
	s_nop 1
	v_cvt_pk_bf16_f32 v100, v86, v87
	v_cvt_pk_bf16_f32 v101, v88, v89
	v_cvt_pk_bf16_f32 v102, v82, v83
	v_cvt_pk_bf16_f32 v103, v84, v85
	global_store_dwordx4 v[104:105], v[100:103], off offset:256
	s_cbranch_vccnz .LBB2_667
	v_mul_f32_e32 v85, v85, v85
	v_mul_f32_e32 v0, v93, v93
	v_fmac_f32_e32 v85, v84, v84
	v_mul_f32_e32 v84, v87, v87
	v_fmac_f32_e32 v0, v92, v92
	v_mul_f32_e32 v92, v95, v95
	v_mul_f32_e32 v93, v97, v97
	v_fmac_f32_e32 v84, v86, v86
	v_mul_f32_e32 v86, v89, v89
	v_fmac_f32_e32 v92, v94, v94
	v_fmac_f32_e32 v93, v96, v96
	v_mul_f32_e32 v91, v91, v91
	v_fmac_f32_e32 v86, v88, v88
	v_mul_f32_e32 v83, v83, v83
	v_add_f32_e32 v92, v92, v93
	v_fmac_f32_e32 v91, v90, v90
	v_add_f32_e32 v84, v84, v86
	v_fmac_f32_e32 v83, v82, v82
	v_add_f32_e32 v90, v92, v91
	v_add_f32_e32 v82, v84, v83
	v_add_f32_e32 v0, v0, v90
	v_add_f32_e32 v82, v85, v82
	v_and_b32_e32 v83, 64, v189
	v_add_f32_e32 v0, v0, v82
	v_xor_b32_e32 v82, 16, v189
	v_add_u32_e32 v83, 64, v83
	v_cmp_lt_i32_e32 vcc, v82, v83
	s_nop 1
	v_cndmask_b32_e32 v82, v189, v82, vcc
	v_lshlrev_b32_e32 v82, 2, v82
	ds_bpermute_b32 v82, v82, v0
	s_waitcnt lgkmcnt(0)
	v_add_f32_e32 v0, v0, v82
	v_xor_b32_e32 v82, 32, v189
	v_cmp_lt_i32_e32 vcc, v82, v83
	s_nop 1
	v_cndmask_b32_e32 v82, v189, v82, vcc
	v_lshlrev_b32_e32 v82, 2, v82
	ds_bpermute_b32 v82, v82, v0
	s_and_saveexec_b64 s[18:19], s[36:37]
	s_cbranch_execz .LBB2_666
	v_lshlrev_b64 v[84:85], 6, v[98:99]
	v_lshl_add_u64 v[84:85], s[46:47], 0, v[84:85]
	v_lshl_add_u64 v[84:85], s[2:3], 2, v[84:85]
	s_lshl_b32 s16, s63, 2
	v_lshl_add_u64 v[84:85], v[84:85], 0, s[16:17]
	s_waitcnt lgkmcnt(0)
	v_add_f32_e32 v0, v0, v82
	global_store_dword v[84:85], v0, off

.LBB2_667:
	s_waitcnt lgkmcnt(0)
	v_or_b32_e32 v82, 48, v144
	v_ashrrev_i32_e32 v83, 31, v82
	v_mul_lo_u32 v0, s8, v83
	v_mul_lo_u32 v86, s9, v82
	v_mad_u64_u32 v[84:85], s[14:15], s8, v82, 0
	v_add3_u32 v85, v85, v0, v86
	v_lshl_add_u64 v[88:89], v[84:85], 1, v[160:161]
	v_cvt_pk_bf16_f32 v84, v78, v79
	v_cvt_pk_bf16_f32 v85, v80, v81
	v_cvt_pk_bf16_f32 v86, v74, v75
	v_cvt_pk_bf16_f32 v87, v76, v77
	s_and_b64 vcc, exec, s[0:1]
	global_store_dwordx4 v[88:89], v[84:87], off
	s_nop 1
	v_cvt_pk_bf16_f32 v84, v70, v71
	v_cvt_pk_bf16_f32 v85, v72, v73
	v_cvt_pk_bf16_f32 v86, v66, v67
	v_cvt_pk_bf16_f32 v87, v68, v69
	global_store_dwordx4 v[88:89], v[84:87], off offset:256
	s_cbranch_vccnz .LBB2_671
	v_mul_f32_e32 v69, v69, v69
	v_mul_f32_e32 v0, v77, v77
	v_fmac_f32_e32 v69, v68, v68
	v_mul_f32_e32 v68, v71, v71
	v_fmac_f32_e32 v0, v76, v76
	v_mul_f32_e32 v76, v79, v79
	v_mul_f32_e32 v77, v81, v81
	v_fmac_f32_e32 v68, v70, v70
	v_mul_f32_e32 v70, v73, v73
	v_fmac_f32_e32 v76, v78, v78
	v_fmac_f32_e32 v77, v80, v80
	v_mul_f32_e32 v75, v75, v75
	v_fmac_f32_e32 v70, v72, v72
	v_mul_f32_e32 v67, v67, v67
	v_add_f32_e32 v76, v76, v77
	v_fmac_f32_e32 v75, v74, v74
	v_add_f32_e32 v68, v68, v70
	v_fmac_f32_e32 v67, v66, v66
	v_add_f32_e32 v74, v76, v75
	v_add_f32_e32 v66, v68, v67
	v_add_f32_e32 v0, v0, v74
	v_add_f32_e32 v66, v69, v66
	v_and_b32_e32 v67, 64, v189
	v_add_f32_e32 v0, v0, v66
	v_xor_b32_e32 v66, 16, v189
	v_add_u32_e32 v67, 64, v67
	v_cmp_lt_i32_e32 vcc, v66, v67
	s_nop 1
	v_cndmask_b32_e32 v66, v189, v66, vcc
	v_lshlrev_b32_e32 v66, 2, v66
	ds_bpermute_b32 v66, v66, v0
	s_waitcnt lgkmcnt(0)
	v_add_f32_e32 v0, v0, v66
	v_xor_b32_e32 v66, 32, v189
	v_cmp_lt_i32_e32 vcc, v66, v67
	s_nop 1
	v_cndmask_b32_e32 v66, v189, v66, vcc
	v_lshlrev_b32_e32 v66, 2, v66
	ds_bpermute_b32 v66, v66, v0
	s_and_saveexec_b64 s[18:19], s[36:37]
	s_cbranch_execz .LBB2_670
	v_lshlrev_b64 v[68:69], 6, v[82:83]
	v_lshl_add_u64 v[68:69], s[46:47], 0, v[68:69]
	v_lshl_add_u64 v[68:69], s[2:3], 2, v[68:69]
	s_lshl_b32 s16, s63, 2
	v_lshl_add_u64 v[68:69], v[68:69], 0, s[16:17]
	s_waitcnt lgkmcnt(0)
	v_add_f32_e32 v0, v0, v66
	global_store_dword v[68:69], v0, off

.LBB2_671:
	s_waitcnt lgkmcnt(0)
	v_add_u32_e32 v66, 0x80, v144
	v_ashrrev_i32_e32 v67, 31, v66
	v_mul_lo_u32 v0, s8, v67
	v_mul_lo_u32 v70, s9, v66
	v_mad_u64_u32 v[68:69], s[14:15], s8, v66, 0
	v_add3_u32 v69, v69, v0, v70
	v_lshl_add_u64 v[72:73], v[68:69], 1, v[160:161]
	v_cvt_pk_bf16_f32 v68, v62, v63
	v_cvt_pk_bf16_f32 v69, v64, v65
	v_cvt_pk_bf16_f32 v70, v58, v59
	v_cvt_pk_bf16_f32 v71, v60, v61
	s_and_b64 vcc, exec, s[0:1]
	global_store_dwordx4 v[72:73], v[68:71], off
	s_nop 1
	v_cvt_pk_bf16_f32 v68, v54, v55
	v_cvt_pk_bf16_f32 v69, v56, v57
	v_cvt_pk_bf16_f32 v70, v50, v51
	v_cvt_pk_bf16_f32 v71, v52, v53
	global_store_dwordx4 v[72:73], v[68:71], off offset:256
	s_cbranch_vccnz .LBB2_675
	v_mul_f32_e32 v53, v53, v53
	v_mul_f32_e32 v0, v61, v61
	v_fmac_f32_e32 v53, v52, v52
	v_mul_f32_e32 v52, v55, v55
	v_fmac_f32_e32 v0, v60, v60
	v_mul_f32_e32 v60, v63, v63
	v_mul_f32_e32 v61, v65, v65
	v_fmac_f32_e32 v52, v54, v54
	v_mul_f32_e32 v54, v57, v57
	v_fmac_f32_e32 v60, v62, v62
	v_fmac_f32_e32 v61, v64, v64
	v_mul_f32_e32 v59, v59, v59
	v_fmac_f32_e32 v54, v56, v56
	v_mul_f32_e32 v51, v51, v51
	v_add_f32_e32 v60, v60, v61
	v_fmac_f32_e32 v59, v58, v58
	v_add_f32_e32 v52, v52, v54
	v_fmac_f32_e32 v51, v50, v50
	v_add_f32_e32 v58, v60, v59
	v_add_f32_e32 v50, v52, v51
	v_add_f32_e32 v0, v0, v58
	v_add_f32_e32 v50, v53, v50
	v_and_b32_e32 v51, 64, v189
	v_add_f32_e32 v0, v0, v50
	v_xor_b32_e32 v50, 16, v189
	v_add_u32_e32 v51, 64, v51
	v_cmp_lt_i32_e32 vcc, v50, v51
	s_nop 1
	v_cndmask_b32_e32 v50, v189, v50, vcc
	v_lshlrev_b32_e32 v50, 2, v50
	ds_bpermute_b32 v50, v50, v0
	s_waitcnt lgkmcnt(0)
	v_add_f32_e32 v0, v0, v50
	v_xor_b32_e32 v50, 32, v189
	v_cmp_lt_i32_e32 vcc, v50, v51
	s_nop 1
	v_cndmask_b32_e32 v50, v189, v50, vcc
	v_lshlrev_b32_e32 v50, 2, v50
	ds_bpermute_b32 v50, v50, v0
	s_and_saveexec_b64 s[18:19], s[36:37]
	s_cbranch_execz .LBB2_674
	v_lshlrev_b64 v[52:53], 6, v[66:67]
	v_lshl_add_u64 v[52:53], s[46:47], 0, v[52:53]
	v_lshl_add_u64 v[52:53], s[2:3], 2, v[52:53]
	s_lshl_b32 s16, s63, 2
	v_lshl_add_u64 v[52:53], v[52:53], 0, s[16:17]
	s_waitcnt lgkmcnt(0)
	v_add_f32_e32 v0, v0, v50
	global_store_dword v[52:53], v0, off

.LBB2_675:
	s_waitcnt lgkmcnt(0)
	v_add_u32_e32 v50, 0x90, v144
	v_ashrrev_i32_e32 v51, 31, v50
	v_mul_lo_u32 v0, s8, v51
	v_mul_lo_u32 v54, s9, v50
	v_mad_u64_u32 v[52:53], s[14:15], s8, v50, 0
	v_add3_u32 v53, v53, v0, v54
	v_lshl_add_u64 v[56:57], v[52:53], 1, v[160:161]
	v_cvt_pk_bf16_f32 v52, v46, v47
	v_cvt_pk_bf16_f32 v53, v48, v49
	v_cvt_pk_bf16_f32 v54, v42, v43
	v_cvt_pk_bf16_f32 v55, v44, v45
	s_and_b64 vcc, exec, s[0:1]
	global_store_dwordx4 v[56:57], v[52:55], off
	s_nop 1
	v_cvt_pk_bf16_f32 v52, v38, v39
	v_cvt_pk_bf16_f32 v53, v40, v41
	v_cvt_pk_bf16_f32 v54, v34, v35
	v_cvt_pk_bf16_f32 v55, v36, v37
	global_store_dwordx4 v[56:57], v[52:55], off offset:256
	s_cbranch_vccnz .LBB2_679
	v_mul_f32_e32 v37, v37, v37
	v_mul_f32_e32 v0, v45, v45
	v_fmac_f32_e32 v37, v36, v36
	v_mul_f32_e32 v36, v39, v39
	v_fmac_f32_e32 v0, v44, v44
	v_mul_f32_e32 v44, v47, v47
	v_mul_f32_e32 v45, v49, v49
	v_fmac_f32_e32 v36, v38, v38
	v_mul_f32_e32 v38, v41, v41
	v_fmac_f32_e32 v44, v46, v46
	v_fmac_f32_e32 v45, v48, v48
	v_mul_f32_e32 v43, v43, v43
	v_fmac_f32_e32 v38, v40, v40
	v_mul_f32_e32 v35, v35, v35
	v_add_f32_e32 v44, v44, v45
	v_fmac_f32_e32 v43, v42, v42
	v_add_f32_e32 v36, v36, v38
	v_fmac_f32_e32 v35, v34, v34
	v_add_f32_e32 v42, v44, v43
	v_add_f32_e32 v34, v36, v35
	v_add_f32_e32 v0, v0, v42
	v_add_f32_e32 v34, v37, v34
	v_and_b32_e32 v35, 64, v189
	v_add_f32_e32 v0, v0, v34
	v_xor_b32_e32 v34, 16, v189
	v_add_u32_e32 v35, 64, v35
	v_cmp_lt_i32_e32 vcc, v34, v35
	s_nop 1
	v_cndmask_b32_e32 v34, v189, v34, vcc
	v_lshlrev_b32_e32 v34, 2, v34
	ds_bpermute_b32 v34, v34, v0
	s_waitcnt lgkmcnt(0)
	v_add_f32_e32 v0, v0, v34
	v_xor_b32_e32 v34, 32, v189
	v_cmp_lt_i32_e32 vcc, v34, v35
	s_nop 1
	v_cndmask_b32_e32 v34, v189, v34, vcc
	v_lshlrev_b32_e32 v34, 2, v34
	ds_bpermute_b32 v34, v34, v0
	s_and_saveexec_b64 s[18:19], s[36:37]
	s_cbranch_execz .LBB2_678
	v_lshlrev_b64 v[36:37], 6, v[50:51]
	v_lshl_add_u64 v[36:37], s[46:47], 0, v[36:37]
	v_lshl_add_u64 v[36:37], s[2:3], 2, v[36:37]
	s_lshl_b32 s16, s63, 2
	v_lshl_add_u64 v[36:37], v[36:37], 0, s[16:17]
	s_waitcnt lgkmcnt(0)
	v_add_f32_e32 v0, v0, v34
	global_store_dword v[36:37], v0, off

.LBB2_679:
	s_waitcnt lgkmcnt(0)
	v_add_u32_e32 v34, 0xa0, v144
	v_ashrrev_i32_e32 v35, 31, v34
	v_mul_lo_u32 v0, s8, v35
	v_mul_lo_u32 v38, s9, v34
	v_mad_u64_u32 v[36:37], s[14:15], s8, v34, 0
	v_add3_u32 v37, v37, v0, v38
	v_lshl_add_u64 v[40:41], v[36:37], 1, v[160:161]
	v_cvt_pk_bf16_f32 v36, v30, v31
	v_cvt_pk_bf16_f32 v37, v32, v33
	v_cvt_pk_bf16_f32 v38, v26, v27
	v_cvt_pk_bf16_f32 v39, v28, v29
	s_and_b64 vcc, exec, s[0:1]
	global_store_dwordx4 v[40:41], v[36:39], off
	s_nop 1
	v_cvt_pk_bf16_f32 v36, v22, v23
	v_cvt_pk_bf16_f32 v37, v24, v25
	v_cvt_pk_bf16_f32 v38, v18, v19
	v_cvt_pk_bf16_f32 v39, v20, v21
	global_store_dwordx4 v[40:41], v[36:39], off offset:256
	s_cbranch_vccnz .LBB2_683
	v_mul_f32_e32 v21, v21, v21
	v_mul_f32_e32 v0, v29, v29
	v_fmac_f32_e32 v21, v20, v20
	v_mul_f32_e32 v20, v23, v23
	v_fmac_f32_e32 v0, v28, v28
	v_mul_f32_e32 v28, v31, v31
	v_mul_f32_e32 v29, v33, v33
	v_fmac_f32_e32 v20, v22, v22
	v_mul_f32_e32 v22, v25, v25
	v_fmac_f32_e32 v28, v30, v30
	v_fmac_f32_e32 v29, v32, v32
	v_mul_f32_e32 v27, v27, v27
	v_fmac_f32_e32 v22, v24, v24
	v_mul_f32_e32 v19, v19, v19
	v_add_f32_e32 v28, v28, v29
	v_fmac_f32_e32 v27, v26, v26
	v_add_f32_e32 v20, v20, v22
	v_fmac_f32_e32 v19, v18, v18
	v_add_f32_e32 v26, v28, v27
	v_add_f32_e32 v18, v20, v19
	v_add_f32_e32 v0, v0, v26
	v_add_f32_e32 v18, v21, v18
	v_and_b32_e32 v19, 64, v189
	v_add_f32_e32 v0, v0, v18
	v_xor_b32_e32 v18, 16, v189
	v_add_u32_e32 v19, 64, v19
	v_cmp_lt_i32_e32 vcc, v18, v19
	s_nop 1
	v_cndmask_b32_e32 v18, v189, v18, vcc
	v_lshlrev_b32_e32 v18, 2, v18
	ds_bpermute_b32 v18, v18, v0
	s_waitcnt lgkmcnt(0)
	v_add_f32_e32 v0, v0, v18
	v_xor_b32_e32 v18, 32, v189
	v_cmp_lt_i32_e32 vcc, v18, v19
	s_nop 1
	v_cndmask_b32_e32 v18, v189, v18, vcc
	v_lshlrev_b32_e32 v18, 2, v18
	ds_bpermute_b32 v18, v18, v0
	s_and_saveexec_b64 s[18:19], s[36:37]
	s_cbranch_execz .LBB2_682
	v_lshlrev_b64 v[20:21], 6, v[34:35]
	v_lshl_add_u64 v[20:21], s[46:47], 0, v[20:21]
	v_lshl_add_u64 v[20:21], s[2:3], 2, v[20:21]
	s_lshl_b32 s16, s63, 2
	v_lshl_add_u64 v[20:21], v[20:21], 0, s[16:17]
	s_waitcnt lgkmcnt(0)
	v_add_f32_e32 v0, v0, v18
	global_store_dword v[20:21], v0, off

.LBB2_683:
	s_waitcnt lgkmcnt(0)
	v_add_u32_e32 v18, 0xb0, v144
	v_ashrrev_i32_e32 v19, 31, v18
	v_mul_lo_u32 v0, s8, v19
	v_mul_lo_u32 v22, s9, v18
	v_mad_u64_u32 v[20:21], s[8:9], s8, v18, 0
	v_add3_u32 v21, v21, v0, v22
	v_lshl_add_u64 v[24:25], v[20:21], 1, v[160:161]
	v_cvt_pk_bf16_f32 v20, v14, v15
	v_cvt_pk_bf16_f32 v21, v16, v17
	v_cvt_pk_bf16_f32 v22, v10, v11
	v_cvt_pk_bf16_f32 v23, v12, v13
	s_and_b64 vcc, exec, s[0:1]
	global_store_dwordx4 v[24:25], v[20:23], off
	s_nop 1
	v_cvt_pk_bf16_f32 v20, v6, v7
	v_cvt_pk_bf16_f32 v21, v8, v9
	v_cvt_pk_bf16_f32 v22, v2, v3
	v_cvt_pk_bf16_f32 v23, v4, v5
	global_store_dwordx4 v[24:25], v[20:23], off offset:256
	s_cbranch_vccnz .LBB2_687
	v_mul_f32_e32 v5, v5, v5
	v_mul_f32_e32 v0, v13, v13
	v_fmac_f32_e32 v5, v4, v4
	v_mul_f32_e32 v4, v7, v7
	v_fmac_f32_e32 v0, v12, v12
	v_mul_f32_e32 v12, v15, v15
	v_mul_f32_e32 v13, v17, v17
	v_fmac_f32_e32 v4, v6, v6
	v_mul_f32_e32 v6, v9, v9
	v_fmac_f32_e32 v12, v14, v14
	v_fmac_f32_e32 v13, v16, v16
	v_mul_f32_e32 v11, v11, v11
	v_fmac_f32_e32 v6, v8, v8
	v_mul_f32_e32 v3, v3, v3
	v_add_f32_e32 v12, v12, v13
	v_fmac_f32_e32 v11, v10, v10
	v_add_f32_e32 v4, v4, v6
	v_fmac_f32_e32 v3, v2, v2
	v_add_f32_e32 v10, v12, v11
	v_add_f32_e32 v2, v4, v3
	v_add_f32_e32 v0, v0, v10
	v_add_f32_e32 v2, v5, v2
	v_and_b32_e32 v3, 64, v189
	v_add_f32_e32 v0, v0, v2
	v_xor_b32_e32 v2, 16, v189
	v_add_u32_e32 v3, 64, v3
	v_cmp_lt_i32_e32 vcc, v2, v3
	s_nop 1
	v_cndmask_b32_e32 v2, v189, v2, vcc
	v_lshlrev_b32_e32 v2, 2, v2
	ds_bpermute_b32 v2, v2, v0
	s_waitcnt lgkmcnt(0)
	v_add_f32_e32 v0, v0, v2
	v_xor_b32_e32 v2, 32, v189
	v_cmp_lt_i32_e32 vcc, v2, v3
	s_nop 1
	v_cndmask_b32_e32 v2, v189, v2, vcc
	v_lshlrev_b32_e32 v2, 2, v2
	ds_bpermute_b32 v2, v2, v0
	s_and_saveexec_b64 s[0:1], s[36:37]
	s_cbranch_execz .LBB2_686
	v_lshlrev_b64 v[4:5], 6, v[18:19]
	v_lshl_add_u64 v[4:5], s[46:47], 0, v[4:5]
	v_lshl_add_u64 v[4:5], s[2:3], 2, v[4:5]
	s_lshl_b32 s16, s63, 2
	v_lshl_add_u64 v[4:5], v[4:5], 0, s[16:17]
	s_waitcnt lgkmcnt(0)
	v_add_f32_e32 v0, v0, v2
	global_store_dword v[4:5], v0, off

.Lnk_loop:
	s_mov_b32 s3, 0x1800000
	s_mov_b64 s[4:5], 0x2000
	global_load_dwordx4 v[156:159], v[64:65], off offset:-4096
	global_load_dwordx4 v[160:163], v[64:65], off offset:-3072
	global_load_dwordx4 v[164:167], v[64:65], off offset:-2048
	global_load_dwordx4 v[168:171], v[64:65], off offset:-1024
	global_load_dwordx4 v[172:175], v[64:65], off
	global_load_dwordx4 v[176:179], v[64:65], off offset:1024
	global_load_dwordx4 v[180:183], v[64:65], off offset:2048
	global_load_dwordx4 v[184:187], v[64:65], off offset:3072
	v_lshl_add_u64 v[64:65], v[64:65], 0, s[4:5]
	global_load_dwordx4 v[192:195], v[64:65], off offset:-4096
	global_load_dwordx4 v[196:199], v[64:65], off offset:-3072
	global_load_dwordx4 v[200:203], v[64:65], off offset:-2048
	global_load_dwordx4 v[204:207], v[64:65], off offset:-1024
	global_load_dwordx4 v[208:211], v[64:65], off
	global_load_dwordx4 v[212:215], v[64:65], off offset:1024
	global_load_dwordx4 v[216:219], v[64:65], off offset:2048
	global_load_dwordx4 v[220:223], v[64:65], off offset:3072
	v_lshl_add_u64 v[64:65], v[64:65], 0, s[4:5]
	v_lshl_add_u64 v[30:31], v[62:63], 0, s[0:1]
	v_add_co_u32_e32 v30, vcc, s3, v30
	s_nop 1
	v_addc_co_u32_e32 v31, vcc, 0, v31, vcc
	s_waitcnt vmcnt(8)
	v_mul_f32_e32 v2, v156, v156
	v_mul_f32_e32 v3, v158, v158
	v_fmac_f32_e32 v2, v157, v157
	v_fmac_f32_e32 v3, v159, v159
	v_add_f32_e32 v0, v2, v3
	v_mul_f32_e32 v2, v160, v160
	v_mul_f32_e32 v3, v162, v162
	v_fmac_f32_e32 v2, v161, v161
	v_fmac_f32_e32 v3, v163, v163
	v_add_f32_e32 v2, v2, v3
	v_add_f32_e32 v0, v0, v2
	v_mul_f32_e32 v2, v164, v164
	v_mul_f32_e32 v3, v166, v166
	v_fmac_f32_e32 v2, v165, v165
	v_fmac_f32_e32 v3, v167, v167
	v_add_f32_e32 v2, v2, v3
	v_add_f32_e32 v0, v0, v2
	v_mul_f32_e32 v2, v168, v168
	v_mul_f32_e32 v3, v170, v170
	v_fmac_f32_e32 v2, v169, v169
	v_fmac_f32_e32 v3, v171, v171
	v_add_f32_e32 v2, v2, v3
	v_add_f32_e32 v0, v0, v2
	v_mul_f32_e32 v2, v172, v172
	v_mul_f32_e32 v3, v174, v174
	v_fmac_f32_e32 v2, v173, v173
	v_fmac_f32_e32 v3, v175, v175
	v_add_f32_e32 v2, v2, v3
	v_add_f32_e32 v0, v0, v2
	v_mul_f32_e32 v2, v176, v176
	v_mul_f32_e32 v3, v178, v178
	v_fmac_f32_e32 v2, v177, v177
	v_fmac_f32_e32 v3, v179, v179
	v_add_f32_e32 v2, v2, v3
	v_add_f32_e32 v0, v0, v2
	v_mul_f32_e32 v2, v180, v180
	v_mul_f32_e32 v3, v182, v182
	v_fmac_f32_e32 v2, v181, v181
	v_fmac_f32_e32 v3, v183, v183
	v_add_f32_e32 v2, v2, v3
	v_add_f32_e32 v0, v0, v2
	v_mul_f32_e32 v2, v184, v184
	v_mul_f32_e32 v3, v186, v186
	v_fmac_f32_e32 v2, v185, v185
	v_fmac_f32_e32 v3, v187, v187
	v_add_f32_e32 v2, v2, v3
	v_add_f32_e32 v0, v0, v2
	ds_bpermute_b32 v78, v68, v0
	s_waitcnt lgkmcnt(0)
	v_add_f32_e32 v0, v0, v78
	ds_bpermute_b32 v78, v69, v0
	s_waitcnt lgkmcnt(0)
	v_add_f32_e32 v0, v0, v78
	ds_bpermute_b32 v78, v70, v0
	s_waitcnt lgkmcnt(0)
	v_add_f32_e32 v0, v0, v78
	ds_bpermute_b32 v78, v71, v0
	s_waitcnt lgkmcnt(0)
	v_add_f32_e32 v0, v0, v78
	ds_bpermute_b32 v78, v72, v0
	s_waitcnt lgkmcnt(0)
	v_add_f32_e32 v0, v0, v78
	ds_bpermute_b32 v78, v73, v0
	s_waitcnt lgkmcnt(0)
	v_add_f32_e32 v0, v0, v78
	v_fmamk_f32 v0, v0, 0x3a000000, v147
	v_cmp_gt_f32_e32 vcc, s29, v0
	v_mul_f32_e32 v78, 0x4b800000, v0
	s_nop 0
	v_cndmask_b32_e32 v0, v0, v78, vcc
	v_rsq_f32_e32 v0, v0
	s_nop 0
	v_mul_f32_e32 v78, 0x45800000, v0
	v_cndmask_b32_e32 v0, v0, v78, vcc
	v_mul_f32_e32 v2, v156, v0
	v_mul_f32_e32 v3, v157, v0
	v_mul_f32_e32 v4, v158, v0
	v_mul_f32_e32 v5, v159, v0
	v_mul_f32_e32 v2, v2, v88
	v_mul_f32_e32 v3, v3, v89
	v_mul_f32_e32 v4, v4, v90
	v_mul_f32_e32 v5, v5, v91
	v_cvt_pk_bf16_f32 v224, v2, v3
	v_cvt_pk_bf16_f32 v225, v4, v5
	global_store_dwordx2 v[30:31], v[224:225], off
	ds_write_b64 v55, v[224:225]
	v_mul_f32_e32 v2, v160, v0
	v_mul_f32_e32 v3, v161, v0
	v_mul_f32_e32 v4, v162, v0
	v_mul_f32_e32 v5, v163, v0
	v_mul_f32_e32 v2, v2, v92
	v_mul_f32_e32 v3, v3, v93
	v_mul_f32_e32 v4, v4, v94
	v_mul_f32_e32 v5, v5, v95
	v_cvt_pk_bf16_f32 v226, v2, v3
	v_cvt_pk_bf16_f32 v227, v4, v5
	global_store_dwordx2 v[30:31], v[226:227], off offset:512
	ds_write_b64 v55, v[226:227] offset:512
	v_mul_f32_e32 v2, v164, v0
	v_mul_f32_e32 v3, v165, v0
	v_mul_f32_e32 v4, v166, v0
	v_mul_f32_e32 v5, v167, v0
	v_mul_f32_e32 v2, v2, v96
	v_mul_f32_e32 v3, v3, v97
	v_mul_f32_e32 v4, v4, v98
	v_mul_f32_e32 v5, v5, v99
	v_cvt_pk_bf16_f32 v228, v2, v3
	v_cvt_pk_bf16_f32 v229, v4, v5
	global_store_dwordx2 v[30:31], v[228:229], off offset:1024
	ds_write_b64 v55, v[228:229] offset:1024
	v_mul_f32_e32 v2, v168, v0
	v_mul_f32_e32 v3, v169, v0
	v_mul_f32_e32 v4, v170, v0
	v_mul_f32_e32 v5, v171, v0
	v_mul_f32_e32 v2, v2, v100
	v_mul_f32_e32 v3, v3, v101
	v_mul_f32_e32 v4, v4, v102
	v_mul_f32_e32 v5, v5, v103
	v_cvt_pk_bf16_f32 v230, v2, v3
	v_cvt_pk_bf16_f32 v231, v4, v5
	global_store_dwordx2 v[30:31], v[230:231], off offset:1536
	ds_write_b64 v55, v[230:231] offset:1536
	v_mul_f32_e32 v2, v172, v0
	v_mul_f32_e32 v3, v173, v0
	v_mul_f32_e32 v4, v174, v0
	v_mul_f32_e32 v5, v175, v0
	v_mul_f32_e32 v2, v2, v104
	v_mul_f32_e32 v3, v3, v105
	v_mul_f32_e32 v4, v4, v106
	v_mul_f32_e32 v5, v5, v107
	v_cvt_pk_bf16_f32 v232, v2, v3
	v_cvt_pk_bf16_f32 v233, v4, v5
	global_store_dwordx2 v[30:31], v[232:233], off offset:2048
	ds_write_b64 v55, v[232:233] offset:2048
	v_mul_f32_e32 v2, v176, v0
	v_mul_f32_e32 v3, v177, v0
	v_mul_f32_e32 v4, v178, v0
	v_mul_f32_e32 v5, v179, v0
	v_mul_f32_e32 v2, v2, v108
	v_mul_f32_e32 v3, v3, v109
	v_mul_f32_e32 v4, v4, v110
	v_mul_f32_e32 v5, v5, v111
	v_cvt_pk_bf16_f32 v234, v2, v3
	v_cvt_pk_bf16_f32 v235, v4, v5
	global_store_dwordx2 v[30:31], v[234:235], off offset:2560
	ds_write_b64 v55, v[234:235] offset:2560
	v_mul_f32_e32 v2, v180, v0
	v_mul_f32_e32 v3, v181, v0
	v_mul_f32_e32 v4, v182, v0
	v_mul_f32_e32 v5, v183, v0
	v_mul_f32_e32 v2, v2, v112
	v_mul_f32_e32 v3, v3, v113
	v_mul_f32_e32 v4, v4, v114
	v_mul_f32_e32 v5, v5, v115
	v_cvt_pk_bf16_f32 v236, v2, v3
	v_cvt_pk_bf16_f32 v237, v4, v5
	global_store_dwordx2 v[30:31], v[236:237], off offset:3072
	ds_write_b64 v55, v[236:237] offset:3072
	v_mul_f32_e32 v2, v184, v0
	v_mul_f32_e32 v3, v185, v0
	v_mul_f32_e32 v4, v186, v0
	v_mul_f32_e32 v5, v187, v0
	v_mul_f32_e32 v2, v2, v116
	v_mul_f32_e32 v3, v3, v117
	v_mul_f32_e32 v4, v4, v118
	v_mul_f32_e32 v5, v5, v119
	v_cvt_pk_bf16_f32 v238, v2, v3
	v_cvt_pk_bf16_f32 v239, v4, v5
	global_store_dwordx2 v[30:31], v[238:239], off offset:3584
	ds_write_b64 v55, v[238:239] offset:3584
	s_add_u32 s0, s0, 0x1000
	s_addc_u32 s1, s1, 0
	v_add_u32_e32 v55, 0x1010, v55
	v_lshl_add_u64 v[30:31], v[62:63], 0, s[0:1]
	v_add_co_u32_e32 v30, vcc, s3, v30
	s_nop 1
	v_addc_co_u32_e32 v31, vcc, 0, v31, vcc
	s_waitcnt vmcnt(8)
	v_mul_f32_e32 v2, v192, v192
	v_mul_f32_e32 v3, v194, v194
	v_fmac_f32_e32 v2, v193, v193
	v_fmac_f32_e32 v3, v195, v195
	v_add_f32_e32 v0, v2, v3
	v_mul_f32_e32 v2, v196, v196
	v_mul_f32_e32 v3, v198, v198
	v_fmac_f32_e32 v2, v197, v197
	v_fmac_f32_e32 v3, v199, v199
	v_add_f32_e32 v2, v2, v3
	v_add_f32_e32 v0, v0, v2
	v_mul_f32_e32 v2, v200, v200
	v_mul_f32_e32 v3, v202, v202
	v_fmac_f32_e32 v2, v201, v201
	v_fmac_f32_e32 v3, v203, v203
	v_add_f32_e32 v2, v2, v3
	v_add_f32_e32 v0, v0, v2
	v_mul_f32_e32 v2, v204, v204
	v_mul_f32_e32 v3, v206, v206
	v_fmac_f32_e32 v2, v205, v205
	v_fmac_f32_e32 v3, v207, v207
	v_add_f32_e32 v2, v2, v3
	v_add_f32_e32 v0, v0, v2
	v_mul_f32_e32 v2, v208, v208
	v_mul_f32_e32 v3, v210, v210
	v_fmac_f32_e32 v2, v209, v209
	v_fmac_f32_e32 v3, v211, v211
	v_add_f32_e32 v2, v2, v3
	v_add_f32_e32 v0, v0, v2
	v_mul_f32_e32 v2, v212, v212
	v_mul_f32_e32 v3, v214, v214
	v_fmac_f32_e32 v2, v213, v213
	v_fmac_f32_e32 v3, v215, v215
	v_add_f32_e32 v2, v2, v3
	v_add_f32_e32 v0, v0, v2
	v_mul_f32_e32 v2, v216, v216
	v_mul_f32_e32 v3, v218, v218
	v_fmac_f32_e32 v2, v217, v217
	v_fmac_f32_e32 v3, v219, v219
	v_add_f32_e32 v2, v2, v3
	v_add_f32_e32 v0, v0, v2
	v_mul_f32_e32 v2, v220, v220
	v_mul_f32_e32 v3, v222, v222
	v_fmac_f32_e32 v2, v221, v221
	v_fmac_f32_e32 v3, v223, v223
	v_add_f32_e32 v2, v2, v3
	v_add_f32_e32 v0, v0, v2
	ds_bpermute_b32 v78, v68, v0
	s_waitcnt lgkmcnt(0)
	v_add_f32_e32 v0, v0, v78
	ds_bpermute_b32 v78, v69, v0
	s_waitcnt lgkmcnt(0)
	v_add_f32_e32 v0, v0, v78
	ds_bpermute_b32 v78, v70, v0
	s_waitcnt lgkmcnt(0)
	v_add_f32_e32 v0, v0, v78
	ds_bpermute_b32 v78, v71, v0
	s_waitcnt lgkmcnt(0)
	v_add_f32_e32 v0, v0, v78
	ds_bpermute_b32 v78, v72, v0
	s_waitcnt lgkmcnt(0)
	v_add_f32_e32 v0, v0, v78
	ds_bpermute_b32 v78, v73, v0
	s_waitcnt lgkmcnt(0)
	v_add_f32_e32 v0, v0, v78
	v_fmamk_f32 v0, v0, 0x3a000000, v147
	v_cmp_gt_f32_e32 vcc, s29, v0
	v_mul_f32_e32 v78, 0x4b800000, v0
	s_nop 0
	v_cndmask_b32_e32 v0, v0, v78, vcc
	v_rsq_f32_e32 v0, v0
	s_nop 0
	v_mul_f32_e32 v78, 0x45800000, v0
	v_cndmask_b32_e32 v0, v0, v78, vcc
	v_mul_f32_e32 v2, v192, v0
	v_mul_f32_e32 v3, v193, v0
	v_mul_f32_e32 v4, v194, v0
	v_mul_f32_e32 v5, v195, v0
	v_mul_f32_e32 v2, v2, v88
	v_mul_f32_e32 v3, v3, v89
	v_mul_f32_e32 v4, v4, v90
	v_mul_f32_e32 v5, v5, v91
	v_cvt_pk_bf16_f32 v120, v2, v3
	v_cvt_pk_bf16_f32 v121, v4, v5
	global_store_dwordx2 v[30:31], v[120:121], off
	ds_write_b64 v55, v[120:121]
	v_mul_f32_e32 v2, v196, v0
	v_mul_f32_e32 v3, v197, v0
	v_mul_f32_e32 v4, v198, v0
	v_mul_f32_e32 v5, v199, v0
	v_mul_f32_e32 v2, v2, v92
	v_mul_f32_e32 v3, v3, v93
	v_mul_f32_e32 v4, v4, v94
	v_mul_f32_e32 v5, v5, v95
	v_cvt_pk_bf16_f32 v122, v2, v3
	v_cvt_pk_bf16_f32 v123, v4, v5
	global_store_dwordx2 v[30:31], v[122:123], off offset:512
	ds_write_b64 v55, v[122:123] offset:512
	v_mul_f32_e32 v2, v200, v0
	v_mul_f32_e32 v3, v201, v0
	v_mul_f32_e32 v4, v202, v0
	v_mul_f32_e32 v5, v203, v0
	v_mul_f32_e32 v2, v2, v96
	v_mul_f32_e32 v3, v3, v97
	v_mul_f32_e32 v4, v4, v98
	v_mul_f32_e32 v5, v5, v99
	v_cvt_pk_bf16_f32 v124, v2, v3
	v_cvt_pk_bf16_f32 v125, v4, v5
	global_store_dwordx2 v[30:31], v[124:125], off offset:1024
	ds_write_b64 v55, v[124:125] offset:1024
	v_mul_f32_e32 v2, v204, v0
	v_mul_f32_e32 v3, v205, v0
	v_mul_f32_e32 v4, v206, v0
	v_mul_f32_e32 v5, v207, v0
	v_mul_f32_e32 v2, v2, v100
	v_mul_f32_e32 v3, v3, v101
	v_mul_f32_e32 v4, v4, v102
	v_mul_f32_e32 v5, v5, v103
	v_cvt_pk_bf16_f32 v126, v2, v3
	v_cvt_pk_bf16_f32 v127, v4, v5
	global_store_dwordx2 v[30:31], v[126:127], off offset:1536
	ds_write_b64 v55, v[126:127] offset:1536
	v_mul_f32_e32 v2, v208, v0
	v_mul_f32_e32 v3, v209, v0
	v_mul_f32_e32 v4, v210, v0
	v_mul_f32_e32 v5, v211, v0
	v_mul_f32_e32 v2, v2, v104
	v_mul_f32_e32 v3, v3, v105
	v_mul_f32_e32 v4, v4, v106
	v_mul_f32_e32 v5, v5, v107
	v_cvt_pk_bf16_f32 v128, v2, v3
	v_cvt_pk_bf16_f32 v129, v4, v5
	global_store_dwordx2 v[30:31], v[128:129], off offset:2048
	ds_write_b64 v55, v[128:129] offset:2048
	v_mul_f32_e32 v2, v212, v0
	v_mul_f32_e32 v3, v213, v0
	v_mul_f32_e32 v4, v214, v0
	v_mul_f32_e32 v5, v215, v0
	v_mul_f32_e32 v2, v2, v108
	v_mul_f32_e32 v3, v3, v109
	v_mul_f32_e32 v4, v4, v110
	v_mul_f32_e32 v5, v5, v111
	v_cvt_pk_bf16_f32 v130, v2, v3
	v_cvt_pk_bf16_f32 v131, v4, v5
	global_store_dwordx2 v[30:31], v[130:131], off offset:2560
	ds_write_b64 v55, v[130:131] offset:2560
	v_mul_f32_e32 v2, v216, v0
	v_mul_f32_e32 v3, v217, v0
	v_mul_f32_e32 v4, v218, v0
	v_mul_f32_e32 v5, v219, v0
	v_mul_f32_e32 v2, v2, v112
	v_mul_f32_e32 v3, v3, v113
	v_mul_f32_e32 v4, v4, v114
	v_mul_f32_e32 v5, v5, v115
	v_cvt_pk_bf16_f32 v132, v2, v3
	v_cvt_pk_bf16_f32 v133, v4, v5
	global_store_dwordx2 v[30:31], v[132:133], off offset:3072
	ds_write_b64 v55, v[132:133] offset:3072
	v_mul_f32_e32 v2, v220, v0
	v_mul_f32_e32 v3, v221, v0
	v_mul_f32_e32 v4, v222, v0
	v_mul_f32_e32 v5, v223, v0
	v_mul_f32_e32 v2, v2, v116
	v_mul_f32_e32 v3, v3, v117
	v_mul_f32_e32 v4, v4, v118
	v_mul_f32_e32 v5, v5, v119
	v_cvt_pk_bf16_f32 v134, v2, v3
	v_cvt_pk_bf16_f32 v135, v4, v5
	global_store_dwordx2 v[30:31], v[134:135], off offset:3584
	ds_write_b64 v55, v[134:135] offset:3584
	s_add_u32 s0, s0, 0x1000
	s_addc_u32 s1, s1, 0
	v_add_u32_e32 v55, 0x1010, v55
	s_cmpk_eq_i32 s0, 0x4000
	s_cbranch_scc0 .Lnk_loop
	v_mov_b32_e32 v2, 0
	s_mov_b32 s0, 0
	v_mov_b64_e32 v[62:63], v[60:61]
	v_mov_b32_e32 v0, v76
	v_mov_b32_e32 v3, v2
	v_mov_b32_e32 v4, v2
	v_mov_b32_e32 v5, v2
	v_mov_b32_e32 v6, v2
	v_mov_b32_e32 v7, v2
	v_mov_b32_e32 v8, v2
	v_mov_b32_e32 v9, v2
	v_mov_b32_e32 v10, v2
	v_mov_b32_e32 v11, v2
	v_mov_b32_e32 v12, v2
	v_mov_b32_e32 v13, v2
	v_mov_b32_e32 v14, v2
	v_mov_b32_e32 v15, v2
	v_mov_b32_e32 v16, v2
	v_mov_b32_e32 v17, v2
	v_mov_b32_e32 v18, v2
	v_mov_b32_e32 v19, v2
	v_mov_b32_e32 v20, v2
	v_mov_b32_e32 v21, v2
	v_mov_b32_e32 v22, v2
	v_mov_b32_e32 v23, v2
	v_mov_b32_e32 v24, v2
	v_mov_b32_e32 v25, v2
	v_mov_b32_e32 v26, v2
	v_mov_b32_e32 v27, v2
	v_mov_b32_e32 v28, v2
	v_mov_b32_e32 v29, v2
	v_mov_b32_e32 v30, v2
	v_mov_b32_e32 v31, v2
	v_mov_b32_e32 v32, v2
	v_mov_b32_e32 v33, v2
	s_waitcnt lgkmcnt(0)
	s_barrier
	v_ashrrev_i32_e32 v65, 31, v58
	v_mov_b32_e32 v64, v58
	v_lshlrev_b64 v[82:83], 1, v[64:65]
	v_lshl_add_u64 v[84:85], v[34:35], 0, v[82:83]
	v_lshl_add_u64 v[86:87], v[36:37], 0, v[82:83]
	global_load_dwordx4 v[88:91], v[84:85], off
	global_load_dwordx4 v[164:167], v[86:87], off
	global_load_dwordx4 v[92:95], v[62:63], off
	global_load_dwordx4 v[168:171], v[86:87], off offset:32
	global_load_dwordx4 v[96:99], v[62:63], off offset:32
	global_load_dwordx4 v[172:175], v[86:87], off offset:64
	global_load_dwordx4 v[100:103], v[62:63], off offset:64
	global_load_dwordx4 v[176:179], v[86:87], off offset:96
	global_load_dwordx4 v[104:107], v[84:85], off offset:128
	global_load_dwordx4 v[180:183], v[86:87], off offset:128
	global_load_dwordx4 v[108:111], v[62:63], off offset:128
	global_load_dwordx4 v[184:187], v[86:87], off offset:160
	global_load_dwordx4 v[112:115], v[62:63], off offset:160
	global_load_dwordx4 v[192:195], v[86:87], off offset:192
	global_load_dwordx4 v[116:119], v[62:63], off offset:192
	global_load_dwordx4 v[196:199], v[86:87], off offset:224
	global_load_dwordx4 v[120:123], v[84:85], off offset:256
	global_load_dwordx4 v[200:203], v[86:87], off offset:256
	global_load_dwordx4 v[124:127], v[62:63], off offset:256
	global_load_dwordx4 v[204:207], v[86:87], off offset:288
	global_load_dwordx4 v[128:131], v[62:63], off offset:288
	global_load_dwordx4 v[208:211], v[86:87], off offset:320
	global_load_dwordx4 v[132:135], v[62:63], off offset:320
	global_load_dwordx4 v[212:215], v[86:87], off offset:352
	global_load_dwordx4 v[136:139], v[84:85], off offset:384
	global_load_dwordx4 v[216:219], v[86:87], off offset:384
	global_load_dwordx4 v[140:143], v[62:63], off offset:384
	global_load_dwordx4 v[220:223], v[86:87], off offset:416
	global_load_dwordx4 v[156:159], v[62:63], off offset:416
	global_load_dwordx4 v[224:227], v[86:87], off offset:448
	global_load_dwordx4 v[160:163], v[62:63], off offset:448
	global_load_dwordx4 v[228:231], v[86:87], off offset:480
	ds_read_b128 v[78:81], v0
	ds_read_b128 v[82:85], v0 offset:32
	s_waitcnt vmcnt(30) lgkmcnt(1)
	v_mfma_f32_32x32x16_bf16 v[2:17], v[88:91], v[78:81], v[2:17]
	v_mfma_f32_32x32x16_bf16 v[18:33], v[164:167], v[78:81], v[18:33]
	ds_read_b128 v[78:81], v0 offset:64
	s_waitcnt vmcnt(28) lgkmcnt(1)
	v_mfma_f32_32x32x16_bf16 v[2:17], v[92:95], v[82:85], v[2:17]
	v_mfma_f32_32x32x16_bf16 v[18:33], v[168:171], v[82:85], v[18:33]
	ds_read_b128 v[82:85], v0 offset:96
	s_waitcnt vmcnt(26) lgkmcnt(1)
	v_mfma_f32_32x32x16_bf16 v[2:17], v[96:99], v[78:81], v[2:17]
	v_mfma_f32_32x32x16_bf16 v[18:33], v[172:175], v[78:81], v[18:33]
	ds_read_b128 v[78:81], v0 offset:128
	s_waitcnt vmcnt(24) lgkmcnt(1)
	v_mfma_f32_32x32x16_bf16 v[2:17], v[100:103], v[82:85], v[2:17]
	v_mfma_f32_32x32x16_bf16 v[18:33], v[176:179], v[82:85], v[18:33]
	ds_read_b128 v[82:85], v0 offset:160
	s_waitcnt vmcnt(22) lgkmcnt(1)
	v_mfma_f32_32x32x16_bf16 v[2:17], v[104:107], v[78:81], v[2:17]
	v_mfma_f32_32x32x16_bf16 v[18:33], v[180:183], v[78:81], v[18:33]
	ds_read_b128 v[78:81], v0 offset:192
	s_waitcnt vmcnt(20) lgkmcnt(1)
	v_mfma_f32_32x32x16_bf16 v[2:17], v[108:111], v[82:85], v[2:17]
	v_mfma_f32_32x32x16_bf16 v[18:33], v[184:187], v[82:85], v[18:33]
	ds_read_b128 v[82:85], v0 offset:224
	s_waitcnt vmcnt(18) lgkmcnt(1)
	v_mfma_f32_32x32x16_bf16 v[2:17], v[112:115], v[78:81], v[2:17]
	v_mfma_f32_32x32x16_bf16 v[18:33], v[192:195], v[78:81], v[18:33]
	ds_read_b128 v[78:81], v0 offset:256
	s_waitcnt vmcnt(16) lgkmcnt(1)
	v_mfma_f32_32x32x16_bf16 v[2:17], v[116:119], v[82:85], v[2:17]
	v_mfma_f32_32x32x16_bf16 v[18:33], v[196:199], v[82:85], v[18:33]
	ds_read_b128 v[82:85], v0 offset:288
	s_waitcnt vmcnt(14) lgkmcnt(1)
	v_mfma_f32_32x32x16_bf16 v[2:17], v[120:123], v[78:81], v[2:17]
	v_mfma_f32_32x32x16_bf16 v[18:33], v[200:203], v[78:81], v[18:33]
	ds_read_b128 v[78:81], v0 offset:320
	s_waitcnt vmcnt(12) lgkmcnt(1)
	v_mfma_f32_32x32x16_bf16 v[2:17], v[124:127], v[82:85], v[2:17]
	v_mfma_f32_32x32x16_bf16 v[18:33], v[204:207], v[82:85], v[18:33]
	ds_read_b128 v[82:85], v0 offset:352
	s_waitcnt vmcnt(10) lgkmcnt(1)
	v_mfma_f32_32x32x16_bf16 v[2:17], v[128:131], v[78:81], v[2:17]
	v_mfma_f32_32x32x16_bf16 v[18:33], v[208:211], v[78:81], v[18:33]
	ds_read_b128 v[78:81], v0 offset:384
	s_waitcnt vmcnt(8) lgkmcnt(1)
	v_mfma_f32_32x32x16_bf16 v[2:17], v[132:135], v[82:85], v[2:17]
	v_mfma_f32_32x32x16_bf16 v[18:33], v[212:215], v[82:85], v[18:33]
	ds_read_b128 v[82:85], v0 offset:416
	s_waitcnt vmcnt(6) lgkmcnt(1)
	v_mfma_f32_32x32x16_bf16 v[2:17], v[136:139], v[78:81], v[2:17]
	v_mfma_f32_32x32x16_bf16 v[18:33], v[216:219], v[78:81], v[18:33]
	ds_read_b128 v[78:81], v0 offset:448
	s_waitcnt vmcnt(4) lgkmcnt(1)
	v_mfma_f32_32x32x16_bf16 v[2:17], v[140:143], v[82:85], v[2:17]
	v_mfma_f32_32x32x16_bf16 v[18:33], v[220:223], v[82:85], v[18:33]
	ds_read_b128 v[82:85], v0 offset:480
	s_waitcnt vmcnt(2) lgkmcnt(1)
	v_mfma_f32_32x32x16_bf16 v[2:17], v[156:159], v[78:81], v[2:17]
	v_mfma_f32_32x32x16_bf16 v[18:33], v[224:227], v[78:81], v[18:33]
	s_waitcnt vmcnt(0) lgkmcnt(0)
	v_mfma_f32_32x32x16_bf16 v[2:17], v[160:163], v[82:85], v[2:17]
	v_mfma_f32_32x32x16_bf16 v[18:33], v[228:231], v[82:85], v[18:33]
	v_add_u32_e32 v0, 0x200, v0
	v_lshl_add_u64 v[62:63], s[34:35], 2, v[62:63]
	s_movk_i32 s0, 0x100
	s_cmpk_eq_i32 s0, 0x100
	s_barrier
	s_nop 6
	ds_write2st64_b32 v59, v2, v3 offset1:1
	s_nop 1
	ds_write2st64_b32 v59, v18, v19 offset0:16 offset1:17
	ds_write2st64_b32 v59, v4, v5 offset0:2 offset1:3
	ds_write2st64_b32 v59, v20, v21 offset0:18 offset1:19
	ds_write2st64_b32 v59, v6, v7 offset0:4 offset1:5
	ds_write2st64_b32 v59, v22, v23 offset0:20 offset1:21
	ds_write2st64_b32 v59, v8, v9 offset0:6 offset1:7
	ds_write2st64_b32 v59, v24, v25 offset0:22 offset1:23
	ds_write2st64_b32 v59, v10, v11 offset0:8 offset1:9
	ds_write2st64_b32 v59, v26, v27 offset0:24 offset1:25
	ds_write2st64_b32 v59, v12, v13 offset0:10 offset1:11
	ds_write2st64_b32 v59, v28, v29 offset0:26 offset1:27
	ds_write2st64_b32 v59, v14, v15 offset0:12 offset1:13
	ds_write2st64_b32 v59, v30, v31 offset0:28 offset1:29
	ds_write2st64_b32 v59, v16, v17 offset0:14 offset1:15
	ds_write2st64_b32 v59, v32, v33 offset0:30 offset1:31
	v_lshl_or_b32 v2, s2, 5, v66
	v_ashrrev_i32_e32 v3, 31, v2
	v_lshlrev_b64 v[4:5], 8, v[2:3]
	v_lshl_add_u64 v[4:5], s[12:13], 0, v[4:5]
	v_lshl_add_u64 v[6:7], v[48:49], 3, v[4:5]
	s_waitcnt lgkmcnt(0)
	s_barrier
	global_load_dwordx2 v[6:7], v[6:7], off
	v_add_u32_e32 v0, v67, v74
	ds_read2st64_b32 v[8:9], v0 offset1:16
	ds_read2st64_b32 v[10:11], v0 offset0:17 offset1:32
	ds_read2st64_b32 v[12:13], v0 offset0:33 offset1:48
	ds_read2st64_b32 v[14:15], v0 offset0:49 offset1:64
	ds_read2st64_b32 v[16:17], v0 offset0:65 offset1:80
	ds_read2st64_b32 v[18:19], v0 offset0:81 offset1:96
	ds_read2st64_b32 v[20:21], v0 offset0:97 offset1:112
	ds_read2st64_b32 v[22:23], v0 offset0:113 offset1:128
	ds_read2st64_b32 v[24:25], v0 offset0:129 offset1:144
	ds_read2st64_b32 v[26:27], v0 offset0:145 offset1:160
	ds_read2st64_b32 v[28:29], v0 offset0:161 offset1:176
	ds_read2st64_b32 v[30:31], v0 offset0:177 offset1:192
	ds_read2st64_b32 v[32:33], v0 offset0:193 offset1:208
	ds_read2st64_b32 v[62:63], v0 offset0:209 offset1:224
	ds_read2st64_b32 v[64:65], v0 offset0:225 offset1:240
	s_waitcnt lgkmcnt(0)
	v_add_f32_e32 v78, 0, v9
	v_add_f32_e32 v55, 0, v8
	v_add_f32_e32 v13, v78, v13
	v_add_f32_e32 v11, v55, v11
	v_add_f32_e32 v13, v13, v17
	v_add_f32_e32 v11, v11, v15
	v_add_f32_e32 v13, v13, v21
	v_add_f32_e32 v11, v11, v19
	v_add_f32_e32 v13, v13, v25
	v_add_f32_e32 v11, v11, v23
	v_add_f32_e32 v13, v13, v29
	v_add_f32_e32 v11, v11, v27
	v_add_f32_e32 v13, v13, v33
	v_add_f32_e32 v11, v11, v31
	v_add_f32_e32 v13, v13, v65
	s_movk_i32 s0, 0xb00
	v_add_f32_e32 v11, v11, v63
	v_mad_i64_i32 v[2:3], s[0:1], v2, s0, v[4:5]
	s_mov_b64 s[0:1], 0xd000100
	s_nop 0
	v_lshl_add_u64 v[2:3], v[2:3], 0, s[0:1]
	v_lshl_add_u64 v[8:9], v[48:49], 1, v[2:3]
	v_lshl_add_u64 v[4:5], v[50:51], 3, v[4:5]
	v_readlane_b32 s0, v252, 1
	s_add_i32 s2, s2, s0
	s_cmpk_gt_i32 s2, 0xff
	v_lshl_add_u64 v[2:3], v[50:51], 1, v[2:3]
	v_add_u32_e32 v54, s6, v54
	v_readlane_b32 s1, v252, 2
	s_waitcnt vmcnt(0)
	v_mul_f32_e32 v15, v13, v7
	v_mul_f32_e32 v7, v11, v7
	v_fma_f32 v11, v11, v6, -v15
	v_fmac_f32_e32 v7, v13, v6
	v_bfe_u32 v6, v11, 16, 1
	v_bfe_u32 v13, v7, 16, 1
	v_add3_u32 v6, v11, v6, s33
	v_add3_u32 v7, v7, v13, s33
	v_lshrrev_b32_e32 v6, 16, v6
	v_lshrrev_b32_e32 v7, 16, v7
	global_store_short v[8:9], v6, off
	global_store_short v[8:9], v7, off offset:64
	global_store_short v[8:9], v6, off offset:384
	global_store_short v[8:9], v7, off offset:448
	global_store_short v[8:9], v6, off offset:768
	global_store_short v[8:9], v7, off offset:832
	global_store_short v[8:9], v6, off offset:1152
	global_store_short v[8:9], v7, off offset:1216
	global_store_short v[8:9], v6, off offset:1536
	global_store_short v[8:9], v7, off offset:1600
	global_store_short v[8:9], v6, off offset:1920
	global_store_short v[8:9], v7, off offset:1984
	global_store_short v[8:9], v6, off offset:2304
	global_store_short v[8:9], v7, off offset:2368
	global_store_short v[8:9], v6, off offset:2688
	global_store_short v[8:9], v7, off offset:2752
	global_load_dwordx2 v[4:5], v[4:5], off
	ds_read_b32 v6, v77
	ds_read_b32 v0, v0 offset:61696
	v_add_f32_e32 v7, 0, v10
	v_add_f32_e32 v7, v7, v14
	v_add_f32_e32 v7, v7, v18
	s_waitcnt lgkmcnt(0)
	v_add_f32_e32 v6, 0, v6
	v_add_f32_e32 v6, v6, v12
	v_add_f32_e32 v6, v6, v16
	v_add_f32_e32 v7, v7, v22
	v_add_f32_e32 v6, v6, v20
	v_add_f32_e32 v7, v7, v26
	v_add_f32_e32 v6, v6, v24
	v_add_f32_e32 v7, v7, v30
	v_add_f32_e32 v6, v6, v28
	v_add_f32_e32 v7, v7, v62
	v_add_f32_e32 v6, v6, v32
	v_add_f32_e32 v0, v7, v0
	v_add_f32_e32 v6, v6, v64
	s_waitcnt vmcnt(0)
	v_mul_f32_e32 v7, v0, v5
	v_mul_f32_e32 v5, v6, v5
	v_fma_f32 v6, v6, v4, -v7
	v_fmac_f32_e32 v5, v0, v4
	v_bfe_u32 v0, v6, 16, 1
	v_bfe_u32 v4, v5, 16, 1
	v_add3_u32 v0, v6, v0, s33
	v_add3_u32 v4, v5, v4, s33
	v_lshrrev_b32_e32 v0, 16, v0
	v_lshrrev_b32_e32 v4, 16, v4
	global_store_short v[2:3], v0, off
	global_store_short v[2:3], v4, off offset:64
	global_store_short v[2:3], v0, off offset:384
	global_store_short v[2:3], v4, off offset:448
	global_store_short v[2:3], v0, off offset:768
	global_store_short v[2:3], v4, off offset:832
	global_store_short v[2:3], v0, off offset:1152
	global_store_short v[2:3], v4, off offset:1216
	global_store_short v[2:3], v0, off offset:1536
	global_store_short v[2:3], v4, off offset:1600
	global_store_short v[2:3], v0, off offset:1920
	global_store_short v[2:3], v4, off offset:1984
	global_store_short v[2:3], v0, off offset:2304
	global_store_short v[2:3], v4, off offset:2368
	global_store_short v[2:3], v0, off offset:2688
	global_store_short v[2:3], v4, off offset:2752
	s_waitcnt lgkmcnt(0)
	s_barrier
	s_cbranch_scc0 .LBB2_716
	v_readlane_b32 s2, v254, 41
	v_readlane_b32 s3, v254, 42
